# K loops (PG/PH/In/Vt): loop counter, pointer updates and next iteration's scalar set-up interleaved with the last 16 MFMAs of the iteration; only the back branch follows the closing barrier
# baseline (speedup 1.0000x reference)
; #define PG8_STAGE(bufoff, gbase, voff) do { _Pragma("unroll") for (int _i = 0; _i < 2; ++_i) \
;         __builtin_amdgcn_global_load_lds((const unsigned*)((const char*)(gbase) + (voff)[_i]), (LAS unsigned*)(lds + (bufoff) + ldsw + _i * 8192), 16, 0, 0); } while (0)
; #define PG8_LDA(dst, b, h) do { _Pragma("unroll") for (int m = 0; m < 4; ++m) _Pragma("unroll") for (int k = 0; k < 2; ++k) dst[m][k] = *(const LAS bf16x8*)(lds + PG8_SA(b, h) + aoff + m * 2048 + k * 1024); } while (0)
; #define PG8_LDB(dst, b, h) do { _Pragma("unroll") for (int n = 0; n < 2; ++n) _Pragma("unroll") for (int k = 0; k < 2; ++k) dst[n][k] = *(const LAS bf16x8*)(lds + PG8_SB(b, h) + boff + n * 2048 + k * 1024); } while (0)
; #define PG8_MMA(ai, bj, At, Bt) do { __builtin_amdgcn_s_setprio(1); _Pragma("unroll") for (int m = 0; m < 4; ++m) _Pragma("unroll") for (int n = 0; n < 2; ++n) _Pragma("unroll") for (int k = 0; k < 2; ++k) \
;         acc[ai][bj][m][n] = __builtin_amdgcn_mfma_f32_16x16x32_bf16(Bt[n][k], At[m][k], acc[ai][bj][m][n], 0, 0, 0); __builtin_amdgcn_s_setprio(0); } while (0)
; #define PG8_WAIT_V(n) asm volatile("s_waitcnt vmcnt(" #n ")" ::: "memory")
; #define PG8_WAIT_L(n) asm volatile("s_waitcnt lgkmcnt(" #n ")" ::: "memory")
; template <class Epi, class Sched, bool ALIGN_EPI>
; __device__ __forceinline__ void gemm_phase(LAS unsigned char* lds, const Gemm g, const Sched& S, const Epi& E) {
;     ...
;         const bool has_next = S.next(ui + 1, nxt);
;         const char* nA = has_next ? (const char*)g.A + (size_t)nxt.pm * tstepA : cA; const char* nB = has_next ? (const char*)g.Bt + (size_t)nxt.pn * tstepB : cB;
;         for (int t = 0; t < nt; t += 2) {
;             const bool last = (t == nt - 2);
;             const char* a1 = cA + (size_t)(t + 1) * kstep;
;             const char* a2 = last ? nA : cA + (size_t)(t + 2) * kstep; const char* b2 = last ? nB : cB + (size_t)(t + 2) * kstep;
;             const char* a3 = a2 + kstep; const char* b3 = b2 + kstep;
;             PG8_LDB(B0, 0, 0); PG8_LDB(B1, 0, 1); PG8_SCHED; PG8_LDA(At, 0, 0); PG8_STAGE(PG8_SA(1, 1), a1 + hstepA, voffA);
;             PG8_WAIT_V(8); PG8_WAIT_L(0); PG8_BAR; PG8_MMA(0, 0, At, B0); PG8_MMA(0, 1, At, B1); PG8_BAR; PG8_SCHED;
;             PG8_LDA(At, 0, 1); PG8_STAGE(PG8_SB(0, 0), b2, voffB); PG8_STAGE(PG8_SB(0, 1), b2 + hstepB, voffB); PG8_STAGE(PG8_SA(0, 0), a2, voffA);
.LBB0_208:
	s_ashr_i32 s81, s80, 31
	s_lshl_b64 s[54:55], s[80:81], 21
	s_add_u32 s84, s33, s54
	s_addc_u32 s85, s51, s55
	s_and_b64 s[54:55], s[42:43], exec
	s_cselect_b32 s56, s85, s45
	s_cselect_b32 s57, s84, s44
	s_ashr_i32 s63, s62, 31
	s_lshl_b64 s[54:55], s[62:63], 21
	v_readlane_b32 s52, v255, 48
	s_add_u32 s90, s52, s54
	s_addc_u32 s91, s48, s55
	s_and_b64 s[54:55], s[42:43], exec
	s_cselect_b32 s63, s91, s47
	s_cselect_b32 s64, s90, s46
	s_add_u32 s44, s44, 0x100080
	s_addc_u32 s45, s45, 0
	s_add_u32 s65, s46, 0x100
	s_addc_u32 s81, s47, 0
	s_mov_b32 s92, -2
	s_add_u32 s46, s44, 0xfff00080
	s_addc_u32 s47, s45, -1
	s_add_i32 s52, 0, 0x10000
	s_cmp_eq_u32 s92, 60
	s_cselect_b32 s55, s56, s47
	s_cselect_b32 s54, s57, s46
	s_cselect_b32 s47, s63, s81
	s_cselect_b32 s46, s64, s65
	s_add_i32 s53, 0, 0x14000
	v_add_u32_e32 v140, s52, v247
	v_add_u32_e32 v156, s53, v247
	ds_read_b128 v[104:107], v140
	ds_read_b128 v[112:115], v140 offset:1024
	ds_read_b128 v[136:139], v140 offset:2048
	ds_read_b128 v[140:143], v140 offset:3072
	ds_read_b128 v[144:147], v156
	ds_read_b128 v[148:151], v156 offset:1024
	ds_read_b128 v[152:155], v156 offset:2048
	ds_read_b128 v[156:159], v156 offset:3072
	v_lshl_add_u64 v[194:195], s[44:45], 0, v[220:221]
	s_add_i32 m0, s49, 0xc000
	ds_read_b128 v[160:163], v248
	ds_read_b128 v[164:167], v248 offset:1024
	ds_read_b128 v[168:171], v248 offset:2048
	ds_read_b128 v[172:175], v248 offset:3072
	ds_read_b128 v[176:179], v248 offset:4096
	ds_read_b128 v[180:183], v248 offset:5120
	ds_read_b128 v[184:187], v248 offset:6144
	ds_read_b128 v[188:191], v248 offset:7168
	global_load_lds_dwordx4 v[194:195], off
	v_lshl_add_u64 v[194:195], s[44:45], 0, v[222:223]
	s_add_i32 m0, s49, 0xe000
	s_nop 0
	global_load_lds_dwordx4 v[194:195], off
	s_waitcnt vmcnt(8)
	s_waitcnt lgkmcnt(0)
	s_barrier
	s_setprio 1
	s_waitcnt lgkmcnt(0)
	v_mfma_f32_16x16x32_bf16 v[132:135], v[104:107], v[160:163], 0
	v_mfma_f32_16x16x32_bf16 v[128:131], v[136:139], v[160:163], 0
	v_mfma_f32_16x16x32_bf16 v[116:119], v[104:107], v[168:171], 0
	v_mfma_f32_16x16x32_bf16 v[108:111], v[136:139], v[168:171], 0
	v_mfma_f32_16x16x32_bf16 v[96:99], v[104:107], v[176:179], 0
	v_mfma_f32_16x16x32_bf16 v[88:91], v[136:139], v[176:179], 0
	v_mfma_f32_16x16x32_bf16 v[80:83], v[104:107], v[184:187], 0
	v_mfma_f32_16x16x32_bf16 v[72:75], v[136:139], v[184:187], 0
	v_mfma_f32_16x16x32_bf16 v[132:135], v[112:115], v[164:167], v[132:135]
	v_mfma_f32_16x16x32_bf16 v[128:131], v[140:143], v[164:167], v[128:131]
	v_mfma_f32_16x16x32_bf16 v[116:119], v[112:115], v[172:175], v[116:119]
	v_mfma_f32_16x16x32_bf16 v[108:111], v[140:143], v[172:175], v[108:111]
	v_mfma_f32_16x16x32_bf16 v[96:99], v[112:115], v[180:183], v[96:99]
	v_mfma_f32_16x16x32_bf16 v[88:91], v[140:143], v[180:183], v[88:91]
	v_mfma_f32_16x16x32_bf16 v[80:83], v[112:115], v[188:191], v[80:83]
	v_mfma_f32_16x16x32_bf16 v[72:75], v[140:143], v[188:191], v[72:75]
	s_setprio 0
	s_setprio 1
	v_mfma_f32_16x16x32_bf16 v[124:127], v[144:147], v[160:163], 0
	v_mfma_f32_16x16x32_bf16 v[120:123], v[152:155], v[160:163], 0
	v_mfma_f32_16x16x32_bf16 v[100:103], v[144:147], v[168:171], 0
	v_mfma_f32_16x16x32_bf16 v[92:95], v[152:155], v[168:171], 0
	v_mfma_f32_16x16x32_bf16 v[84:87], v[144:147], v[176:179], 0
	v_mfma_f32_16x16x32_bf16 v[76:79], v[152:155], v[176:179], 0
	v_mfma_f32_16x16x32_bf16 v[68:71], v[144:147], v[184:187], 0
	v_mfma_f32_16x16x32_bf16 v[64:67], v[152:155], v[184:187], 0
	v_mfma_f32_16x16x32_bf16 v[124:127], v[148:151], v[164:167], v[124:127]
	v_mfma_f32_16x16x32_bf16 v[120:123], v[156:159], v[164:167], v[120:123]
	v_mfma_f32_16x16x32_bf16 v[100:103], v[148:151], v[172:175], v[100:103]
	v_mfma_f32_16x16x32_bf16 v[92:95], v[156:159], v[172:175], v[92:95]
	v_mfma_f32_16x16x32_bf16 v[84:87], v[148:151], v[180:183], v[84:87]
	v_mfma_f32_16x16x32_bf16 v[76:79], v[156:159], v[180:183], v[76:79]
	v_mfma_f32_16x16x32_bf16 v[68:71], v[148:151], v[188:191], v[68:71]
	v_mfma_f32_16x16x32_bf16 v[64:67], v[156:159], v[188:191], v[64:67]
	s_setprio 0
	s_barrier
	s_add_i32 s52, s52, s50
	v_lshl_add_u64 v[194:195], s[46:47], 0, v[216:217]
	s_mov_b32 m0, s52
	ds_read_b128 v[160:163], v248 offset:16384
	ds_read_b128 v[164:167], v248 offset:17408
	ds_read_b128 v[168:171], v248 offset:18432
	ds_read_b128 v[172:175], v248 offset:19456
	ds_read_b128 v[176:179], v248 offset:20480
	ds_read_b128 v[180:183], v248 offset:21504
	ds_read_b128 v[184:187], v248 offset:22528
	ds_read_b128 v[188:191], v248 offset:23552
	global_load_lds_dwordx4 v[194:195], off
	s_add_i32 m0, s52, 0x2000
	s_add_u32 vcc_lo, s46, 0x100000
	v_lshl_add_u64 v[196:197], s[46:47], 0, v[212:213]
	s_addc_u32 vcc_hi, s47, 0
	s_add_i32 s52, s53, s50
	global_load_lds_dwordx4 v[196:197], off
	v_lshl_add_u64 v[198:199], vcc, 0, v[216:217]
	s_mov_b32 m0, s52
	v_lshl_add_u64 v[200:201], s[54:55], 0, v[214:215]
	global_load_lds_dwordx4 v[198:199], off
	v_lshl_add_u64 v[198:199], vcc, 0, v[212:213]
	s_add_i32 m0, s52, 0x2000
	s_nop 0
	global_load_lds_dwordx4 v[198:199], off
	v_lshl_add_u64 v[198:199], s[54:55], 0, v[218:219]
	s_mov_b32 m0, s49
	s_nop 0
	global_load_lds_dwordx4 v[198:199], off
	s_mov_b32 m0, s67
	s_nop 0
	global_load_lds_dwordx4 v[200:201], off
	s_waitcnt vmcnt(8)
	s_waitcnt lgkmcnt(0)
	s_barrier
; #define PG8_STAGE(bufoff, gbase, voff) do { _Pragma("unroll") for (int _i = 0; _i < 2; ++_i) \
;         __builtin_amdgcn_global_load_lds((const unsigned*)((const char*)(gbase) + (voff)[_i]), (LAS unsigned*)(lds + (bufoff) + ldsw + _i * 8192), 16, 0, 0); } while (0)
; #define PG8_LDA(dst, b, h) do { _Pragma("unroll") for (int m = 0; m < 4; ++m) _Pragma("unroll") for (int k = 0; k < 2; ++k) dst[m][k] = *(const LAS bf16x8*)(lds + PG8_SA(b, h) + aoff + m * 2048 + k * 1024); } while (0)
; #define PG8_LDB(dst, b, h) do { _Pragma("unroll") for (int n = 0; n < 2; ++n) _Pragma("unroll") for (int k = 0; k < 2; ++k) dst[n][k] = *(const LAS bf16x8*)(lds + PG8_SB(b, h) + boff + n * 2048 + k * 1024); } while (0)
; #define PG8_MMA(ai, bj, At, Bt) do { __builtin_amdgcn_s_setprio(1); _Pragma("unroll") for (int m = 0; m < 4; ++m) _Pragma("unroll") for (int n = 0; n < 2; ++n) _Pragma("unroll") for (int k = 0; k < 2; ++k) \
;         acc[ai][bj][m][n] = __builtin_amdgcn_mfma_f32_16x16x32_bf16(Bt[n][k], At[m][k], acc[ai][bj][m][n], 0, 0, 0); __builtin_amdgcn_s_setprio(0); } while (0)
; #define PG8_WAIT_V(n) asm volatile("s_waitcnt vmcnt(" #n ")" ::: "memory")
; #define PG8_WAIT_L(n) asm volatile("s_waitcnt lgkmcnt(" #n ")" ::: "memory")
; #define PG8_BAR __builtin_amdgcn_s_barrier()
; #define PG8_SCHED __builtin_amdgcn_sched_barrier(0)
; template <class Epi, class Sched, bool ALIGN_EPI>
; __device__ __forceinline__ void gemm_phase(LAS unsigned char* lds, const Gemm g, const Sched& S, const Epi& E) {
;     ...
;             PG8_LDA(At, 0, 1); PG8_STAGE(PG8_SB(0, 0), b2, voffB); PG8_STAGE(PG8_SB(0, 1), b2 + hstepB, voffB); PG8_STAGE(PG8_SA(0, 0), a2, voffA);
;             PG8_WAIT_V(8); PG8_WAIT_L(0); PG8_BAR; PG8_MMA(1, 0, At, B0); PG8_MMA(1, 1, At, B1); PG8_BAR; PG8_SCHED;
;             PG8_LDB(B0, 1, 0); PG8_LDB(B1, 1, 1); PG8_SCHED; PG8_LDA(At, 1, 0); PG8_STAGE(PG8_SA(0, 1), a2 + hstepA, voffA);
;             PG8_WAIT_V(8); PG8_WAIT_L(0); PG8_BAR; PG8_MMA(0, 0, At, B0); PG8_MMA(0, 1, At, B1); PG8_BAR; PG8_SCHED;
	s_setprio 1
	s_waitcnt lgkmcnt(0)
	v_mfma_f32_16x16x32_bf16 v[60:63], v[104:107], v[160:163], 0
	v_mfma_f32_16x16x32_bf16 v[56:59], v[136:139], v[160:163], 0
	v_mfma_f32_16x16x32_bf16 v[44:47], v[104:107], v[168:171], 0
	v_mfma_f32_16x16x32_bf16 v[40:43], v[136:139], v[168:171], 0
	v_mfma_f32_16x16x32_bf16 v[32:35], v[104:107], v[176:179], 0
	v_mfma_f32_16x16x32_bf16 v[24:27], v[136:139], v[176:179], 0
	v_mfma_f32_16x16x32_bf16 v[16:19], v[104:107], v[184:187], 0
	v_mfma_f32_16x16x32_bf16 v[8:11], v[136:139], v[184:187], 0
	v_mfma_f32_16x16x32_bf16 v[60:63], v[112:115], v[164:167], v[60:63]
	v_mfma_f32_16x16x32_bf16 v[56:59], v[140:143], v[164:167], v[56:59]
	v_mfma_f32_16x16x32_bf16 v[44:47], v[112:115], v[172:175], v[44:47]
	v_mfma_f32_16x16x32_bf16 v[40:43], v[140:143], v[172:175], v[40:43]
	v_mfma_f32_16x16x32_bf16 v[32:35], v[112:115], v[180:183], v[32:35]
	v_mfma_f32_16x16x32_bf16 v[24:27], v[140:143], v[180:183], v[24:27]
	v_mfma_f32_16x16x32_bf16 v[16:19], v[112:115], v[188:191], v[16:19]
	v_mfma_f32_16x16x32_bf16 v[8:11], v[140:143], v[188:191], v[8:11]
	s_setprio 0
	s_setprio 1
	v_mfma_f32_16x16x32_bf16 v[52:55], v[144:147], v[160:163], 0
	v_mfma_f32_16x16x32_bf16 v[48:51], v[152:155], v[160:163], 0
	v_mfma_f32_16x16x32_bf16 v[36:39], v[144:147], v[168:171], 0
	v_mfma_f32_16x16x32_bf16 v[28:31], v[152:155], v[168:171], 0
	v_mfma_f32_16x16x32_bf16 v[20:23], v[144:147], v[176:179], 0
	v_mfma_f32_16x16x32_bf16 v[12:15], v[152:155], v[176:179], 0
	v_mfma_f32_16x16x32_bf16 v[4:7], v[144:147], v[184:187], 0
	v_mfma_f32_16x16x32_bf16 v[0:3], v[152:155], v[184:187], 0
	v_mfma_f32_16x16x32_bf16 v[52:55], v[148:151], v[164:167], v[52:55]
	v_mfma_f32_16x16x32_bf16 v[48:51], v[156:159], v[164:167], v[48:51]
	v_mfma_f32_16x16x32_bf16 v[36:39], v[148:151], v[172:175], v[36:39]
	v_mfma_f32_16x16x32_bf16 v[28:31], v[156:159], v[172:175], v[28:31]
	v_mfma_f32_16x16x32_bf16 v[20:23], v[148:151], v[180:183], v[20:23]
	v_mfma_f32_16x16x32_bf16 v[12:15], v[156:159], v[180:183], v[12:15]
	v_mfma_f32_16x16x32_bf16 v[4:7], v[148:151], v[188:191], v[4:7]
	v_mfma_f32_16x16x32_bf16 v[0:3], v[156:159], v[188:191], v[0:3]
	s_setprio 0
	s_barrier
	s_add_i32 s52, 0, 0x18000
	s_add_i32 s53, 0, 0x1c000
	v_add_u32_e32 v140, s52, v247
	v_add_u32_e32 v156, s53, v247
	ds_read_b128 v[104:107], v140
	ds_read_b128 v[112:115], v140 offset:1024
	ds_read_b128 v[136:139], v140 offset:2048
	ds_read_b128 v[140:143], v140 offset:3072
	ds_read_b128 v[144:147], v156
	ds_read_b128 v[148:151], v156 offset:1024
	ds_read_b128 v[152:155], v156 offset:2048
	ds_read_b128 v[156:159], v156 offset:3072
	s_add_u32 s54, s54, 0x100000
	s_addc_u32 s55, s55, 0
	s_mov_b32 m0, s86
	v_lshl_add_u64 v[202:203], s[54:55], 0, v[218:219]
	ds_read_b128 v[160:163], v248 offset:32768
	ds_read_b128 v[164:167], v248 offset:33792
	ds_read_b128 v[168:171], v248 offset:34816
	ds_read_b128 v[172:175], v248 offset:35840
	ds_read_b128 v[176:179], v248 offset:36864
	ds_read_b128 v[180:183], v248 offset:37888
	ds_read_b128 v[184:187], v248 offset:38912
	ds_read_b128 v[188:191], v248 offset:39936
	global_load_lds_dwordx4 v[202:203], off
	v_lshl_add_u64 v[202:203], s[54:55], 0, v[214:215]
	s_mov_b32 m0, s66
	s_nop 0
	global_load_lds_dwordx4 v[202:203], off
	s_waitcnt vmcnt(8)
	s_waitcnt lgkmcnt(0)
	s_barrier
	s_setprio 1
	s_waitcnt lgkmcnt(0)
	v_mfma_f32_16x16x32_bf16 v[132:135], v[104:107], v[160:163], v[132:135]
	v_mfma_f32_16x16x32_bf16 v[128:131], v[136:139], v[160:163], v[128:131]
	v_mfma_f32_16x16x32_bf16 v[116:119], v[104:107], v[168:171], v[116:119]
	v_mfma_f32_16x16x32_bf16 v[108:111], v[136:139], v[168:171], v[108:111]
	v_mfma_f32_16x16x32_bf16 v[96:99], v[104:107], v[176:179], v[96:99]
	v_mfma_f32_16x16x32_bf16 v[88:91], v[136:139], v[176:179], v[88:91]
	v_mfma_f32_16x16x32_bf16 v[80:83], v[104:107], v[184:187], v[80:83]
	v_mfma_f32_16x16x32_bf16 v[72:75], v[136:139], v[184:187], v[72:75]
	v_mfma_f32_16x16x32_bf16 v[132:135], v[112:115], v[164:167], v[132:135]
	v_mfma_f32_16x16x32_bf16 v[128:131], v[140:143], v[164:167], v[128:131]
	v_mfma_f32_16x16x32_bf16 v[116:119], v[112:115], v[172:175], v[116:119]
	v_mfma_f32_16x16x32_bf16 v[108:111], v[140:143], v[172:175], v[108:111]
	v_mfma_f32_16x16x32_bf16 v[96:99], v[112:115], v[180:183], v[96:99]
	v_mfma_f32_16x16x32_bf16 v[88:91], v[140:143], v[180:183], v[88:91]
	v_mfma_f32_16x16x32_bf16 v[80:83], v[112:115], v[188:191], v[80:83]
	v_mfma_f32_16x16x32_bf16 v[72:75], v[140:143], v[188:191], v[72:75]
	s_setprio 0
	s_setprio 1
	v_mfma_f32_16x16x32_bf16 v[124:127], v[144:147], v[160:163], v[124:127]
	v_mfma_f32_16x16x32_bf16 v[120:123], v[152:155], v[160:163], v[120:123]
	v_mfma_f32_16x16x32_bf16 v[100:103], v[144:147], v[168:171], v[100:103]
	v_mfma_f32_16x16x32_bf16 v[92:95], v[152:155], v[168:171], v[92:95]
	v_mfma_f32_16x16x32_bf16 v[84:87], v[144:147], v[176:179], v[84:87]
	v_mfma_f32_16x16x32_bf16 v[76:79], v[152:155], v[176:179], v[76:79]
	v_mfma_f32_16x16x32_bf16 v[68:71], v[144:147], v[184:187], v[68:71]
	v_mfma_f32_16x16x32_bf16 v[64:67], v[152:155], v[184:187], v[64:67]
	v_mfma_f32_16x16x32_bf16 v[124:127], v[148:151], v[164:167], v[124:127]
	v_mfma_f32_16x16x32_bf16 v[120:123], v[156:159], v[164:167], v[120:123]
	v_mfma_f32_16x16x32_bf16 v[100:103], v[148:151], v[172:175], v[100:103]
	v_mfma_f32_16x16x32_bf16 v[92:95], v[156:159], v[172:175], v[92:95]
	v_mfma_f32_16x16x32_bf16 v[84:87], v[148:151], v[180:183], v[84:87]
	v_mfma_f32_16x16x32_bf16 v[76:79], v[156:159], v[180:183], v[76:79]
	v_mfma_f32_16x16x32_bf16 v[68:71], v[148:151], v[188:191], v[68:71]
	v_mfma_f32_16x16x32_bf16 v[64:67], v[156:159], v[188:191], v[64:67]
	s_setprio 0
	s_barrier
; #define PG8_STAGE(bufoff, gbase, voff) do { _Pragma("unroll") for (int _i = 0; _i < 2; ++_i) \
;         __builtin_amdgcn_global_load_lds((const unsigned*)((const char*)(gbase) + (voff)[_i]), (LAS unsigned*)(lds + (bufoff) + ldsw + _i * 8192), 16, 0, 0); } while (0)
; #define PG8_LDA(dst, b, h) do { _Pragma("unroll") for (int m = 0; m < 4; ++m) _Pragma("unroll") for (int k = 0; k < 2; ++k) dst[m][k] = *(const LAS bf16x8*)(lds + PG8_SA(b, h) + aoff + m * 2048 + k * 1024); } while (0)
; #define PG8_LDB(dst, b, h) do { _Pragma("unroll") for (int n = 0; n < 2; ++n) _Pragma("unroll") for (int k = 0; k < 2; ++k) dst[n][k] = *(const LAS bf16x8*)(lds + PG8_SB(b, h) + boff + n * 2048 + k * 1024); } while (0)
; #define PG8_MMA(ai, bj, At, Bt) do { __builtin_amdgcn_s_setprio(1); _Pragma("unroll") for (int m = 0; m < 4; ++m) _Pragma("unroll") for (int n = 0; n < 2; ++n) _Pragma("unroll") for (int k = 0; k < 2; ++k) \
;         acc[ai][bj][m][n] = __builtin_amdgcn_mfma_f32_16x16x32_bf16(Bt[n][k], At[m][k], acc[ai][bj][m][n], 0, 0, 0); __builtin_amdgcn_s_setprio(0); } while (0)
; #define PG8_WAIT_V(n) asm volatile("s_waitcnt vmcnt(" #n ")" ::: "memory")
; #define PG8_WAIT_L(n) asm volatile("s_waitcnt lgkmcnt(" #n ")" ::: "memory")
; #define PG8_BAR __builtin_amdgcn_s_barrier()
; #define PG8_SCHED __builtin_amdgcn_sched_barrier(0)
; template <class Epi, class Sched, bool ALIGN_EPI>
; __device__ __forceinline__ void gemm_phase(LAS unsigned char* lds, const Gemm g, const Sched& S, const Epi& E) {
;     ...
;         for (int t = 0; t < nt; t += 2) {
;             const bool last = (t == nt - 2);
;             const char* a1 = cA + (size_t)(t + 1) * kstep;
;             const char* a2 = last ? nA : cA + (size_t)(t + 2) * kstep; const char* b2 = last ? nB : cB + (size_t)(t + 2) * kstep;
;             const char* a3 = a2 + kstep; const char* b3 = b2 + kstep;
;             PG8_LDB(B0, 0, 0); PG8_LDB(B1, 0, 1); PG8_SCHED; PG8_LDA(At, 0, 0); PG8_STAGE(PG8_SA(1, 1), a1 + hstepA, voffA);
;     ...
;             PG8_LDA(At, 1, 1); PG8_STAGE(PG8_SB(1, 0), b3, voffB); PG8_STAGE(PG8_SB(1, 1), b3 + hstepB, voffB); PG8_STAGE(PG8_SA(1, 0), a3, voffA);
;             PG8_WAIT_V(8); PG8_WAIT_L(0); PG8_BAR; PG8_MMA(1, 0, At, B0); PG8_MMA(1, 1, At, B1); PG8_BAR; PG8_SCHED;
	s_add_i32 s52, s52, s50
	v_lshl_add_u64 v[194:195], v[194:195], 0, s[12:13]
	s_mov_b32 m0, s52
	ds_read_b128 v[160:163], v248 offset:49152
	ds_read_b128 v[164:167], v248 offset:50176
	ds_read_b128 v[168:171], v248 offset:51200
	ds_read_b128 v[172:175], v248 offset:52224
	ds_read_b128 v[176:179], v248 offset:53248
	ds_read_b128 v[180:183], v248 offset:54272
	ds_read_b128 v[184:187], v248 offset:55296
	ds_read_b128 v[188:191], v248 offset:56320
	global_load_lds_dwordx4 v[194:195], off
	s_add_i32 m0, s52, 0x2000
	s_add_u32 s46, s46, 0x100080
	v_lshl_add_u64 v[194:195], v[196:197], 0, s[12:13]
	s_addc_u32 s47, s47, 0
	s_add_i32 s52, s53, s50
	global_load_lds_dwordx4 v[194:195], off
	v_lshl_add_u64 v[194:195], s[46:47], 0, v[216:217]
	s_mov_b32 m0, s52
	s_nop 0
	global_load_lds_dwordx4 v[194:195], off
	v_lshl_add_u64 v[194:195], s[46:47], 0, v[212:213]
	s_add_i32 m0, s52, 0x2000
	s_nop 0
	global_load_lds_dwordx4 v[194:195], off
	v_lshl_add_u64 v[194:195], v[198:199], 0, s[12:13]
	s_mov_b32 m0, s59
	s_nop 0
	global_load_lds_dwordx4 v[194:195], off
	v_lshl_add_u64 v[194:195], v[200:201], 0, s[12:13]
	s_mov_b32 m0, s4
	s_nop 0
	global_load_lds_dwordx4 v[194:195], off
	s_waitcnt vmcnt(8)
	s_waitcnt lgkmcnt(0)
	s_barrier
	s_setprio 1
	s_waitcnt lgkmcnt(0)
	v_mfma_f32_16x16x32_bf16 v[60:63], v[104:107], v[160:163], v[60:63]
	v_mfma_f32_16x16x32_bf16 v[56:59], v[136:139], v[160:163], v[56:59]
	v_mfma_f32_16x16x32_bf16 v[44:47], v[104:107], v[168:171], v[44:47]
	v_mfma_f32_16x16x32_bf16 v[40:43], v[136:139], v[168:171], v[40:43]
	v_mfma_f32_16x16x32_bf16 v[32:35], v[104:107], v[176:179], v[32:35]
	v_mfma_f32_16x16x32_bf16 v[24:27], v[136:139], v[176:179], v[24:27]
	v_mfma_f32_16x16x32_bf16 v[16:19], v[104:107], v[184:187], v[16:19]
	v_mfma_f32_16x16x32_bf16 v[8:11], v[136:139], v[184:187], v[8:11]
	v_mfma_f32_16x16x32_bf16 v[60:63], v[112:115], v[164:167], v[60:63]
	v_mfma_f32_16x16x32_bf16 v[56:59], v[140:143], v[164:167], v[56:59]
	v_mfma_f32_16x16x32_bf16 v[44:47], v[112:115], v[172:175], v[44:47]
	v_mfma_f32_16x16x32_bf16 v[40:43], v[140:143], v[172:175], v[40:43]
	v_mfma_f32_16x16x32_bf16 v[32:35], v[112:115], v[180:183], v[32:35]
	v_mfma_f32_16x16x32_bf16 v[24:27], v[140:143], v[180:183], v[24:27]
	v_mfma_f32_16x16x32_bf16 v[16:19], v[112:115], v[188:191], v[16:19]
	v_mfma_f32_16x16x32_bf16 v[8:11], v[140:143], v[188:191], v[8:11]
	s_setprio 0
	s_setprio 1
	v_mfma_f32_16x16x32_bf16 v[52:55], v[144:147], v[160:163], v[52:55]
	s_add_i32 s92, s92, 2
	v_mfma_f32_16x16x32_bf16 v[48:51], v[152:155], v[160:163], v[48:51]
	s_add_u32 s44, s44, 0x100
	v_mfma_f32_16x16x32_bf16 v[36:39], v[144:147], v[168:171], v[36:39]
	s_addc_u32 s45, s45, 0
	v_mfma_f32_16x16x32_bf16 v[28:31], v[152:155], v[168:171], v[28:31]
	s_add_u32 s65, s65, 0x100
	v_mfma_f32_16x16x32_bf16 v[20:23], v[144:147], v[176:179], v[20:23]
	s_addc_u32 s81, s81, 0
	v_mfma_f32_16x16x32_bf16 v[12:15], v[152:155], v[176:179], v[12:15]
	s_add_u32 s46, s44, 0xfff00080
	v_mfma_f32_16x16x32_bf16 v[4:7], v[144:147], v[184:187], v[4:7]
	s_addc_u32 s47, s45, -1
	v_mfma_f32_16x16x32_bf16 v[0:3], v[152:155], v[184:187], v[0:3]
	s_add_i32 s52, 0, 0x10000
	v_mfma_f32_16x16x32_bf16 v[52:55], v[148:151], v[164:167], v[52:55]
	s_cmp_eq_u32 s92, 60
	v_mfma_f32_16x16x32_bf16 v[48:51], v[156:159], v[164:167], v[48:51]
	s_cselect_b32 s55, s56, s47
	v_mfma_f32_16x16x32_bf16 v[36:39], v[148:151], v[172:175], v[36:39]
	s_cselect_b32 s54, s57, s46
	v_mfma_f32_16x16x32_bf16 v[28:31], v[156:159], v[172:175], v[28:31]
	s_cselect_b32 s47, s63, s81
	v_mfma_f32_16x16x32_bf16 v[20:23], v[148:151], v[180:183], v[20:23]
	s_cselect_b32 s46, s64, s65
	v_mfma_f32_16x16x32_bf16 v[12:15], v[156:159], v[180:183], v[12:15]
	s_add_i32 s53, 0, 0x14000
	v_mfma_f32_16x16x32_bf16 v[4:7], v[148:151], v[188:191], v[4:7]
	s_cmp_gt_u32 s92, 61
	v_mfma_f32_16x16x32_bf16 v[0:3], v[156:159], v[188:191], v[0:3]
	s_setprio 0
	s_barrier
.LBB0_209:
	v_add_u32_e32 v140, s52, v247
	v_add_u32_e32 v156, s53, v247
	ds_read_b128 v[104:107], v140
	ds_read_b128 v[112:115], v140 offset:1024
	ds_read_b128 v[136:139], v140 offset:2048
	ds_read_b128 v[140:143], v140 offset:3072
	ds_read_b128 v[144:147], v156
	ds_read_b128 v[148:151], v156 offset:1024
	ds_read_b128 v[152:155], v156 offset:2048
	ds_read_b128 v[156:159], v156 offset:3072
	v_lshl_add_u64 v[194:195], s[44:45], 0, v[220:221]
	s_add_i32 m0, s49, 0xc000
	ds_read_b128 v[160:163], v248
	ds_read_b128 v[164:167], v248 offset:1024
	ds_read_b128 v[168:171], v248 offset:2048
	ds_read_b128 v[172:175], v248 offset:3072
	ds_read_b128 v[176:179], v248 offset:4096
	ds_read_b128 v[180:183], v248 offset:5120
	ds_read_b128 v[184:187], v248 offset:6144
	ds_read_b128 v[188:191], v248 offset:7168
	global_load_lds_dwordx4 v[194:195], off
	v_lshl_add_u64 v[194:195], s[44:45], 0, v[222:223]
	s_add_i32 m0, s49, 0xe000
	s_nop 0
	global_load_lds_dwordx4 v[194:195], off
	s_waitcnt vmcnt(8)
	s_waitcnt lgkmcnt(0)
	s_barrier
; #define PG8_STAGE(bufoff, gbase, voff) do { _Pragma("unroll") for (int _i = 0; _i < 2; ++_i) \
;         __builtin_amdgcn_global_load_lds((const unsigned*)((const char*)(gbase) + (voff)[_i]), (LAS unsigned*)(lds + (bufoff) + ldsw + _i * 8192), 16, 0, 0); } while (0)
; #define PG8_LDA(dst, b, h) do { _Pragma("unroll") for (int m = 0; m < 4; ++m) _Pragma("unroll") for (int k = 0; k < 2; ++k) dst[m][k] = *(const LAS bf16x8*)(lds + PG8_SA(b, h) + aoff + m * 2048 + k * 1024); } while (0)
; #define PG8_MMA(ai, bj, At, Bt) do { __builtin_amdgcn_s_setprio(1); _Pragma("unroll") for (int m = 0; m < 4; ++m) _Pragma("unroll") for (int n = 0; n < 2; ++n) _Pragma("unroll") for (int k = 0; k < 2; ++k) \
;         acc[ai][bj][m][n] = __builtin_amdgcn_mfma_f32_16x16x32_bf16(Bt[n][k], At[m][k], acc[ai][bj][m][n], 0, 0, 0); __builtin_amdgcn_s_setprio(0); } while (0)
; #define PG8_WAIT_V(n) asm volatile("s_waitcnt vmcnt(" #n ")" ::: "memory")
; #define PG8_WAIT_L(n) asm volatile("s_waitcnt lgkmcnt(" #n ")" ::: "memory")
; #define PG8_BAR __builtin_amdgcn_s_barrier()
; #define PG8_SCHED __builtin_amdgcn_sched_barrier(0)
; template <class Epi, class Sched, bool ALIGN_EPI>
; __device__ __forceinline__ void gemm_phase(LAS unsigned char* lds, const Gemm g, const Sched& S, const Epi& E) {
;     ...
;             PG8_WAIT_V(8); PG8_WAIT_L(0); PG8_BAR; PG8_MMA(0, 0, At, B0); PG8_MMA(0, 1, At, B1); PG8_BAR; PG8_SCHED;
;             PG8_LDA(At, 0, 1); PG8_STAGE(PG8_SB(0, 0), b2, voffB); PG8_STAGE(PG8_SB(0, 1), b2 + hstepB, voffB); PG8_STAGE(PG8_SA(0, 0), a2, voffA);
;             PG8_WAIT_V(8); PG8_WAIT_L(0); PG8_BAR; PG8_MMA(1, 0, At, B0); PG8_MMA(1, 1, At, B1); PG8_BAR; PG8_SCHED;
	s_setprio 1
	s_waitcnt lgkmcnt(0)
	v_mfma_f32_16x16x32_bf16 v[132:135], v[104:107], v[160:163], v[132:135]
	v_mfma_f32_16x16x32_bf16 v[128:131], v[136:139], v[160:163], v[128:131]
	v_mfma_f32_16x16x32_bf16 v[116:119], v[104:107], v[168:171], v[116:119]
	v_mfma_f32_16x16x32_bf16 v[108:111], v[136:139], v[168:171], v[108:111]
	v_mfma_f32_16x16x32_bf16 v[96:99], v[104:107], v[176:179], v[96:99]
	v_mfma_f32_16x16x32_bf16 v[88:91], v[136:139], v[176:179], v[88:91]
	v_mfma_f32_16x16x32_bf16 v[80:83], v[104:107], v[184:187], v[80:83]
	v_mfma_f32_16x16x32_bf16 v[72:75], v[136:139], v[184:187], v[72:75]
	v_mfma_f32_16x16x32_bf16 v[132:135], v[112:115], v[164:167], v[132:135]
	v_mfma_f32_16x16x32_bf16 v[128:131], v[140:143], v[164:167], v[128:131]
	v_mfma_f32_16x16x32_bf16 v[116:119], v[112:115], v[172:175], v[116:119]
	v_mfma_f32_16x16x32_bf16 v[108:111], v[140:143], v[172:175], v[108:111]
	v_mfma_f32_16x16x32_bf16 v[96:99], v[112:115], v[180:183], v[96:99]
	v_mfma_f32_16x16x32_bf16 v[88:91], v[140:143], v[180:183], v[88:91]
	v_mfma_f32_16x16x32_bf16 v[80:83], v[112:115], v[188:191], v[80:83]
	v_mfma_f32_16x16x32_bf16 v[72:75], v[140:143], v[188:191], v[72:75]
	s_setprio 0
	s_setprio 1
	v_mfma_f32_16x16x32_bf16 v[124:127], v[144:147], v[160:163], v[124:127]
	v_mfma_f32_16x16x32_bf16 v[120:123], v[152:155], v[160:163], v[120:123]
	v_mfma_f32_16x16x32_bf16 v[100:103], v[144:147], v[168:171], v[100:103]
	v_mfma_f32_16x16x32_bf16 v[92:95], v[152:155], v[168:171], v[92:95]
	v_mfma_f32_16x16x32_bf16 v[84:87], v[144:147], v[176:179], v[84:87]
	v_mfma_f32_16x16x32_bf16 v[76:79], v[152:155], v[176:179], v[76:79]
	v_mfma_f32_16x16x32_bf16 v[68:71], v[144:147], v[184:187], v[68:71]
	v_mfma_f32_16x16x32_bf16 v[64:67], v[152:155], v[184:187], v[64:67]
	v_mfma_f32_16x16x32_bf16 v[124:127], v[148:151], v[164:167], v[124:127]
	v_mfma_f32_16x16x32_bf16 v[120:123], v[156:159], v[164:167], v[120:123]
	v_mfma_f32_16x16x32_bf16 v[100:103], v[148:151], v[172:175], v[100:103]
	v_mfma_f32_16x16x32_bf16 v[92:95], v[156:159], v[172:175], v[92:95]
	v_mfma_f32_16x16x32_bf16 v[84:87], v[148:151], v[180:183], v[84:87]
	v_mfma_f32_16x16x32_bf16 v[76:79], v[156:159], v[180:183], v[76:79]
	v_mfma_f32_16x16x32_bf16 v[68:71], v[148:151], v[188:191], v[68:71]
	v_mfma_f32_16x16x32_bf16 v[64:67], v[156:159], v[188:191], v[64:67]
	s_setprio 0
	s_barrier
	s_add_i32 s52, s52, s50
	v_lshl_add_u64 v[194:195], s[46:47], 0, v[216:217]
	s_mov_b32 m0, s52
	ds_read_b128 v[160:163], v248 offset:16384
	ds_read_b128 v[164:167], v248 offset:17408
	ds_read_b128 v[168:171], v248 offset:18432
	ds_read_b128 v[172:175], v248 offset:19456
	ds_read_b128 v[176:179], v248 offset:20480
	ds_read_b128 v[180:183], v248 offset:21504
	ds_read_b128 v[184:187], v248 offset:22528
	ds_read_b128 v[188:191], v248 offset:23552
	global_load_lds_dwordx4 v[194:195], off
	s_add_i32 m0, s52, 0x2000
	s_add_u32 vcc_lo, s46, 0x100000
	v_lshl_add_u64 v[196:197], s[46:47], 0, v[212:213]
	s_addc_u32 vcc_hi, s47, 0
	s_add_i32 s52, s53, s50
	global_load_lds_dwordx4 v[196:197], off
	v_lshl_add_u64 v[198:199], vcc, 0, v[216:217]
	s_mov_b32 m0, s52
	v_lshl_add_u64 v[200:201], s[54:55], 0, v[214:215]
	global_load_lds_dwordx4 v[198:199], off
	v_lshl_add_u64 v[198:199], vcc, 0, v[212:213]
	s_add_i32 m0, s52, 0x2000
	s_nop 0
	global_load_lds_dwordx4 v[198:199], off
	v_lshl_add_u64 v[198:199], s[54:55], 0, v[218:219]
	s_mov_b32 m0, s49
	s_nop 0
	global_load_lds_dwordx4 v[198:199], off
	s_mov_b32 m0, s67
	s_nop 0
	global_load_lds_dwordx4 v[200:201], off
	s_waitcnt vmcnt(8)
	s_waitcnt lgkmcnt(0)
	s_barrier
	s_setprio 1
	s_waitcnt lgkmcnt(0)
	v_mfma_f32_16x16x32_bf16 v[60:63], v[104:107], v[160:163], v[60:63]
	v_mfma_f32_16x16x32_bf16 v[56:59], v[136:139], v[160:163], v[56:59]
	v_mfma_f32_16x16x32_bf16 v[44:47], v[104:107], v[168:171], v[44:47]
	v_mfma_f32_16x16x32_bf16 v[40:43], v[136:139], v[168:171], v[40:43]
	v_mfma_f32_16x16x32_bf16 v[32:35], v[104:107], v[176:179], v[32:35]
	v_mfma_f32_16x16x32_bf16 v[24:27], v[136:139], v[176:179], v[24:27]
	v_mfma_f32_16x16x32_bf16 v[16:19], v[104:107], v[184:187], v[16:19]
	v_mfma_f32_16x16x32_bf16 v[8:11], v[136:139], v[184:187], v[8:11]
	v_mfma_f32_16x16x32_bf16 v[60:63], v[112:115], v[164:167], v[60:63]
	v_mfma_f32_16x16x32_bf16 v[56:59], v[140:143], v[164:167], v[56:59]
	v_mfma_f32_16x16x32_bf16 v[44:47], v[112:115], v[172:175], v[44:47]
	v_mfma_f32_16x16x32_bf16 v[40:43], v[140:143], v[172:175], v[40:43]
	v_mfma_f32_16x16x32_bf16 v[32:35], v[112:115], v[180:183], v[32:35]
	v_mfma_f32_16x16x32_bf16 v[24:27], v[140:143], v[180:183], v[24:27]
	v_mfma_f32_16x16x32_bf16 v[16:19], v[112:115], v[188:191], v[16:19]
	v_mfma_f32_16x16x32_bf16 v[8:11], v[140:143], v[188:191], v[8:11]
	s_setprio 0
	s_setprio 1
	v_mfma_f32_16x16x32_bf16 v[52:55], v[144:147], v[160:163], v[52:55]
	v_mfma_f32_16x16x32_bf16 v[48:51], v[152:155], v[160:163], v[48:51]
	v_mfma_f32_16x16x32_bf16 v[36:39], v[144:147], v[168:171], v[36:39]
	v_mfma_f32_16x16x32_bf16 v[28:31], v[152:155], v[168:171], v[28:31]
	v_mfma_f32_16x16x32_bf16 v[20:23], v[144:147], v[176:179], v[20:23]
	v_mfma_f32_16x16x32_bf16 v[12:15], v[152:155], v[176:179], v[12:15]
	v_mfma_f32_16x16x32_bf16 v[4:7], v[144:147], v[184:187], v[4:7]
	v_mfma_f32_16x16x32_bf16 v[0:3], v[152:155], v[184:187], v[0:3]
	v_mfma_f32_16x16x32_bf16 v[52:55], v[148:151], v[164:167], v[52:55]
	v_mfma_f32_16x16x32_bf16 v[48:51], v[156:159], v[164:167], v[48:51]
	v_mfma_f32_16x16x32_bf16 v[36:39], v[148:151], v[172:175], v[36:39]
	v_mfma_f32_16x16x32_bf16 v[28:31], v[156:159], v[172:175], v[28:31]
	v_mfma_f32_16x16x32_bf16 v[20:23], v[148:151], v[180:183], v[20:23]
	v_mfma_f32_16x16x32_bf16 v[12:15], v[156:159], v[180:183], v[12:15]
	v_mfma_f32_16x16x32_bf16 v[4:7], v[148:151], v[188:191], v[4:7]
	v_mfma_f32_16x16x32_bf16 v[0:3], v[156:159], v[188:191], v[0:3]
	s_setprio 0
	s_barrier
; #define PG8_STAGE(bufoff, gbase, voff) do { _Pragma("unroll") for (int _i = 0; _i < 2; ++_i) \
;         __builtin_amdgcn_global_load_lds((const unsigned*)((const char*)(gbase) + (voff)[_i]), (LAS unsigned*)(lds + (bufoff) + ldsw + _i * 8192), 16, 0, 0); } while (0)
; #define PG8_LDA(dst, b, h) do { _Pragma("unroll") for (int m = 0; m < 4; ++m) _Pragma("unroll") for (int k = 0; k < 2; ++k) dst[m][k] = *(const LAS bf16x8*)(lds + PG8_SA(b, h) + aoff + m * 2048 + k * 1024); } while (0)
; #define PG8_LDB(dst, b, h) do { _Pragma("unroll") for (int n = 0; n < 2; ++n) _Pragma("unroll") for (int k = 0; k < 2; ++k) dst[n][k] = *(const LAS bf16x8*)(lds + PG8_SB(b, h) + boff + n * 2048 + k * 1024); } while (0)
; #define PG8_MMA(ai, bj, At, Bt) do { __builtin_amdgcn_s_setprio(1); _Pragma("unroll") for (int m = 0; m < 4; ++m) _Pragma("unroll") for (int n = 0; n < 2; ++n) _Pragma("unroll") for (int k = 0; k < 2; ++k) \
;         acc[ai][bj][m][n] = __builtin_amdgcn_mfma_f32_16x16x32_bf16(Bt[n][k], At[m][k], acc[ai][bj][m][n], 0, 0, 0); __builtin_amdgcn_s_setprio(0); } while (0)
; #define PG8_WAIT_V(n) asm volatile("s_waitcnt vmcnt(" #n ")" ::: "memory")
; #define PG8_WAIT_L(n) asm volatile("s_waitcnt lgkmcnt(" #n ")" ::: "memory")
; #define PG8_BAR __builtin_amdgcn_s_barrier()
; #define PG8_SCHED __builtin_amdgcn_sched_barrier(0)
; template <class Epi, class Sched, bool ALIGN_EPI>
; __device__ __forceinline__ void gemm_phase(LAS unsigned char* lds, const Gemm g, const Sched& S, const Epi& E) {
;     ...
;             PG8_LDB(B0, 1, 0); PG8_LDB(B1, 1, 1); PG8_SCHED; PG8_LDA(At, 1, 0); PG8_STAGE(PG8_SA(0, 1), a2 + hstepA, voffA);
;             PG8_WAIT_V(8); PG8_WAIT_L(0); PG8_BAR; PG8_MMA(0, 0, At, B0); PG8_MMA(0, 1, At, B1); PG8_BAR; PG8_SCHED;
	s_add_i32 s52, 0, 0x18000
	s_add_i32 s53, 0, 0x1c000
	v_add_u32_e32 v140, s52, v247
	v_add_u32_e32 v156, s53, v247
	ds_read_b128 v[104:107], v140
	ds_read_b128 v[112:115], v140 offset:1024
	ds_read_b128 v[136:139], v140 offset:2048
	ds_read_b128 v[140:143], v140 offset:3072
	ds_read_b128 v[144:147], v156
	ds_read_b128 v[148:151], v156 offset:1024
	ds_read_b128 v[152:155], v156 offset:2048
	ds_read_b128 v[156:159], v156 offset:3072
	s_add_u32 s54, s54, 0x100000
	s_addc_u32 s55, s55, 0
	s_mov_b32 m0, s86
	v_lshl_add_u64 v[202:203], s[54:55], 0, v[218:219]
	ds_read_b128 v[160:163], v248 offset:32768
	ds_read_b128 v[164:167], v248 offset:33792
	ds_read_b128 v[168:171], v248 offset:34816
	ds_read_b128 v[172:175], v248 offset:35840
	ds_read_b128 v[176:179], v248 offset:36864
	ds_read_b128 v[180:183], v248 offset:37888
	ds_read_b128 v[184:187], v248 offset:38912
	ds_read_b128 v[188:191], v248 offset:39936
	global_load_lds_dwordx4 v[202:203], off
	v_lshl_add_u64 v[202:203], s[54:55], 0, v[214:215]
	s_mov_b32 m0, s66
	s_nop 0
	global_load_lds_dwordx4 v[202:203], off
	s_waitcnt vmcnt(8)
	s_waitcnt lgkmcnt(0)
	s_barrier
	s_setprio 1
	s_waitcnt lgkmcnt(0)
	v_mfma_f32_16x16x32_bf16 v[132:135], v[104:107], v[160:163], v[132:135]
	v_mfma_f32_16x16x32_bf16 v[128:131], v[136:139], v[160:163], v[128:131]
	v_mfma_f32_16x16x32_bf16 v[116:119], v[104:107], v[168:171], v[116:119]
	v_mfma_f32_16x16x32_bf16 v[108:111], v[136:139], v[168:171], v[108:111]
	v_mfma_f32_16x16x32_bf16 v[96:99], v[104:107], v[176:179], v[96:99]
	v_mfma_f32_16x16x32_bf16 v[88:91], v[136:139], v[176:179], v[88:91]
	v_mfma_f32_16x16x32_bf16 v[80:83], v[104:107], v[184:187], v[80:83]
	v_mfma_f32_16x16x32_bf16 v[72:75], v[136:139], v[184:187], v[72:75]
	v_mfma_f32_16x16x32_bf16 v[132:135], v[112:115], v[164:167], v[132:135]
	v_mfma_f32_16x16x32_bf16 v[128:131], v[140:143], v[164:167], v[128:131]
	v_mfma_f32_16x16x32_bf16 v[116:119], v[112:115], v[172:175], v[116:119]
	v_mfma_f32_16x16x32_bf16 v[108:111], v[140:143], v[172:175], v[108:111]
	v_mfma_f32_16x16x32_bf16 v[96:99], v[112:115], v[180:183], v[96:99]
	v_mfma_f32_16x16x32_bf16 v[88:91], v[140:143], v[180:183], v[88:91]
	v_mfma_f32_16x16x32_bf16 v[80:83], v[112:115], v[188:191], v[80:83]
	v_mfma_f32_16x16x32_bf16 v[72:75], v[140:143], v[188:191], v[72:75]
	s_setprio 0
	s_setprio 1
	v_mfma_f32_16x16x32_bf16 v[124:127], v[144:147], v[160:163], v[124:127]
	v_mfma_f32_16x16x32_bf16 v[120:123], v[152:155], v[160:163], v[120:123]
	v_mfma_f32_16x16x32_bf16 v[100:103], v[144:147], v[168:171], v[100:103]
	v_mfma_f32_16x16x32_bf16 v[92:95], v[152:155], v[168:171], v[92:95]
	v_mfma_f32_16x16x32_bf16 v[84:87], v[144:147], v[176:179], v[84:87]
	v_mfma_f32_16x16x32_bf16 v[76:79], v[152:155], v[176:179], v[76:79]
	v_mfma_f32_16x16x32_bf16 v[68:71], v[144:147], v[184:187], v[68:71]
	v_mfma_f32_16x16x32_bf16 v[64:67], v[152:155], v[184:187], v[64:67]
	v_mfma_f32_16x16x32_bf16 v[124:127], v[148:151], v[164:167], v[124:127]
	v_mfma_f32_16x16x32_bf16 v[120:123], v[156:159], v[164:167], v[120:123]
	v_mfma_f32_16x16x32_bf16 v[100:103], v[148:151], v[172:175], v[100:103]
	v_mfma_f32_16x16x32_bf16 v[92:95], v[156:159], v[172:175], v[92:95]
	v_mfma_f32_16x16x32_bf16 v[84:87], v[148:151], v[180:183], v[84:87]
	v_mfma_f32_16x16x32_bf16 v[76:79], v[156:159], v[180:183], v[76:79]
	v_mfma_f32_16x16x32_bf16 v[68:71], v[148:151], v[188:191], v[68:71]
	v_mfma_f32_16x16x32_bf16 v[64:67], v[156:159], v[188:191], v[64:67]
	s_setprio 0
	s_barrier
; #define PG8_STAGE(bufoff, gbase, voff) do { _Pragma("unroll") for (int _i = 0; _i < 2; ++_i) \
;         __builtin_amdgcn_global_load_lds((const unsigned*)((const char*)(gbase) + (voff)[_i]), (LAS unsigned*)(lds + (bufoff) + ldsw + _i * 8192), 16, 0, 0); } while (0)
; #define PG8_LDA(dst, b, h) do { _Pragma("unroll") for (int m = 0; m < 4; ++m) _Pragma("unroll") for (int k = 0; k < 2; ++k) dst[m][k] = *(const LAS bf16x8*)(lds + PG8_SA(b, h) + aoff + m * 2048 + k * 1024); } while (0)
; #define PG8_LDB(dst, b, h) do { _Pragma("unroll") for (int n = 0; n < 2; ++n) _Pragma("unroll") for (int k = 0; k < 2; ++k) dst[n][k] = *(const LAS bf16x8*)(lds + PG8_SB(b, h) + boff + n * 2048 + k * 1024); } while (0)
; #define PG8_MMA(ai, bj, At, Bt) do { __builtin_amdgcn_s_setprio(1); _Pragma("unroll") for (int m = 0; m < 4; ++m) _Pragma("unroll") for (int n = 0; n < 2; ++n) _Pragma("unroll") for (int k = 0; k < 2; ++k) \
;         acc[ai][bj][m][n] = __builtin_amdgcn_mfma_f32_16x16x32_bf16(Bt[n][k], At[m][k], acc[ai][bj][m][n], 0, 0, 0); __builtin_amdgcn_s_setprio(0); } while (0)
; #define PG8_WAIT_V(n) asm volatile("s_waitcnt vmcnt(" #n ")" ::: "memory")
; #define PG8_WAIT_L(n) asm volatile("s_waitcnt lgkmcnt(" #n ")" ::: "memory")
; #define PG8_BAR __builtin_amdgcn_s_barrier()
; #define PG8_SCHED __builtin_amdgcn_sched_barrier(0)
; template <class Epi, class Sched, bool ALIGN_EPI>
; __device__ __forceinline__ void gemm_phase(LAS unsigned char* lds, const Gemm g, const Sched& S, const Epi& E) {
;     ...
;         for (int t = 0; t < nt; t += 2) {
;             const bool last = (t == nt - 2);
;             const char* a1 = cA + (size_t)(t + 1) * kstep;
;             const char* a2 = last ? nA : cA + (size_t)(t + 2) * kstep; const char* b2 = last ? nB : cB + (size_t)(t + 2) * kstep;
;             const char* a3 = a2 + kstep; const char* b3 = b2 + kstep;
;             PG8_LDB(B0, 0, 0); PG8_LDB(B1, 0, 1); PG8_SCHED; PG8_LDA(At, 0, 0); PG8_STAGE(PG8_SA(1, 1), a1 + hstepA, voffA);
;     ...
;             PG8_LDA(At, 1, 1); PG8_STAGE(PG8_SB(1, 0), b3, voffB); PG8_STAGE(PG8_SB(1, 1), b3 + hstepB, voffB); PG8_STAGE(PG8_SA(1, 0), a3, voffA);
;             PG8_WAIT_V(8); PG8_WAIT_L(0); PG8_BAR; PG8_MMA(1, 0, At, B0); PG8_MMA(1, 1, At, B1); PG8_BAR; PG8_SCHED;
	s_add_i32 s52, s52, s50
	v_lshl_add_u64 v[194:195], v[194:195], 0, s[12:13]
	s_mov_b32 m0, s52
	ds_read_b128 v[160:163], v248 offset:49152
	ds_read_b128 v[164:167], v248 offset:50176
	ds_read_b128 v[168:171], v248 offset:51200
	ds_read_b128 v[172:175], v248 offset:52224
	ds_read_b128 v[176:179], v248 offset:53248
	ds_read_b128 v[180:183], v248 offset:54272
	ds_read_b128 v[184:187], v248 offset:55296
	ds_read_b128 v[188:191], v248 offset:56320
	global_load_lds_dwordx4 v[194:195], off
	s_add_i32 m0, s52, 0x2000
	s_add_u32 s46, s46, 0x100080
	v_lshl_add_u64 v[194:195], v[196:197], 0, s[12:13]
	s_addc_u32 s47, s47, 0
	s_add_i32 s52, s53, s50
	global_load_lds_dwordx4 v[194:195], off
	v_lshl_add_u64 v[194:195], s[46:47], 0, v[216:217]
	s_mov_b32 m0, s52
	s_nop 0
	global_load_lds_dwordx4 v[194:195], off
	v_lshl_add_u64 v[194:195], s[46:47], 0, v[212:213]
	s_add_i32 m0, s52, 0x2000
	s_nop 0
	global_load_lds_dwordx4 v[194:195], off
	v_lshl_add_u64 v[194:195], v[198:199], 0, s[12:13]
	s_mov_b32 m0, s59
	s_nop 0
	global_load_lds_dwordx4 v[194:195], off
	v_lshl_add_u64 v[194:195], v[200:201], 0, s[12:13]
	s_mov_b32 m0, s4
	s_nop 0
	global_load_lds_dwordx4 v[194:195], off
	s_waitcnt vmcnt(8)
	s_waitcnt lgkmcnt(0)
	s_barrier
	s_setprio 1
	s_waitcnt lgkmcnt(0)
	v_mfma_f32_16x16x32_bf16 v[60:63], v[104:107], v[160:163], v[60:63]
	v_mfma_f32_16x16x32_bf16 v[56:59], v[136:139], v[160:163], v[56:59]
	v_mfma_f32_16x16x32_bf16 v[44:47], v[104:107], v[168:171], v[44:47]
	v_mfma_f32_16x16x32_bf16 v[40:43], v[136:139], v[168:171], v[40:43]
	v_mfma_f32_16x16x32_bf16 v[32:35], v[104:107], v[176:179], v[32:35]
	v_mfma_f32_16x16x32_bf16 v[24:27], v[136:139], v[176:179], v[24:27]
	v_mfma_f32_16x16x32_bf16 v[16:19], v[104:107], v[184:187], v[16:19]
	v_mfma_f32_16x16x32_bf16 v[8:11], v[136:139], v[184:187], v[8:11]
	v_mfma_f32_16x16x32_bf16 v[60:63], v[112:115], v[164:167], v[60:63]
	v_mfma_f32_16x16x32_bf16 v[56:59], v[140:143], v[164:167], v[56:59]
	v_mfma_f32_16x16x32_bf16 v[44:47], v[112:115], v[172:175], v[44:47]
	v_mfma_f32_16x16x32_bf16 v[40:43], v[140:143], v[172:175], v[40:43]
	v_mfma_f32_16x16x32_bf16 v[32:35], v[112:115], v[180:183], v[32:35]
	v_mfma_f32_16x16x32_bf16 v[24:27], v[140:143], v[180:183], v[24:27]
	v_mfma_f32_16x16x32_bf16 v[16:19], v[112:115], v[188:191], v[16:19]
	v_mfma_f32_16x16x32_bf16 v[8:11], v[140:143], v[188:191], v[8:11]
	s_setprio 0
	s_setprio 1
	v_mfma_f32_16x16x32_bf16 v[52:55], v[144:147], v[160:163], v[52:55]
	s_add_i32 s92, s92, 2
	v_mfma_f32_16x16x32_bf16 v[48:51], v[152:155], v[160:163], v[48:51]
	s_add_u32 s44, s44, 0x100
	v_mfma_f32_16x16x32_bf16 v[36:39], v[144:147], v[168:171], v[36:39]
	s_addc_u32 s45, s45, 0
	v_mfma_f32_16x16x32_bf16 v[28:31], v[152:155], v[168:171], v[28:31]
	s_add_u32 s65, s65, 0x100
	v_mfma_f32_16x16x32_bf16 v[20:23], v[144:147], v[176:179], v[20:23]
	s_addc_u32 s81, s81, 0
	v_mfma_f32_16x16x32_bf16 v[12:15], v[152:155], v[176:179], v[12:15]
	s_add_u32 s46, s44, 0xfff00080
	v_mfma_f32_16x16x32_bf16 v[4:7], v[144:147], v[184:187], v[4:7]
	s_addc_u32 s47, s45, -1
	v_mfma_f32_16x16x32_bf16 v[0:3], v[152:155], v[184:187], v[0:3]
	s_add_i32 s52, 0, 0x10000
	v_mfma_f32_16x16x32_bf16 v[52:55], v[148:151], v[164:167], v[52:55]
	s_cmp_eq_u32 s92, 60
	v_mfma_f32_16x16x32_bf16 v[48:51], v[156:159], v[164:167], v[48:51]
	s_cselect_b32 s55, s56, s47
	v_mfma_f32_16x16x32_bf16 v[36:39], v[148:151], v[172:175], v[36:39]
	s_cselect_b32 s54, s57, s46
	v_mfma_f32_16x16x32_bf16 v[28:31], v[156:159], v[172:175], v[28:31]
	s_cselect_b32 s47, s63, s81
	v_mfma_f32_16x16x32_bf16 v[20:23], v[148:151], v[180:183], v[20:23]
	s_cselect_b32 s46, s64, s65
	v_mfma_f32_16x16x32_bf16 v[12:15], v[156:159], v[180:183], v[12:15]
	s_add_i32 s53, 0, 0x14000
	v_mfma_f32_16x16x32_bf16 v[4:7], v[148:151], v[188:191], v[4:7]
	s_cmp_gt_u32 s92, 61
	v_mfma_f32_16x16x32_bf16 v[0:3], v[156:159], v[188:191], v[0:3]
	s_setprio 0
	s_barrier
	s_cbranch_scc0 .LBB0_209
	s_and_b64 vcc, exec, s[38:39]
	s_cbranch_vccz .LBB0_212
	s_barrier

; #define PG8_STAGE(bufoff, gbase, voff) do { _Pragma("unroll") for (int _i = 0; _i < 2; ++_i) \
;         __builtin_amdgcn_global_load_lds((const unsigned*)((const char*)(gbase) + (voff)[_i]), (LAS unsigned*)(lds + (bufoff) + ldsw + _i * 8192), 16, 0, 0); } while (0)
; #define PG8_LDA(dst, b, h) do { _Pragma("unroll") for (int m = 0; m < 4; ++m) _Pragma("unroll") for (int k = 0; k < 2; ++k) dst[m][k] = *(const LAS bf16x8*)(lds + PG8_SA(b, h) + aoff + m * 2048 + k * 1024); } while (0)
; #define PG8_LDB(dst, b, h) do { _Pragma("unroll") for (int n = 0; n < 2; ++n) _Pragma("unroll") for (int k = 0; k < 2; ++k) dst[n][k] = *(const LAS bf16x8*)(lds + PG8_SB(b, h) + boff + n * 2048 + k * 1024); } while (0)
; #define PG8_MMA(ai, bj, At, Bt) do { __builtin_amdgcn_s_setprio(1); _Pragma("unroll") for (int m = 0; m < 4; ++m) _Pragma("unroll") for (int n = 0; n < 2; ++n) _Pragma("unroll") for (int k = 0; k < 2; ++k) \
;         acc[ai][bj][m][n] = __builtin_amdgcn_mfma_f32_16x16x32_bf16(Bt[n][k], At[m][k], acc[ai][bj][m][n], 0, 0, 0); __builtin_amdgcn_s_setprio(0); } while (0)
; #define PG8_WAIT_V(n) asm volatile("s_waitcnt vmcnt(" #n ")" ::: "memory")
; #define PG8_WAIT_L(n) asm volatile("s_waitcnt lgkmcnt(" #n ")" ::: "memory")
; template <class Epi, class Sched, bool ALIGN_EPI>
; __device__ __forceinline__ void gemm_phase(LAS unsigned char* lds, const Gemm g, const Sched& S, const Epi& E) {
;     ...
;         const bool has_next = S.next(ui + 1, nxt);
;         const char* nA = has_next ? (const char*)g.A + (size_t)nxt.pm * tstepA : cA; const char* nB = has_next ? (const char*)g.Bt + (size_t)nxt.pn * tstepB : cB;
;         for (int t = 0; t < nt; t += 2) {
;             const bool last = (t == nt - 2);
;             const char* a1 = cA + (size_t)(t + 1) * kstep;
;             const char* a2 = last ? nA : cA + (size_t)(t + 2) * kstep; const char* b2 = last ? nB : cB + (size_t)(t + 2) * kstep;
;             const char* a3 = a2 + kstep; const char* b3 = b2 + kstep;
;             PG8_LDB(B0, 0, 0); PG8_LDB(B1, 0, 1); PG8_SCHED; PG8_LDA(At, 0, 0); PG8_STAGE(PG8_SA(1, 1), a1 + hstepA, voffA);
;             PG8_WAIT_V(8); PG8_WAIT_L(0); PG8_BAR; PG8_MMA(0, 0, At, B0); PG8_MMA(0, 1, At, B1); PG8_BAR; PG8_SCHED;
;             PG8_LDA(At, 0, 1); PG8_STAGE(PG8_SB(0, 0), b2, voffB); PG8_STAGE(PG8_SB(0, 1), b2 + hstepB, voffB); PG8_STAGE(PG8_SA(0, 0), a2, voffA);
.LBB0_286:
	s_ashr_i32 s23, s22, 31
	s_lshl_b64 s[38:39], s[22:23], 19
	s_add_u32 s38, s48, s38
	s_addc_u32 s39, s49, s39
	s_and_b64 s[40:41], s[42:43], exec
	s_cselect_b32 s23, s39, s45
	s_cselect_b32 s85, s38, s44
	s_ashr_i32 s21, s20, 31
	s_lshl_b64 s[40:41], s[20:21], 19
	s_add_u32 s40, s50, s40
	s_addc_u32 s41, s51, s41
	s_and_b64 s[54:55], s[42:43], exec
	s_cselect_b32 s21, s41, s47
	s_cselect_b32 s86, s40, s46
	s_add_u32 s44, s44, 0x40080
	s_addc_u32 s45, s45, 0
	s_add_u32 s87, s46, 0x100
	s_addc_u32 s90, s47, 0
	s_mov_b32 s91, -2
	s_add_u32 s46, s44, 0xfffc0080
	s_addc_u32 s47, s45, -1
	s_add_i32 s92, 0, 0x10000
	s_cmp_eq_u32 s91, 12
	s_cselect_b32 s55, s23, s47
	s_cselect_b32 s54, s85, s46
	s_cselect_b32 s47, s21, s90
	s_cselect_b32 s46, s86, s87
	s_add_i32 s4, 0, 0x14000
	v_add_u32_e32 v132, s92, v160
	v_add_u32_e32 v170, s4, v160
	ds_read_b128 v[120:123], v132
	ds_read_b128 v[124:127], v132 offset:1024
	ds_read_b128 v[128:131], v132 offset:2048
	ds_read_b128 v[132:135], v132 offset:3072
	ds_read_b128 v[154:157], v170
	ds_read_b128 v[162:165], v170 offset:1024
	ds_read_b128 v[166:169], v170 offset:2048
	ds_read_b128 v[170:173], v170 offset:3072
	v_lshl_add_u64 v[190:191], s[44:45], 0, v[150:151]
	s_add_i32 m0, s53, 0xc000
	ds_read_b128 v[174:177], v161
	ds_read_b128 v[178:181], v161 offset:1024
	ds_read_b128 v[182:185], v161 offset:2048
	ds_read_b128 v[186:189], v161 offset:3072
	ds_read_b128 v[194:197], v161 offset:4096
	ds_read_b128 v[198:201], v161 offset:5120
	ds_read_b128 v[202:205], v161 offset:6144
	ds_read_b128 v[212:215], v161 offset:7168
	global_load_lds_dwordx4 v[190:191], off
	v_lshl_add_u64 v[190:191], s[44:45], 0, v[152:153]
	s_add_i32 m0, s53, 0xe000
	s_nop 0
	global_load_lds_dwordx4 v[190:191], off
	s_waitcnt vmcnt(8)
	s_waitcnt lgkmcnt(0)
	s_barrier
	s_setprio 1
	s_waitcnt lgkmcnt(0)
	v_mfma_f32_16x16x32_bf16 v[140:143], v[120:123], v[174:177], 0
	v_mfma_f32_16x16x32_bf16 v[136:139], v[128:131], v[174:177], 0
	v_mfma_f32_16x16x32_bf16 v[108:111], v[120:123], v[182:185], 0
	v_mfma_f32_16x16x32_bf16 v[104:107], v[128:131], v[182:185], 0
	v_mfma_f32_16x16x32_bf16 v[92:95], v[120:123], v[194:197], 0
	v_mfma_f32_16x16x32_bf16 v[88:91], v[128:131], v[194:197], 0
	v_mfma_f32_16x16x32_bf16 v[76:79], v[120:123], v[202:205], 0
	v_mfma_f32_16x16x32_bf16 v[72:75], v[128:131], v[202:205], 0
	v_mfma_f32_16x16x32_bf16 v[140:143], v[124:127], v[178:181], v[140:143]
	v_mfma_f32_16x16x32_bf16 v[136:139], v[132:135], v[178:181], v[136:139]
	v_mfma_f32_16x16x32_bf16 v[108:111], v[124:127], v[186:189], v[108:111]
	v_mfma_f32_16x16x32_bf16 v[104:107], v[132:135], v[186:189], v[104:107]
	v_mfma_f32_16x16x32_bf16 v[92:95], v[124:127], v[198:201], v[92:95]
	v_mfma_f32_16x16x32_bf16 v[88:91], v[132:135], v[198:201], v[88:91]
	v_mfma_f32_16x16x32_bf16 v[76:79], v[124:127], v[212:215], v[76:79]
	v_mfma_f32_16x16x32_bf16 v[72:75], v[132:135], v[212:215], v[72:75]
	s_setprio 0
	s_setprio 1
	v_mfma_f32_16x16x32_bf16 v[116:119], v[154:157], v[174:177], 0
	v_mfma_f32_16x16x32_bf16 v[112:115], v[166:169], v[174:177], 0
	v_mfma_f32_16x16x32_bf16 v[100:103], v[154:157], v[182:185], 0
	v_mfma_f32_16x16x32_bf16 v[96:99], v[166:169], v[182:185], 0
	v_mfma_f32_16x16x32_bf16 v[84:87], v[154:157], v[194:197], 0
	v_mfma_f32_16x16x32_bf16 v[80:83], v[166:169], v[194:197], 0
	v_mfma_f32_16x16x32_bf16 v[68:71], v[154:157], v[202:205], 0
	v_mfma_f32_16x16x32_bf16 v[64:67], v[166:169], v[202:205], 0
	v_mfma_f32_16x16x32_bf16 v[116:119], v[162:165], v[178:181], v[116:119]
	v_mfma_f32_16x16x32_bf16 v[112:115], v[170:173], v[178:181], v[112:115]
	v_mfma_f32_16x16x32_bf16 v[100:103], v[162:165], v[186:189], v[100:103]
	v_mfma_f32_16x16x32_bf16 v[96:99], v[170:173], v[186:189], v[96:99]
	v_mfma_f32_16x16x32_bf16 v[84:87], v[162:165], v[198:201], v[84:87]
	v_mfma_f32_16x16x32_bf16 v[80:83], v[170:173], v[198:201], v[80:83]
	v_mfma_f32_16x16x32_bf16 v[68:71], v[162:165], v[212:215], v[68:71]
	v_mfma_f32_16x16x32_bf16 v[64:67], v[170:173], v[212:215], v[64:67]
	s_setprio 0
	s_barrier
	s_add_i32 s5, s92, s52
	v_lshl_add_u64 v[190:191], s[46:47], 0, v[192:193]
	s_mov_b32 m0, s5
	ds_read_b128 v[174:177], v161 offset:16384
	ds_read_b128 v[178:181], v161 offset:17408
	ds_read_b128 v[182:185], v161 offset:18432
	ds_read_b128 v[186:189], v161 offset:19456
	ds_read_b128 v[194:197], v161 offset:20480
	ds_read_b128 v[198:201], v161 offset:21504
	ds_read_b128 v[202:205], v161 offset:22528
	ds_read_b128 v[212:215], v161 offset:23552
	global_load_lds_dwordx4 v[190:191], off
	s_add_i32 m0, s5, 0x2000
	s_add_u32 vcc_lo, s46, 0x40000
	v_lshl_add_u64 v[216:217], s[46:47], 0, v[144:145]
	s_addc_u32 vcc_hi, s47, 0
	s_add_i32 s4, s4, s52
	global_load_lds_dwordx4 v[216:217], off
	v_lshl_add_u64 v[218:219], vcc, 0, v[192:193]
	s_mov_b32 m0, s4
	v_lshl_add_u64 v[220:221], s[54:55], 0, v[146:147]
	global_load_lds_dwordx4 v[218:219], off
	v_lshl_add_u64 v[218:219], vcc, 0, v[144:145]
	s_add_i32 m0, s4, 0x2000
	s_nop 0
	global_load_lds_dwordx4 v[218:219], off
	v_lshl_add_u64 v[218:219], s[54:55], 0, v[148:149]
	s_mov_b32 m0, s53
	s_nop 0
	global_load_lds_dwordx4 v[218:219], off
	s_mov_b32 m0, s56
	s_nop 0
	global_load_lds_dwordx4 v[220:221], off
	s_waitcnt vmcnt(8)
	s_waitcnt lgkmcnt(0)
	s_barrier
; #define PG8_STAGE(bufoff, gbase, voff) do { _Pragma("unroll") for (int _i = 0; _i < 2; ++_i) \
;         __builtin_amdgcn_global_load_lds((const unsigned*)((const char*)(gbase) + (voff)[_i]), (LAS unsigned*)(lds + (bufoff) + ldsw + _i * 8192), 16, 0, 0); } while (0)
; #define PG8_LDA(dst, b, h) do { _Pragma("unroll") for (int m = 0; m < 4; ++m) _Pragma("unroll") for (int k = 0; k < 2; ++k) dst[m][k] = *(const LAS bf16x8*)(lds + PG8_SA(b, h) + aoff + m * 2048 + k * 1024); } while (0)
; #define PG8_LDB(dst, b, h) do { _Pragma("unroll") for (int n = 0; n < 2; ++n) _Pragma("unroll") for (int k = 0; k < 2; ++k) dst[n][k] = *(const LAS bf16x8*)(lds + PG8_SB(b, h) + boff + n * 2048 + k * 1024); } while (0)
; #define PG8_MMA(ai, bj, At, Bt) do { __builtin_amdgcn_s_setprio(1); _Pragma("unroll") for (int m = 0; m < 4; ++m) _Pragma("unroll") for (int n = 0; n < 2; ++n) _Pragma("unroll") for (int k = 0; k < 2; ++k) \
;         acc[ai][bj][m][n] = __builtin_amdgcn_mfma_f32_16x16x32_bf16(Bt[n][k], At[m][k], acc[ai][bj][m][n], 0, 0, 0); __builtin_amdgcn_s_setprio(0); } while (0)
; #define PG8_WAIT_V(n) asm volatile("s_waitcnt vmcnt(" #n ")" ::: "memory")
; #define PG8_WAIT_L(n) asm volatile("s_waitcnt lgkmcnt(" #n ")" ::: "memory")
; #define PG8_BAR __builtin_amdgcn_s_barrier()
; #define PG8_SCHED __builtin_amdgcn_sched_barrier(0)
; template <class Epi, class Sched, bool ALIGN_EPI>
; __device__ __forceinline__ void gemm_phase(LAS unsigned char* lds, const Gemm g, const Sched& S, const Epi& E) {
;     ...
;             PG8_LDA(At, 0, 1); PG8_STAGE(PG8_SB(0, 0), b2, voffB); PG8_STAGE(PG8_SB(0, 1), b2 + hstepB, voffB); PG8_STAGE(PG8_SA(0, 0), a2, voffA);
;             PG8_WAIT_V(8); PG8_WAIT_L(0); PG8_BAR; PG8_MMA(1, 0, At, B0); PG8_MMA(1, 1, At, B1); PG8_BAR; PG8_SCHED;
;             PG8_LDB(B0, 1, 0); PG8_LDB(B1, 1, 1); PG8_SCHED; PG8_LDA(At, 1, 0); PG8_STAGE(PG8_SA(0, 1), a2 + hstepA, voffA);
;             PG8_WAIT_V(8); PG8_WAIT_L(0); PG8_BAR; PG8_MMA(0, 0, At, B0); PG8_MMA(0, 1, At, B1); PG8_BAR; PG8_SCHED;
	s_setprio 1
	s_waitcnt lgkmcnt(0)
	v_mfma_f32_16x16x32_bf16 v[60:63], v[120:123], v[174:177], 0
	v_mfma_f32_16x16x32_bf16 v[56:59], v[128:131], v[174:177], 0
	v_mfma_f32_16x16x32_bf16 v[48:51], v[120:123], v[182:185], 0
	v_mfma_f32_16x16x32_bf16 v[40:43], v[128:131], v[182:185], 0
	v_mfma_f32_16x16x32_bf16 v[32:35], v[120:123], v[194:197], 0
	v_mfma_f32_16x16x32_bf16 v[24:27], v[128:131], v[194:197], 0
	v_mfma_f32_16x16x32_bf16 v[16:19], v[120:123], v[202:205], 0
	v_mfma_f32_16x16x32_bf16 v[8:11], v[128:131], v[202:205], 0
	v_mfma_f32_16x16x32_bf16 v[60:63], v[124:127], v[178:181], v[60:63]
	v_mfma_f32_16x16x32_bf16 v[56:59], v[132:135], v[178:181], v[56:59]
	v_mfma_f32_16x16x32_bf16 v[48:51], v[124:127], v[186:189], v[48:51]
	v_mfma_f32_16x16x32_bf16 v[40:43], v[132:135], v[186:189], v[40:43]
	v_mfma_f32_16x16x32_bf16 v[32:35], v[124:127], v[198:201], v[32:35]
	v_mfma_f32_16x16x32_bf16 v[24:27], v[132:135], v[198:201], v[24:27]
	v_mfma_f32_16x16x32_bf16 v[16:19], v[124:127], v[212:215], v[16:19]
	v_mfma_f32_16x16x32_bf16 v[8:11], v[132:135], v[212:215], v[8:11]
	s_setprio 0
	s_setprio 1
	v_mfma_f32_16x16x32_bf16 v[52:55], v[154:157], v[174:177], 0
	v_mfma_f32_16x16x32_bf16 v[44:47], v[166:169], v[174:177], 0
	v_mfma_f32_16x16x32_bf16 v[36:39], v[154:157], v[182:185], 0
	v_mfma_f32_16x16x32_bf16 v[28:31], v[166:169], v[182:185], 0
	v_mfma_f32_16x16x32_bf16 v[20:23], v[154:157], v[194:197], 0
	v_mfma_f32_16x16x32_bf16 v[12:15], v[166:169], v[194:197], 0
	v_mfma_f32_16x16x32_bf16 v[4:7], v[154:157], v[202:205], 0
	v_mfma_f32_16x16x32_bf16 v[0:3], v[166:169], v[202:205], 0
	v_mfma_f32_16x16x32_bf16 v[52:55], v[162:165], v[178:181], v[52:55]
	v_mfma_f32_16x16x32_bf16 v[44:47], v[170:173], v[178:181], v[44:47]
	v_mfma_f32_16x16x32_bf16 v[36:39], v[162:165], v[186:189], v[36:39]
	v_mfma_f32_16x16x32_bf16 v[28:31], v[170:173], v[186:189], v[28:31]
	v_mfma_f32_16x16x32_bf16 v[20:23], v[162:165], v[198:201], v[20:23]
	v_mfma_f32_16x16x32_bf16 v[12:15], v[170:173], v[198:201], v[12:15]
	v_mfma_f32_16x16x32_bf16 v[4:7], v[162:165], v[212:215], v[4:7]
	v_mfma_f32_16x16x32_bf16 v[0:3], v[170:173], v[212:215], v[0:3]
	s_setprio 0
	s_barrier
	s_add_i32 s4, 0, 0x18000
	s_add_i32 s5, 0, 0x1c000
	v_add_u32_e32 v132, s4, v160
	v_add_u32_e32 v170, s5, v160
	ds_read_b128 v[120:123], v132
	ds_read_b128 v[124:127], v132 offset:1024
	ds_read_b128 v[128:131], v132 offset:2048
	ds_read_b128 v[132:135], v132 offset:3072
	ds_read_b128 v[154:157], v170
	ds_read_b128 v[162:165], v170 offset:1024
	ds_read_b128 v[166:169], v170 offset:2048
	ds_read_b128 v[170:173], v170 offset:3072
	s_add_u32 s54, s54, 0x40000
	s_addc_u32 s55, s55, 0
	s_mov_b32 m0, s57
	v_lshl_add_u64 v[222:223], s[54:55], 0, v[148:149]
	ds_read_b128 v[174:177], v161 offset:32768
	ds_read_b128 v[178:181], v161 offset:33792
	ds_read_b128 v[182:185], v161 offset:34816
	ds_read_b128 v[186:189], v161 offset:35840
	ds_read_b128 v[194:197], v161 offset:36864
	ds_read_b128 v[198:201], v161 offset:37888
	ds_read_b128 v[202:205], v161 offset:38912
	ds_read_b128 v[212:215], v161 offset:39936
	global_load_lds_dwordx4 v[222:223], off
	v_lshl_add_u64 v[222:223], s[54:55], 0, v[146:147]
	s_mov_b32 m0, s58
	s_nop 0
	global_load_lds_dwordx4 v[222:223], off
	s_waitcnt vmcnt(8)
	s_waitcnt lgkmcnt(0)
	s_barrier
	s_setprio 1
	s_waitcnt lgkmcnt(0)
	v_mfma_f32_16x16x32_bf16 v[140:143], v[120:123], v[174:177], v[140:143]
	v_mfma_f32_16x16x32_bf16 v[136:139], v[128:131], v[174:177], v[136:139]
	v_mfma_f32_16x16x32_bf16 v[108:111], v[120:123], v[182:185], v[108:111]
	v_mfma_f32_16x16x32_bf16 v[104:107], v[128:131], v[182:185], v[104:107]
	v_mfma_f32_16x16x32_bf16 v[92:95], v[120:123], v[194:197], v[92:95]
	v_mfma_f32_16x16x32_bf16 v[88:91], v[128:131], v[194:197], v[88:91]
	v_mfma_f32_16x16x32_bf16 v[76:79], v[120:123], v[202:205], v[76:79]
	v_mfma_f32_16x16x32_bf16 v[72:75], v[128:131], v[202:205], v[72:75]
	v_mfma_f32_16x16x32_bf16 v[140:143], v[124:127], v[178:181], v[140:143]
	v_mfma_f32_16x16x32_bf16 v[136:139], v[132:135], v[178:181], v[136:139]
	v_mfma_f32_16x16x32_bf16 v[108:111], v[124:127], v[186:189], v[108:111]
	v_mfma_f32_16x16x32_bf16 v[104:107], v[132:135], v[186:189], v[104:107]
	v_mfma_f32_16x16x32_bf16 v[92:95], v[124:127], v[198:201], v[92:95]
	v_mfma_f32_16x16x32_bf16 v[88:91], v[132:135], v[198:201], v[88:91]
	v_mfma_f32_16x16x32_bf16 v[76:79], v[124:127], v[212:215], v[76:79]
	v_mfma_f32_16x16x32_bf16 v[72:75], v[132:135], v[212:215], v[72:75]
	s_setprio 0
	s_setprio 1
	v_mfma_f32_16x16x32_bf16 v[116:119], v[154:157], v[174:177], v[116:119]
	v_mfma_f32_16x16x32_bf16 v[112:115], v[166:169], v[174:177], v[112:115]
	v_mfma_f32_16x16x32_bf16 v[100:103], v[154:157], v[182:185], v[100:103]
	v_mfma_f32_16x16x32_bf16 v[96:99], v[166:169], v[182:185], v[96:99]
	v_mfma_f32_16x16x32_bf16 v[84:87], v[154:157], v[194:197], v[84:87]
	v_mfma_f32_16x16x32_bf16 v[80:83], v[166:169], v[194:197], v[80:83]
	v_mfma_f32_16x16x32_bf16 v[68:71], v[154:157], v[202:205], v[68:71]
	v_mfma_f32_16x16x32_bf16 v[64:67], v[166:169], v[202:205], v[64:67]
	v_mfma_f32_16x16x32_bf16 v[116:119], v[162:165], v[178:181], v[116:119]
	v_mfma_f32_16x16x32_bf16 v[112:115], v[170:173], v[178:181], v[112:115]
	v_mfma_f32_16x16x32_bf16 v[100:103], v[162:165], v[186:189], v[100:103]
	v_mfma_f32_16x16x32_bf16 v[96:99], v[170:173], v[186:189], v[96:99]
	v_mfma_f32_16x16x32_bf16 v[84:87], v[162:165], v[198:201], v[84:87]
	v_mfma_f32_16x16x32_bf16 v[80:83], v[170:173], v[198:201], v[80:83]
	v_mfma_f32_16x16x32_bf16 v[68:71], v[162:165], v[212:215], v[68:71]
	v_mfma_f32_16x16x32_bf16 v[64:67], v[170:173], v[212:215], v[64:67]
	s_setprio 0
	s_barrier
; #define PG8_STAGE(bufoff, gbase, voff) do { _Pragma("unroll") for (int _i = 0; _i < 2; ++_i) \
;         __builtin_amdgcn_global_load_lds((const unsigned*)((const char*)(gbase) + (voff)[_i]), (LAS unsigned*)(lds + (bufoff) + ldsw + _i * 8192), 16, 0, 0); } while (0)
; #define PG8_LDA(dst, b, h) do { _Pragma("unroll") for (int m = 0; m < 4; ++m) _Pragma("unroll") for (int k = 0; k < 2; ++k) dst[m][k] = *(const LAS bf16x8*)(lds + PG8_SA(b, h) + aoff + m * 2048 + k * 1024); } while (0)
; #define PG8_LDB(dst, b, h) do { _Pragma("unroll") for (int n = 0; n < 2; ++n) _Pragma("unroll") for (int k = 0; k < 2; ++k) dst[n][k] = *(const LAS bf16x8*)(lds + PG8_SB(b, h) + boff + n * 2048 + k * 1024); } while (0)
; #define PG8_MMA(ai, bj, At, Bt) do { __builtin_amdgcn_s_setprio(1); _Pragma("unroll") for (int m = 0; m < 4; ++m) _Pragma("unroll") for (int n = 0; n < 2; ++n) _Pragma("unroll") for (int k = 0; k < 2; ++k) \
;         acc[ai][bj][m][n] = __builtin_amdgcn_mfma_f32_16x16x32_bf16(Bt[n][k], At[m][k], acc[ai][bj][m][n], 0, 0, 0); __builtin_amdgcn_s_setprio(0); } while (0)
; #define PG8_WAIT_V(n) asm volatile("s_waitcnt vmcnt(" #n ")" ::: "memory")
; #define PG8_WAIT_L(n) asm volatile("s_waitcnt lgkmcnt(" #n ")" ::: "memory")
; #define PG8_BAR __builtin_amdgcn_s_barrier()
; #define PG8_SCHED __builtin_amdgcn_sched_barrier(0)
; template <class Epi, class Sched, bool ALIGN_EPI>
; __device__ __forceinline__ void gemm_phase(LAS unsigned char* lds, const Gemm g, const Sched& S, const Epi& E) {
;     ...
;         for (int t = 0; t < nt; t += 2) {
;             const bool last = (t == nt - 2);
;             const char* a1 = cA + (size_t)(t + 1) * kstep;
;             const char* a2 = last ? nA : cA + (size_t)(t + 2) * kstep; const char* b2 = last ? nB : cB + (size_t)(t + 2) * kstep;
;             const char* a3 = a2 + kstep; const char* b3 = b2 + kstep;
;             PG8_LDB(B0, 0, 0); PG8_LDB(B1, 0, 1); PG8_SCHED; PG8_LDA(At, 0, 0); PG8_STAGE(PG8_SA(1, 1), a1 + hstepA, voffA);
;     ...
;             PG8_LDA(At, 1, 1); PG8_STAGE(PG8_SB(1, 0), b3, voffB); PG8_STAGE(PG8_SB(1, 1), b3 + hstepB, voffB); PG8_STAGE(PG8_SA(1, 0), a3, voffA);
;             PG8_WAIT_V(8); PG8_WAIT_L(0); PG8_BAR; PG8_MMA(1, 0, At, B0); PG8_MMA(1, 1, At, B1); PG8_BAR; PG8_SCHED;
	s_add_i32 s4, s4, s52
	v_lshl_add_u64 v[190:191], v[190:191], 0, s[12:13]
	s_mov_b32 m0, s4
	ds_read_b128 v[174:177], v161 offset:49152
	ds_read_b128 v[178:181], v161 offset:50176
	ds_read_b128 v[182:185], v161 offset:51200
	ds_read_b128 v[186:189], v161 offset:52224
	ds_read_b128 v[194:197], v161 offset:53248
	ds_read_b128 v[198:201], v161 offset:54272
	ds_read_b128 v[202:205], v161 offset:55296
	ds_read_b128 v[212:215], v161 offset:56320
	global_load_lds_dwordx4 v[190:191], off
	s_add_i32 m0, s4, 0x2000
	s_add_u32 s46, s46, 0x40080
	v_lshl_add_u64 v[190:191], v[216:217], 0, s[12:13]
	s_addc_u32 s47, s47, 0
	s_add_i32 s4, s5, s52
	global_load_lds_dwordx4 v[190:191], off
	v_lshl_add_u64 v[190:191], s[46:47], 0, v[192:193]
	s_mov_b32 m0, s4
	s_nop 0
	global_load_lds_dwordx4 v[190:191], off
	v_lshl_add_u64 v[190:191], s[46:47], 0, v[144:145]
	s_add_i32 m0, s4, 0x2000
	s_nop 0
	global_load_lds_dwordx4 v[190:191], off
	v_lshl_add_u64 v[190:191], v[218:219], 0, s[12:13]
	s_mov_b32 m0, s65
	s_nop 0
	global_load_lds_dwordx4 v[190:191], off
	v_lshl_add_u64 v[190:191], v[220:221], 0, s[12:13]
	s_mov_b32 m0, s66
	s_nop 0
	global_load_lds_dwordx4 v[190:191], off
	s_waitcnt vmcnt(8)
	s_waitcnt lgkmcnt(0)
	s_barrier
	s_setprio 1
	s_waitcnt lgkmcnt(0)
	v_mfma_f32_16x16x32_bf16 v[60:63], v[120:123], v[174:177], v[60:63]
	v_mfma_f32_16x16x32_bf16 v[56:59], v[128:131], v[174:177], v[56:59]
	v_mfma_f32_16x16x32_bf16 v[48:51], v[120:123], v[182:185], v[48:51]
	v_mfma_f32_16x16x32_bf16 v[40:43], v[128:131], v[182:185], v[40:43]
	v_mfma_f32_16x16x32_bf16 v[32:35], v[120:123], v[194:197], v[32:35]
	v_mfma_f32_16x16x32_bf16 v[24:27], v[128:131], v[194:197], v[24:27]
	v_mfma_f32_16x16x32_bf16 v[16:19], v[120:123], v[202:205], v[16:19]
	v_mfma_f32_16x16x32_bf16 v[8:11], v[128:131], v[202:205], v[8:11]
	v_mfma_f32_16x16x32_bf16 v[60:63], v[124:127], v[178:181], v[60:63]
	v_mfma_f32_16x16x32_bf16 v[56:59], v[132:135], v[178:181], v[56:59]
	v_mfma_f32_16x16x32_bf16 v[48:51], v[124:127], v[186:189], v[48:51]
	v_mfma_f32_16x16x32_bf16 v[40:43], v[132:135], v[186:189], v[40:43]
	v_mfma_f32_16x16x32_bf16 v[32:35], v[124:127], v[198:201], v[32:35]
	v_mfma_f32_16x16x32_bf16 v[24:27], v[132:135], v[198:201], v[24:27]
	v_mfma_f32_16x16x32_bf16 v[16:19], v[124:127], v[212:215], v[16:19]
	v_mfma_f32_16x16x32_bf16 v[8:11], v[132:135], v[212:215], v[8:11]
	s_setprio 0
	s_setprio 1
	v_mfma_f32_16x16x32_bf16 v[52:55], v[154:157], v[174:177], v[52:55]
	s_add_i32 s91, s91, 2
	v_mfma_f32_16x16x32_bf16 v[44:47], v[166:169], v[174:177], v[44:47]
	s_add_u32 s44, s44, 0x100
	v_mfma_f32_16x16x32_bf16 v[36:39], v[154:157], v[182:185], v[36:39]
	s_addc_u32 s45, s45, 0
	v_mfma_f32_16x16x32_bf16 v[28:31], v[166:169], v[182:185], v[28:31]
	s_add_u32 s87, s87, 0x100
	v_mfma_f32_16x16x32_bf16 v[20:23], v[154:157], v[194:197], v[20:23]
	s_addc_u32 s90, s90, 0
	v_mfma_f32_16x16x32_bf16 v[12:15], v[166:169], v[194:197], v[12:15]
	s_add_u32 s46, s44, 0xfffc0080
	v_mfma_f32_16x16x32_bf16 v[4:7], v[154:157], v[202:205], v[4:7]
	s_addc_u32 s47, s45, -1
	v_mfma_f32_16x16x32_bf16 v[0:3], v[166:169], v[202:205], v[0:3]
	s_add_i32 s92, 0, 0x10000
	v_mfma_f32_16x16x32_bf16 v[52:55], v[162:165], v[178:181], v[52:55]
	s_cmp_eq_u32 s91, 12
	v_mfma_f32_16x16x32_bf16 v[44:47], v[170:173], v[178:181], v[44:47]
	s_cselect_b32 s55, s23, s47
	v_mfma_f32_16x16x32_bf16 v[36:39], v[162:165], v[186:189], v[36:39]
	s_cselect_b32 s54, s85, s46
	v_mfma_f32_16x16x32_bf16 v[28:31], v[170:173], v[186:189], v[28:31]
	s_cselect_b32 s47, s21, s90
	v_mfma_f32_16x16x32_bf16 v[20:23], v[162:165], v[198:201], v[20:23]
	s_cselect_b32 s46, s86, s87
	v_mfma_f32_16x16x32_bf16 v[12:15], v[170:173], v[198:201], v[12:15]
	s_add_i32 s4, 0, 0x14000
	v_mfma_f32_16x16x32_bf16 v[4:7], v[162:165], v[212:215], v[4:7]
	s_cmp_gt_u32 s91, 13
	v_mfma_f32_16x16x32_bf16 v[0:3], v[170:173], v[212:215], v[0:3]
	s_setprio 0
	s_barrier
.LBB0_287:
	v_add_u32_e32 v132, s92, v160
	v_add_u32_e32 v170, s4, v160
	ds_read_b128 v[120:123], v132
	ds_read_b128 v[124:127], v132 offset:1024
	ds_read_b128 v[128:131], v132 offset:2048
	ds_read_b128 v[132:135], v132 offset:3072
	ds_read_b128 v[154:157], v170
	ds_read_b128 v[162:165], v170 offset:1024
	ds_read_b128 v[166:169], v170 offset:2048
	ds_read_b128 v[170:173], v170 offset:3072
	v_lshl_add_u64 v[190:191], s[44:45], 0, v[150:151]
	s_add_i32 m0, s53, 0xc000
	ds_read_b128 v[174:177], v161
	ds_read_b128 v[178:181], v161 offset:1024
	ds_read_b128 v[182:185], v161 offset:2048
	ds_read_b128 v[186:189], v161 offset:3072
	ds_read_b128 v[194:197], v161 offset:4096
	ds_read_b128 v[198:201], v161 offset:5120
	ds_read_b128 v[202:205], v161 offset:6144
	ds_read_b128 v[212:215], v161 offset:7168
	global_load_lds_dwordx4 v[190:191], off
	v_lshl_add_u64 v[190:191], s[44:45], 0, v[152:153]
	s_add_i32 m0, s53, 0xe000
	s_nop 0
	global_load_lds_dwordx4 v[190:191], off
	s_waitcnt vmcnt(8)
	s_waitcnt lgkmcnt(0)
	s_barrier
; #define PG8_STAGE(bufoff, gbase, voff) do { _Pragma("unroll") for (int _i = 0; _i < 2; ++_i) \
;         __builtin_amdgcn_global_load_lds((const unsigned*)((const char*)(gbase) + (voff)[_i]), (LAS unsigned*)(lds + (bufoff) + ldsw + _i * 8192), 16, 0, 0); } while (0)
; #define PG8_LDA(dst, b, h) do { _Pragma("unroll") for (int m = 0; m < 4; ++m) _Pragma("unroll") for (int k = 0; k < 2; ++k) dst[m][k] = *(const LAS bf16x8*)(lds + PG8_SA(b, h) + aoff + m * 2048 + k * 1024); } while (0)
; #define PG8_MMA(ai, bj, At, Bt) do { __builtin_amdgcn_s_setprio(1); _Pragma("unroll") for (int m = 0; m < 4; ++m) _Pragma("unroll") for (int n = 0; n < 2; ++n) _Pragma("unroll") for (int k = 0; k < 2; ++k) \
;         acc[ai][bj][m][n] = __builtin_amdgcn_mfma_f32_16x16x32_bf16(Bt[n][k], At[m][k], acc[ai][bj][m][n], 0, 0, 0); __builtin_amdgcn_s_setprio(0); } while (0)
; #define PG8_WAIT_V(n) asm volatile("s_waitcnt vmcnt(" #n ")" ::: "memory")
; #define PG8_WAIT_L(n) asm volatile("s_waitcnt lgkmcnt(" #n ")" ::: "memory")
; #define PG8_BAR __builtin_amdgcn_s_barrier()
; #define PG8_SCHED __builtin_amdgcn_sched_barrier(0)
; template <class Epi, class Sched, bool ALIGN_EPI>
; __device__ __forceinline__ void gemm_phase(LAS unsigned char* lds, const Gemm g, const Sched& S, const Epi& E) {
;     ...
;             PG8_WAIT_V(8); PG8_WAIT_L(0); PG8_BAR; PG8_MMA(0, 0, At, B0); PG8_MMA(0, 1, At, B1); PG8_BAR; PG8_SCHED;
;             PG8_LDA(At, 0, 1); PG8_STAGE(PG8_SB(0, 0), b2, voffB); PG8_STAGE(PG8_SB(0, 1), b2 + hstepB, voffB); PG8_STAGE(PG8_SA(0, 0), a2, voffA);
;             PG8_WAIT_V(8); PG8_WAIT_L(0); PG8_BAR; PG8_MMA(1, 0, At, B0); PG8_MMA(1, 1, At, B1); PG8_BAR; PG8_SCHED;
	s_setprio 1
	s_waitcnt lgkmcnt(0)
	v_mfma_f32_16x16x32_bf16 v[140:143], v[120:123], v[174:177], v[140:143]
	v_mfma_f32_16x16x32_bf16 v[136:139], v[128:131], v[174:177], v[136:139]
	v_mfma_f32_16x16x32_bf16 v[108:111], v[120:123], v[182:185], v[108:111]
	v_mfma_f32_16x16x32_bf16 v[104:107], v[128:131], v[182:185], v[104:107]
	v_mfma_f32_16x16x32_bf16 v[92:95], v[120:123], v[194:197], v[92:95]
	v_mfma_f32_16x16x32_bf16 v[88:91], v[128:131], v[194:197], v[88:91]
	v_mfma_f32_16x16x32_bf16 v[76:79], v[120:123], v[202:205], v[76:79]
	v_mfma_f32_16x16x32_bf16 v[72:75], v[128:131], v[202:205], v[72:75]
	v_mfma_f32_16x16x32_bf16 v[140:143], v[124:127], v[178:181], v[140:143]
	v_mfma_f32_16x16x32_bf16 v[136:139], v[132:135], v[178:181], v[136:139]
	v_mfma_f32_16x16x32_bf16 v[108:111], v[124:127], v[186:189], v[108:111]
	v_mfma_f32_16x16x32_bf16 v[104:107], v[132:135], v[186:189], v[104:107]
	v_mfma_f32_16x16x32_bf16 v[92:95], v[124:127], v[198:201], v[92:95]
	v_mfma_f32_16x16x32_bf16 v[88:91], v[132:135], v[198:201], v[88:91]
	v_mfma_f32_16x16x32_bf16 v[76:79], v[124:127], v[212:215], v[76:79]
	v_mfma_f32_16x16x32_bf16 v[72:75], v[132:135], v[212:215], v[72:75]
	s_setprio 0
	s_setprio 1
	v_mfma_f32_16x16x32_bf16 v[116:119], v[154:157], v[174:177], v[116:119]
	v_mfma_f32_16x16x32_bf16 v[112:115], v[166:169], v[174:177], v[112:115]
	v_mfma_f32_16x16x32_bf16 v[100:103], v[154:157], v[182:185], v[100:103]
	v_mfma_f32_16x16x32_bf16 v[96:99], v[166:169], v[182:185], v[96:99]
	v_mfma_f32_16x16x32_bf16 v[84:87], v[154:157], v[194:197], v[84:87]
	v_mfma_f32_16x16x32_bf16 v[80:83], v[166:169], v[194:197], v[80:83]
	v_mfma_f32_16x16x32_bf16 v[68:71], v[154:157], v[202:205], v[68:71]
	v_mfma_f32_16x16x32_bf16 v[64:67], v[166:169], v[202:205], v[64:67]
	v_mfma_f32_16x16x32_bf16 v[116:119], v[162:165], v[178:181], v[116:119]
	v_mfma_f32_16x16x32_bf16 v[112:115], v[170:173], v[178:181], v[112:115]
	v_mfma_f32_16x16x32_bf16 v[100:103], v[162:165], v[186:189], v[100:103]
	v_mfma_f32_16x16x32_bf16 v[96:99], v[170:173], v[186:189], v[96:99]
	v_mfma_f32_16x16x32_bf16 v[84:87], v[162:165], v[198:201], v[84:87]
	v_mfma_f32_16x16x32_bf16 v[80:83], v[170:173], v[198:201], v[80:83]
	v_mfma_f32_16x16x32_bf16 v[68:71], v[162:165], v[212:215], v[68:71]
	v_mfma_f32_16x16x32_bf16 v[64:67], v[170:173], v[212:215], v[64:67]
	s_setprio 0
	s_barrier
	s_add_i32 s5, s92, s52
	v_lshl_add_u64 v[190:191], s[46:47], 0, v[192:193]
	s_mov_b32 m0, s5
	ds_read_b128 v[174:177], v161 offset:16384
	ds_read_b128 v[178:181], v161 offset:17408
	ds_read_b128 v[182:185], v161 offset:18432
	ds_read_b128 v[186:189], v161 offset:19456
	ds_read_b128 v[194:197], v161 offset:20480
	ds_read_b128 v[198:201], v161 offset:21504
	ds_read_b128 v[202:205], v161 offset:22528
	ds_read_b128 v[212:215], v161 offset:23552
	global_load_lds_dwordx4 v[190:191], off
	s_add_i32 m0, s5, 0x2000
	s_add_u32 vcc_lo, s46, 0x40000
	v_lshl_add_u64 v[216:217], s[46:47], 0, v[144:145]
	s_addc_u32 vcc_hi, s47, 0
	s_add_i32 s4, s4, s52
	global_load_lds_dwordx4 v[216:217], off
	v_lshl_add_u64 v[218:219], vcc, 0, v[192:193]
	s_mov_b32 m0, s4
	v_lshl_add_u64 v[220:221], s[54:55], 0, v[146:147]
	global_load_lds_dwordx4 v[218:219], off
	v_lshl_add_u64 v[218:219], vcc, 0, v[144:145]
	s_add_i32 m0, s4, 0x2000
	s_nop 0
	global_load_lds_dwordx4 v[218:219], off
	v_lshl_add_u64 v[218:219], s[54:55], 0, v[148:149]
	s_mov_b32 m0, s53
	s_nop 0
	global_load_lds_dwordx4 v[218:219], off
	s_mov_b32 m0, s56
	s_nop 0
	global_load_lds_dwordx4 v[220:221], off
	s_waitcnt vmcnt(8)
	s_waitcnt lgkmcnt(0)
	s_barrier
	s_setprio 1
	s_waitcnt lgkmcnt(0)
	v_mfma_f32_16x16x32_bf16 v[60:63], v[120:123], v[174:177], v[60:63]
	v_mfma_f32_16x16x32_bf16 v[56:59], v[128:131], v[174:177], v[56:59]
	v_mfma_f32_16x16x32_bf16 v[48:51], v[120:123], v[182:185], v[48:51]
	v_mfma_f32_16x16x32_bf16 v[40:43], v[128:131], v[182:185], v[40:43]
	v_mfma_f32_16x16x32_bf16 v[32:35], v[120:123], v[194:197], v[32:35]
	v_mfma_f32_16x16x32_bf16 v[24:27], v[128:131], v[194:197], v[24:27]
	v_mfma_f32_16x16x32_bf16 v[16:19], v[120:123], v[202:205], v[16:19]
	v_mfma_f32_16x16x32_bf16 v[8:11], v[128:131], v[202:205], v[8:11]
	v_mfma_f32_16x16x32_bf16 v[60:63], v[124:127], v[178:181], v[60:63]
	v_mfma_f32_16x16x32_bf16 v[56:59], v[132:135], v[178:181], v[56:59]
	v_mfma_f32_16x16x32_bf16 v[48:51], v[124:127], v[186:189], v[48:51]
	v_mfma_f32_16x16x32_bf16 v[40:43], v[132:135], v[186:189], v[40:43]
	v_mfma_f32_16x16x32_bf16 v[32:35], v[124:127], v[198:201], v[32:35]
	v_mfma_f32_16x16x32_bf16 v[24:27], v[132:135], v[198:201], v[24:27]
	v_mfma_f32_16x16x32_bf16 v[16:19], v[124:127], v[212:215], v[16:19]
	v_mfma_f32_16x16x32_bf16 v[8:11], v[132:135], v[212:215], v[8:11]
	s_setprio 0
	s_setprio 1
	v_mfma_f32_16x16x32_bf16 v[52:55], v[154:157], v[174:177], v[52:55]
	v_mfma_f32_16x16x32_bf16 v[44:47], v[166:169], v[174:177], v[44:47]
	v_mfma_f32_16x16x32_bf16 v[36:39], v[154:157], v[182:185], v[36:39]
	v_mfma_f32_16x16x32_bf16 v[28:31], v[166:169], v[182:185], v[28:31]
	v_mfma_f32_16x16x32_bf16 v[20:23], v[154:157], v[194:197], v[20:23]
	v_mfma_f32_16x16x32_bf16 v[12:15], v[166:169], v[194:197], v[12:15]
	v_mfma_f32_16x16x32_bf16 v[4:7], v[154:157], v[202:205], v[4:7]
	v_mfma_f32_16x16x32_bf16 v[0:3], v[166:169], v[202:205], v[0:3]
	v_mfma_f32_16x16x32_bf16 v[52:55], v[162:165], v[178:181], v[52:55]
	v_mfma_f32_16x16x32_bf16 v[44:47], v[170:173], v[178:181], v[44:47]
	v_mfma_f32_16x16x32_bf16 v[36:39], v[162:165], v[186:189], v[36:39]
	v_mfma_f32_16x16x32_bf16 v[28:31], v[170:173], v[186:189], v[28:31]
	v_mfma_f32_16x16x32_bf16 v[20:23], v[162:165], v[198:201], v[20:23]
	v_mfma_f32_16x16x32_bf16 v[12:15], v[170:173], v[198:201], v[12:15]
	v_mfma_f32_16x16x32_bf16 v[4:7], v[162:165], v[212:215], v[4:7]
	v_mfma_f32_16x16x32_bf16 v[0:3], v[170:173], v[212:215], v[0:3]
	s_setprio 0
	s_barrier
; #define PG8_STAGE(bufoff, gbase, voff) do { _Pragma("unroll") for (int _i = 0; _i < 2; ++_i) \
;         __builtin_amdgcn_global_load_lds((const unsigned*)((const char*)(gbase) + (voff)[_i]), (LAS unsigned*)(lds + (bufoff) + ldsw + _i * 8192), 16, 0, 0); } while (0)
; #define PG8_LDA(dst, b, h) do { _Pragma("unroll") for (int m = 0; m < 4; ++m) _Pragma("unroll") for (int k = 0; k < 2; ++k) dst[m][k] = *(const LAS bf16x8*)(lds + PG8_SA(b, h) + aoff + m * 2048 + k * 1024); } while (0)
; #define PG8_LDB(dst, b, h) do { _Pragma("unroll") for (int n = 0; n < 2; ++n) _Pragma("unroll") for (int k = 0; k < 2; ++k) dst[n][k] = *(const LAS bf16x8*)(lds + PG8_SB(b, h) + boff + n * 2048 + k * 1024); } while (0)
; #define PG8_MMA(ai, bj, At, Bt) do { __builtin_amdgcn_s_setprio(1); _Pragma("unroll") for (int m = 0; m < 4; ++m) _Pragma("unroll") for (int n = 0; n < 2; ++n) _Pragma("unroll") for (int k = 0; k < 2; ++k) \
;         acc[ai][bj][m][n] = __builtin_amdgcn_mfma_f32_16x16x32_bf16(Bt[n][k], At[m][k], acc[ai][bj][m][n], 0, 0, 0); __builtin_amdgcn_s_setprio(0); } while (0)
; #define PG8_WAIT_V(n) asm volatile("s_waitcnt vmcnt(" #n ")" ::: "memory")
; #define PG8_WAIT_L(n) asm volatile("s_waitcnt lgkmcnt(" #n ")" ::: "memory")
; #define PG8_BAR __builtin_amdgcn_s_barrier()
; #define PG8_SCHED __builtin_amdgcn_sched_barrier(0)
; template <class Epi, class Sched, bool ALIGN_EPI>
; __device__ __forceinline__ void gemm_phase(LAS unsigned char* lds, const Gemm g, const Sched& S, const Epi& E) {
;     ...
;             PG8_LDB(B0, 1, 0); PG8_LDB(B1, 1, 1); PG8_SCHED; PG8_LDA(At, 1, 0); PG8_STAGE(PG8_SA(0, 1), a2 + hstepA, voffA);
;             PG8_WAIT_V(8); PG8_WAIT_L(0); PG8_BAR; PG8_MMA(0, 0, At, B0); PG8_MMA(0, 1, At, B1); PG8_BAR; PG8_SCHED;
	s_add_i32 s4, 0, 0x18000
	s_add_i32 s5, 0, 0x1c000
	v_add_u32_e32 v132, s4, v160
	v_add_u32_e32 v170, s5, v160
	ds_read_b128 v[120:123], v132
	ds_read_b128 v[124:127], v132 offset:1024
	ds_read_b128 v[128:131], v132 offset:2048
	ds_read_b128 v[132:135], v132 offset:3072
	ds_read_b128 v[154:157], v170
	ds_read_b128 v[162:165], v170 offset:1024
	ds_read_b128 v[166:169], v170 offset:2048
	ds_read_b128 v[170:173], v170 offset:3072
	s_add_u32 s54, s54, 0x40000
	s_addc_u32 s55, s55, 0
	s_mov_b32 m0, s57
	v_lshl_add_u64 v[222:223], s[54:55], 0, v[148:149]
	ds_read_b128 v[174:177], v161 offset:32768
	ds_read_b128 v[178:181], v161 offset:33792
	ds_read_b128 v[182:185], v161 offset:34816
	ds_read_b128 v[186:189], v161 offset:35840
	ds_read_b128 v[194:197], v161 offset:36864
	ds_read_b128 v[198:201], v161 offset:37888
	ds_read_b128 v[202:205], v161 offset:38912
	ds_read_b128 v[212:215], v161 offset:39936
	global_load_lds_dwordx4 v[222:223], off
	v_lshl_add_u64 v[222:223], s[54:55], 0, v[146:147]
	s_mov_b32 m0, s58
	s_nop 0
	global_load_lds_dwordx4 v[222:223], off
	s_waitcnt vmcnt(8)
	s_waitcnt lgkmcnt(0)
	s_barrier
	s_setprio 1
	s_waitcnt lgkmcnt(0)
	v_mfma_f32_16x16x32_bf16 v[140:143], v[120:123], v[174:177], v[140:143]
	v_mfma_f32_16x16x32_bf16 v[136:139], v[128:131], v[174:177], v[136:139]
	v_mfma_f32_16x16x32_bf16 v[108:111], v[120:123], v[182:185], v[108:111]
	v_mfma_f32_16x16x32_bf16 v[104:107], v[128:131], v[182:185], v[104:107]
	v_mfma_f32_16x16x32_bf16 v[92:95], v[120:123], v[194:197], v[92:95]
	v_mfma_f32_16x16x32_bf16 v[88:91], v[128:131], v[194:197], v[88:91]
	v_mfma_f32_16x16x32_bf16 v[76:79], v[120:123], v[202:205], v[76:79]
	v_mfma_f32_16x16x32_bf16 v[72:75], v[128:131], v[202:205], v[72:75]
	v_mfma_f32_16x16x32_bf16 v[140:143], v[124:127], v[178:181], v[140:143]
	v_mfma_f32_16x16x32_bf16 v[136:139], v[132:135], v[178:181], v[136:139]
	v_mfma_f32_16x16x32_bf16 v[108:111], v[124:127], v[186:189], v[108:111]
	v_mfma_f32_16x16x32_bf16 v[104:107], v[132:135], v[186:189], v[104:107]
	v_mfma_f32_16x16x32_bf16 v[92:95], v[124:127], v[198:201], v[92:95]
	v_mfma_f32_16x16x32_bf16 v[88:91], v[132:135], v[198:201], v[88:91]
	v_mfma_f32_16x16x32_bf16 v[76:79], v[124:127], v[212:215], v[76:79]
	v_mfma_f32_16x16x32_bf16 v[72:75], v[132:135], v[212:215], v[72:75]
	s_setprio 0
	s_setprio 1
	v_mfma_f32_16x16x32_bf16 v[116:119], v[154:157], v[174:177], v[116:119]
	v_mfma_f32_16x16x32_bf16 v[112:115], v[166:169], v[174:177], v[112:115]
	v_mfma_f32_16x16x32_bf16 v[100:103], v[154:157], v[182:185], v[100:103]
	v_mfma_f32_16x16x32_bf16 v[96:99], v[166:169], v[182:185], v[96:99]
	v_mfma_f32_16x16x32_bf16 v[84:87], v[154:157], v[194:197], v[84:87]
	v_mfma_f32_16x16x32_bf16 v[80:83], v[166:169], v[194:197], v[80:83]
	v_mfma_f32_16x16x32_bf16 v[68:71], v[154:157], v[202:205], v[68:71]
	v_mfma_f32_16x16x32_bf16 v[64:67], v[166:169], v[202:205], v[64:67]
	v_mfma_f32_16x16x32_bf16 v[116:119], v[162:165], v[178:181], v[116:119]
	v_mfma_f32_16x16x32_bf16 v[112:115], v[170:173], v[178:181], v[112:115]
	v_mfma_f32_16x16x32_bf16 v[100:103], v[162:165], v[186:189], v[100:103]
	v_mfma_f32_16x16x32_bf16 v[96:99], v[170:173], v[186:189], v[96:99]
	v_mfma_f32_16x16x32_bf16 v[84:87], v[162:165], v[198:201], v[84:87]
	v_mfma_f32_16x16x32_bf16 v[80:83], v[170:173], v[198:201], v[80:83]
	v_mfma_f32_16x16x32_bf16 v[68:71], v[162:165], v[212:215], v[68:71]
	v_mfma_f32_16x16x32_bf16 v[64:67], v[170:173], v[212:215], v[64:67]
	s_setprio 0
	s_barrier
; #define PG8_STAGE(bufoff, gbase, voff) do { _Pragma("unroll") for (int _i = 0; _i < 2; ++_i) \
;         __builtin_amdgcn_global_load_lds((const unsigned*)((const char*)(gbase) + (voff)[_i]), (LAS unsigned*)(lds + (bufoff) + ldsw + _i * 8192), 16, 0, 0); } while (0)
; #define PG8_LDA(dst, b, h) do { _Pragma("unroll") for (int m = 0; m < 4; ++m) _Pragma("unroll") for (int k = 0; k < 2; ++k) dst[m][k] = *(const LAS bf16x8*)(lds + PG8_SA(b, h) + aoff + m * 2048 + k * 1024); } while (0)
; #define PG8_LDB(dst, b, h) do { _Pragma("unroll") for (int n = 0; n < 2; ++n) _Pragma("unroll") for (int k = 0; k < 2; ++k) dst[n][k] = *(const LAS bf16x8*)(lds + PG8_SB(b, h) + boff + n * 2048 + k * 1024); } while (0)
; #define PG8_MMA(ai, bj, At, Bt) do { __builtin_amdgcn_s_setprio(1); _Pragma("unroll") for (int m = 0; m < 4; ++m) _Pragma("unroll") for (int n = 0; n < 2; ++n) _Pragma("unroll") for (int k = 0; k < 2; ++k) \
;         acc[ai][bj][m][n] = __builtin_amdgcn_mfma_f32_16x16x32_bf16(Bt[n][k], At[m][k], acc[ai][bj][m][n], 0, 0, 0); __builtin_amdgcn_s_setprio(0); } while (0)
; #define PG8_WAIT_V(n) asm volatile("s_waitcnt vmcnt(" #n ")" ::: "memory")
; #define PG8_WAIT_L(n) asm volatile("s_waitcnt lgkmcnt(" #n ")" ::: "memory")
; #define PG8_BAR __builtin_amdgcn_s_barrier()
; #define PG8_SCHED __builtin_amdgcn_sched_barrier(0)
; template <class Epi, class Sched, bool ALIGN_EPI>
; __device__ __forceinline__ void gemm_phase(LAS unsigned char* lds, const Gemm g, const Sched& S, const Epi& E) {
;     ...
;         for (int t = 0; t < nt; t += 2) {
;             const bool last = (t == nt - 2);
;             const char* a1 = cA + (size_t)(t + 1) * kstep;
;             const char* a2 = last ? nA : cA + (size_t)(t + 2) * kstep; const char* b2 = last ? nB : cB + (size_t)(t + 2) * kstep;
;             const char* a3 = a2 + kstep; const char* b3 = b2 + kstep;
;             PG8_LDB(B0, 0, 0); PG8_LDB(B1, 0, 1); PG8_SCHED; PG8_LDA(At, 0, 0); PG8_STAGE(PG8_SA(1, 1), a1 + hstepA, voffA);
;     ...
;             PG8_LDA(At, 1, 1); PG8_STAGE(PG8_SB(1, 0), b3, voffB); PG8_STAGE(PG8_SB(1, 1), b3 + hstepB, voffB); PG8_STAGE(PG8_SA(1, 0), a3, voffA);
;             PG8_WAIT_V(8); PG8_WAIT_L(0); PG8_BAR; PG8_MMA(1, 0, At, B0); PG8_MMA(1, 1, At, B1); PG8_BAR; PG8_SCHED;
	s_add_i32 s4, s4, s52
	v_lshl_add_u64 v[190:191], v[190:191], 0, s[12:13]
	s_mov_b32 m0, s4
	ds_read_b128 v[174:177], v161 offset:49152
	ds_read_b128 v[178:181], v161 offset:50176
	ds_read_b128 v[182:185], v161 offset:51200
	ds_read_b128 v[186:189], v161 offset:52224
	ds_read_b128 v[194:197], v161 offset:53248
	ds_read_b128 v[198:201], v161 offset:54272
	ds_read_b128 v[202:205], v161 offset:55296
	ds_read_b128 v[212:215], v161 offset:56320
	global_load_lds_dwordx4 v[190:191], off
	s_add_i32 m0, s4, 0x2000
	s_add_u32 s46, s46, 0x40080
	v_lshl_add_u64 v[190:191], v[216:217], 0, s[12:13]
	s_addc_u32 s47, s47, 0
	s_add_i32 s4, s5, s52
	global_load_lds_dwordx4 v[190:191], off
	v_lshl_add_u64 v[190:191], s[46:47], 0, v[192:193]
	s_mov_b32 m0, s4
	s_nop 0
	global_load_lds_dwordx4 v[190:191], off
	v_lshl_add_u64 v[190:191], s[46:47], 0, v[144:145]
	s_add_i32 m0, s4, 0x2000
	s_nop 0
	global_load_lds_dwordx4 v[190:191], off
	v_lshl_add_u64 v[190:191], v[218:219], 0, s[12:13]
	s_mov_b32 m0, s65
	s_nop 0
	global_load_lds_dwordx4 v[190:191], off
	v_lshl_add_u64 v[190:191], v[220:221], 0, s[12:13]
	s_mov_b32 m0, s66
	s_nop 0
	global_load_lds_dwordx4 v[190:191], off
	s_waitcnt vmcnt(8)
	s_waitcnt lgkmcnt(0)
	s_barrier
	s_setprio 1
	s_waitcnt lgkmcnt(0)
	v_mfma_f32_16x16x32_bf16 v[60:63], v[120:123], v[174:177], v[60:63]
	v_mfma_f32_16x16x32_bf16 v[56:59], v[128:131], v[174:177], v[56:59]
	v_mfma_f32_16x16x32_bf16 v[48:51], v[120:123], v[182:185], v[48:51]
	v_mfma_f32_16x16x32_bf16 v[40:43], v[128:131], v[182:185], v[40:43]
	v_mfma_f32_16x16x32_bf16 v[32:35], v[120:123], v[194:197], v[32:35]
	v_mfma_f32_16x16x32_bf16 v[24:27], v[128:131], v[194:197], v[24:27]
	v_mfma_f32_16x16x32_bf16 v[16:19], v[120:123], v[202:205], v[16:19]
	v_mfma_f32_16x16x32_bf16 v[8:11], v[128:131], v[202:205], v[8:11]
	v_mfma_f32_16x16x32_bf16 v[60:63], v[124:127], v[178:181], v[60:63]
	v_mfma_f32_16x16x32_bf16 v[56:59], v[132:135], v[178:181], v[56:59]
	v_mfma_f32_16x16x32_bf16 v[48:51], v[124:127], v[186:189], v[48:51]
	v_mfma_f32_16x16x32_bf16 v[40:43], v[132:135], v[186:189], v[40:43]
	v_mfma_f32_16x16x32_bf16 v[32:35], v[124:127], v[198:201], v[32:35]
	v_mfma_f32_16x16x32_bf16 v[24:27], v[132:135], v[198:201], v[24:27]
	v_mfma_f32_16x16x32_bf16 v[16:19], v[124:127], v[212:215], v[16:19]
	v_mfma_f32_16x16x32_bf16 v[8:11], v[132:135], v[212:215], v[8:11]
	s_setprio 0
	s_setprio 1
	v_mfma_f32_16x16x32_bf16 v[52:55], v[154:157], v[174:177], v[52:55]
	s_add_i32 s91, s91, 2
	v_mfma_f32_16x16x32_bf16 v[44:47], v[166:169], v[174:177], v[44:47]
	s_add_u32 s44, s44, 0x100
	v_mfma_f32_16x16x32_bf16 v[36:39], v[154:157], v[182:185], v[36:39]
	s_addc_u32 s45, s45, 0
	v_mfma_f32_16x16x32_bf16 v[28:31], v[166:169], v[182:185], v[28:31]
	s_add_u32 s87, s87, 0x100
	v_mfma_f32_16x16x32_bf16 v[20:23], v[154:157], v[194:197], v[20:23]
	s_addc_u32 s90, s90, 0
	v_mfma_f32_16x16x32_bf16 v[12:15], v[166:169], v[194:197], v[12:15]
	s_add_u32 s46, s44, 0xfffc0080
	v_mfma_f32_16x16x32_bf16 v[4:7], v[154:157], v[202:205], v[4:7]
	s_addc_u32 s47, s45, -1
	v_mfma_f32_16x16x32_bf16 v[0:3], v[166:169], v[202:205], v[0:3]
	s_add_i32 s92, 0, 0x10000
	v_mfma_f32_16x16x32_bf16 v[52:55], v[162:165], v[178:181], v[52:55]
	s_cmp_eq_u32 s91, 12
	v_mfma_f32_16x16x32_bf16 v[44:47], v[170:173], v[178:181], v[44:47]
	s_cselect_b32 s55, s23, s47
	v_mfma_f32_16x16x32_bf16 v[36:39], v[162:165], v[186:189], v[36:39]
	s_cselect_b32 s54, s85, s46
	v_mfma_f32_16x16x32_bf16 v[28:31], v[170:173], v[186:189], v[28:31]
	s_cselect_b32 s47, s21, s90
	v_mfma_f32_16x16x32_bf16 v[20:23], v[162:165], v[198:201], v[20:23]
	s_cselect_b32 s46, s86, s87
	v_mfma_f32_16x16x32_bf16 v[12:15], v[170:173], v[198:201], v[12:15]
	s_add_i32 s4, 0, 0x14000
	v_mfma_f32_16x16x32_bf16 v[4:7], v[162:165], v[212:215], v[4:7]
	s_cmp_gt_u32 s91, 13
	v_mfma_f32_16x16x32_bf16 v[0:3], v[170:173], v[212:215], v[0:3]
	s_setprio 0
	s_barrier
	s_cbranch_scc0 .LBB0_287
	s_and_b64 vcc, exec, s[16:17]
	s_cbranch_vccz .LBB0_290
	s_barrier

; #define PG8_STAGE(bufoff, gbase, voff) do { _Pragma("unroll") for (int _i = 0; _i < 2; ++_i) \
;         __builtin_amdgcn_global_load_lds((const unsigned*)((const char*)(gbase) + (voff)[_i]), (LAS unsigned*)(lds + (bufoff) + ldsw + _i * 8192), 16, 0, 0); } while (0)
; #define PG8_LDA(dst, b, h) do { _Pragma("unroll") for (int m = 0; m < 4; ++m) _Pragma("unroll") for (int k = 0; k < 2; ++k) dst[m][k] = *(const LAS bf16x8*)(lds + PG8_SA(b, h) + aoff + m * 2048 + k * 1024); } while (0)
; #define PG8_LDB(dst, b, h) do { _Pragma("unroll") for (int n = 0; n < 2; ++n) _Pragma("unroll") for (int k = 0; k < 2; ++k) dst[n][k] = *(const LAS bf16x8*)(lds + PG8_SB(b, h) + boff + n * 2048 + k * 1024); } while (0)
; #define PG8_MMA(ai, bj, At, Bt) do { __builtin_amdgcn_s_setprio(1); _Pragma("unroll") for (int m = 0; m < 4; ++m) _Pragma("unroll") for (int n = 0; n < 2; ++n) _Pragma("unroll") for (int k = 0; k < 2; ++k) \
;         acc[ai][bj][m][n] = __builtin_amdgcn_mfma_f32_16x16x32_bf16(Bt[n][k], At[m][k], acc[ai][bj][m][n], 0, 0, 0); __builtin_amdgcn_s_setprio(0); } while (0)
; #define PG8_WAIT_V(n) asm volatile("s_waitcnt vmcnt(" #n ")" ::: "memory")
; #define PG8_WAIT_L(n) asm volatile("s_waitcnt lgkmcnt(" #n ")" ::: "memory")
; template <class Epi, class Sched, bool ALIGN_EPI>
; __device__ __forceinline__ void gemm_phase(LAS unsigned char* lds, const Gemm g, const Sched& S, const Epi& E) {
;     ...
;         const bool has_next = S.next(ui + 1, nxt);
;         const char* nA = has_next ? (const char*)g.A + (size_t)nxt.pm * tstepA : cA; const char* nB = has_next ? (const char*)g.Bt + (size_t)nxt.pn * tstepB : cB;
;         for (int t = 0; t < nt; t += 2) {
;             const bool last = (t == nt - 2);
;             const char* a1 = cA + (size_t)(t + 1) * kstep;
;             const char* a2 = last ? nA : cA + (size_t)(t + 2) * kstep; const char* b2 = last ? nB : cB + (size_t)(t + 2) * kstep;
;             const char* a3 = a2 + kstep; const char* b3 = b2 + kstep;
;             PG8_LDB(B0, 0, 0); PG8_LDB(B1, 0, 1); PG8_SCHED; PG8_LDA(At, 0, 0); PG8_STAGE(PG8_SA(1, 1), a1 + hstepA, voffA);
;             PG8_WAIT_V(8); PG8_WAIT_L(0); PG8_BAR; PG8_MMA(0, 0, At, B0); PG8_MMA(0, 1, At, B1); PG8_BAR; PG8_SCHED;
;             PG8_LDA(At, 0, 1); PG8_STAGE(PG8_SB(0, 0), b2, voffB); PG8_STAGE(PG8_SB(0, 1), b2 + hstepB, voffB); PG8_STAGE(PG8_SA(0, 0), a2, voffA);
.LBB0_452:
	s_ashr_i32 s81, s80, 31
	s_lshl_b64 s[6:7], s[80:81], 19
	v_readlane_b32 s17, v255, 36
	s_add_u32 s6, s17, s6
	s_addc_u32 s7, s33, s7
	s_and_b64 s[48:49], s[42:43], exec
	s_cselect_b32 s54, s7, s47
	s_cselect_b32 s55, s6, s46
	s_ashr_i32 s17, s16, 31
	s_lshl_b64 s[48:49], s[16:17], 19
	v_readlane_b32 s17, v255, 46
	s_add_u32 s62, s17, s48
	v_readlane_b32 s17, v255, 48
	s_addc_u32 s63, s17, s49
	s_and_b64 s[48:49], s[42:43], exec
	s_cselect_b32 s17, s63, s9
	s_cselect_b32 s56, s62, s8
	s_add_u32 s46, s46, 0x40080
	s_addc_u32 s47, s47, 0
	s_add_u32 s57, s8, 0x100
	s_addc_u32 s64, s9, 0
	s_mov_b32 s65, -2
	s_add_u32 s8, s46, 0xfffc0080
	s_addc_u32 s9, s47, -1
	s_add_i32 s66, 0, 0x10000
	s_cmp_eq_u32 s65, 12
	s_cselect_b32 s49, s54, s9
	s_cselect_b32 s48, s55, s8
	s_cselect_b32 s9, s17, s64
	s_cselect_b32 s8, s56, s57
	s_add_i32 s76, 0, 0x14000
	v_add_u32_e32 v52, s66, v178
	v_add_u32_e32 v168, s76, v178
	ds_read_b128 v[40:43], v52
	ds_read_b128 v[44:47], v52 offset:1024
	ds_read_b128 v[48:51], v52 offset:2048
	ds_read_b128 v[52:55], v52 offset:3072
	ds_read_b128 v[156:159], v168
	ds_read_b128 v[160:163], v168 offset:1024
	ds_read_b128 v[164:167], v168 offset:2048
	ds_read_b128 v[168:171], v168 offset:3072
	v_lshl_add_u64 v[194:195], s[46:47], 0, v[152:153]
	s_add_i32 m0, s50, 0xc000
	ds_read_b128 v[172:175], v179
	ds_read_b128 v[180:183], v179 offset:1024
	ds_read_b128 v[184:187], v179 offset:2048
	ds_read_b128 v[188:191], v179 offset:3072
	ds_read_b128 v[212:215], v179 offset:4096
	ds_read_b128 v[216:219], v179 offset:5120
	ds_read_b128 v[220:223], v179 offset:6144
	ds_read_b128 v[224:227], v179 offset:7168
	global_load_lds_dwordx4 v[194:195], off
	v_lshl_add_u64 v[194:195], s[46:47], 0, v[154:155]
	s_add_i32 m0, s50, 0xe000
	s_nop 0
	global_load_lds_dwordx4 v[194:195], off
	s_waitcnt vmcnt(8)
	s_waitcnt lgkmcnt(0)
	s_barrier
	s_setprio 1
	s_waitcnt lgkmcnt(0)
	v_mfma_f32_16x16x32_bf16 v[140:143], v[40:43], v[172:175], 0
	v_mfma_f32_16x16x32_bf16 v[136:139], v[48:51], v[172:175], 0
	v_mfma_f32_16x16x32_bf16 v[124:127], v[40:43], v[184:187], 0
	v_mfma_f32_16x16x32_bf16 v[120:123], v[48:51], v[184:187], 0
	v_mfma_f32_16x16x32_bf16 v[108:111], v[40:43], v[212:215], 0
	v_mfma_f32_16x16x32_bf16 v[104:107], v[48:51], v[212:215], 0
	v_mfma_f32_16x16x32_bf16 v[92:95], v[40:43], v[220:223], 0
	v_mfma_f32_16x16x32_bf16 v[88:91], v[48:51], v[220:223], 0
	v_mfma_f32_16x16x32_bf16 v[140:143], v[44:47], v[180:183], v[140:143]
	v_mfma_f32_16x16x32_bf16 v[136:139], v[52:55], v[180:183], v[136:139]
	v_mfma_f32_16x16x32_bf16 v[124:127], v[44:47], v[188:191], v[124:127]
	v_mfma_f32_16x16x32_bf16 v[120:123], v[52:55], v[188:191], v[120:123]
	v_mfma_f32_16x16x32_bf16 v[108:111], v[44:47], v[216:219], v[108:111]
	v_mfma_f32_16x16x32_bf16 v[104:107], v[52:55], v[216:219], v[104:107]
	v_mfma_f32_16x16x32_bf16 v[92:95], v[44:47], v[224:227], v[92:95]
	v_mfma_f32_16x16x32_bf16 v[88:91], v[52:55], v[224:227], v[88:91]
	s_setprio 0
	s_setprio 1
	v_mfma_f32_16x16x32_bf16 v[132:135], v[156:159], v[172:175], 0
	v_mfma_f32_16x16x32_bf16 v[128:131], v[164:167], v[172:175], 0
	v_mfma_f32_16x16x32_bf16 v[116:119], v[156:159], v[184:187], 0
	v_mfma_f32_16x16x32_bf16 v[112:115], v[164:167], v[184:187], 0
	v_mfma_f32_16x16x32_bf16 v[100:103], v[156:159], v[212:215], 0
	v_mfma_f32_16x16x32_bf16 v[96:99], v[164:167], v[212:215], 0
	v_mfma_f32_16x16x32_bf16 v[84:87], v[156:159], v[220:223], 0
	v_mfma_f32_16x16x32_bf16 v[80:83], v[164:167], v[220:223], 0
	v_mfma_f32_16x16x32_bf16 v[132:135], v[160:163], v[180:183], v[132:135]
	v_mfma_f32_16x16x32_bf16 v[128:131], v[168:171], v[180:183], v[128:131]
	v_mfma_f32_16x16x32_bf16 v[116:119], v[160:163], v[188:191], v[116:119]
	v_mfma_f32_16x16x32_bf16 v[112:115], v[168:171], v[188:191], v[112:115]
	v_mfma_f32_16x16x32_bf16 v[100:103], v[160:163], v[216:219], v[100:103]
	v_mfma_f32_16x16x32_bf16 v[96:99], v[168:171], v[216:219], v[96:99]
	v_mfma_f32_16x16x32_bf16 v[84:87], v[160:163], v[224:227], v[84:87]
	v_mfma_f32_16x16x32_bf16 v[80:83], v[168:171], v[224:227], v[80:83]
	s_setprio 0
	s_barrier
	s_add_i32 s66, s66, s53
	v_lshl_add_u64 v[194:195], s[8:9], 0, v[148:149]
	s_mov_b32 m0, s66
	ds_read_b128 v[172:175], v179 offset:16384
	ds_read_b128 v[180:183], v179 offset:17408
	ds_read_b128 v[184:187], v179 offset:18432
	ds_read_b128 v[188:191], v179 offset:19456
	ds_read_b128 v[212:215], v179 offset:20480
	ds_read_b128 v[216:219], v179 offset:21504
	ds_read_b128 v[220:223], v179 offset:22528
	ds_read_b128 v[224:227], v179 offset:23552
	global_load_lds_dwordx4 v[194:195], off
	s_add_i32 m0, s66, 0x2000
	s_add_u32 s66, s8, 0x40000
	v_lshl_add_u64 v[196:197], s[8:9], 0, v[144:145]
	s_addc_u32 s67, s9, 0
	s_add_i32 s76, s76, s53
	global_load_lds_dwordx4 v[196:197], off
	v_lshl_add_u64 v[198:199], s[66:67], 0, v[148:149]
	s_mov_b32 m0, s76
	v_lshl_add_u64 v[200:201], s[48:49], 0, v[146:147]
	global_load_lds_dwordx4 v[198:199], off
	v_lshl_add_u64 v[198:199], s[66:67], 0, v[144:145]
	s_add_i32 m0, s76, 0x2000
	s_nop 0
	global_load_lds_dwordx4 v[198:199], off
	v_lshl_add_u64 v[198:199], s[48:49], 0, v[150:151]
	s_mov_b32 m0, s50
	s_nop 0
	global_load_lds_dwordx4 v[198:199], off
	s_mov_b32 m0, s51
	s_nop 0
	global_load_lds_dwordx4 v[200:201], off
	s_waitcnt vmcnt(8)
	s_waitcnt lgkmcnt(0)
	s_barrier
; #define PG8_STAGE(bufoff, gbase, voff) do { _Pragma("unroll") for (int _i = 0; _i < 2; ++_i) \
;         __builtin_amdgcn_global_load_lds((const unsigned*)((const char*)(gbase) + (voff)[_i]), (LAS unsigned*)(lds + (bufoff) + ldsw + _i * 8192), 16, 0, 0); } while (0)
; #define PG8_LDA(dst, b, h) do { _Pragma("unroll") for (int m = 0; m < 4; ++m) _Pragma("unroll") for (int k = 0; k < 2; ++k) dst[m][k] = *(const LAS bf16x8*)(lds + PG8_SA(b, h) + aoff + m * 2048 + k * 1024); } while (0)
; #define PG8_LDB(dst, b, h) do { _Pragma("unroll") for (int n = 0; n < 2; ++n) _Pragma("unroll") for (int k = 0; k < 2; ++k) dst[n][k] = *(const LAS bf16x8*)(lds + PG8_SB(b, h) + boff + n * 2048 + k * 1024); } while (0)
; #define PG8_MMA(ai, bj, At, Bt) do { __builtin_amdgcn_s_setprio(1); _Pragma("unroll") for (int m = 0; m < 4; ++m) _Pragma("unroll") for (int n = 0; n < 2; ++n) _Pragma("unroll") for (int k = 0; k < 2; ++k) \
;         acc[ai][bj][m][n] = __builtin_amdgcn_mfma_f32_16x16x32_bf16(Bt[n][k], At[m][k], acc[ai][bj][m][n], 0, 0, 0); __builtin_amdgcn_s_setprio(0); } while (0)
; #define PG8_WAIT_V(n) asm volatile("s_waitcnt vmcnt(" #n ")" ::: "memory")
; #define PG8_WAIT_L(n) asm volatile("s_waitcnt lgkmcnt(" #n ")" ::: "memory")
; #define PG8_BAR __builtin_amdgcn_s_barrier()
; #define PG8_SCHED __builtin_amdgcn_sched_barrier(0)
; template <class Epi, class Sched, bool ALIGN_EPI>
; __device__ __forceinline__ void gemm_phase(LAS unsigned char* lds, const Gemm g, const Sched& S, const Epi& E) {
;     ...
;             PG8_WAIT_V(8); PG8_WAIT_L(0); PG8_BAR; PG8_MMA(1, 0, At, B0); PG8_MMA(1, 1, At, B1); PG8_BAR; PG8_SCHED;
;             PG8_LDB(B0, 1, 0); PG8_LDB(B1, 1, 1); PG8_SCHED; PG8_LDA(At, 1, 0); PG8_STAGE(PG8_SA(0, 1), a2 + hstepA, voffA);
;             PG8_WAIT_V(8); PG8_WAIT_L(0); PG8_BAR; PG8_MMA(0, 0, At, B0); PG8_MMA(0, 1, At, B1); PG8_BAR; PG8_SCHED;
	s_setprio 1
	s_waitcnt lgkmcnt(0)
	v_mfma_f32_16x16x32_bf16 v[76:79], v[40:43], v[172:175], 0
	v_mfma_f32_16x16x32_bf16 v[72:75], v[48:51], v[172:175], 0
	v_mfma_f32_16x16x32_bf16 v[60:63], v[40:43], v[184:187], 0
	v_mfma_f32_16x16x32_bf16 v[56:59], v[48:51], v[184:187], 0
	v_mfma_f32_16x16x32_bf16 v[28:31], v[40:43], v[212:215], 0
	v_mfma_f32_16x16x32_bf16 v[24:27], v[48:51], v[212:215], 0
	v_mfma_f32_16x16x32_bf16 v[12:15], v[40:43], v[220:223], 0
	v_mfma_f32_16x16x32_bf16 v[8:11], v[48:51], v[220:223], 0
	v_mfma_f32_16x16x32_bf16 v[76:79], v[44:47], v[180:183], v[76:79]
	v_mfma_f32_16x16x32_bf16 v[72:75], v[52:55], v[180:183], v[72:75]
	v_mfma_f32_16x16x32_bf16 v[60:63], v[44:47], v[188:191], v[60:63]
	v_mfma_f32_16x16x32_bf16 v[56:59], v[52:55], v[188:191], v[56:59]
	v_mfma_f32_16x16x32_bf16 v[28:31], v[44:47], v[216:219], v[28:31]
	v_mfma_f32_16x16x32_bf16 v[24:27], v[52:55], v[216:219], v[24:27]
	v_mfma_f32_16x16x32_bf16 v[12:15], v[44:47], v[224:227], v[12:15]
	v_mfma_f32_16x16x32_bf16 v[8:11], v[52:55], v[224:227], v[8:11]
	s_setprio 0
	s_setprio 1
	v_mfma_f32_16x16x32_bf16 v[36:39], v[156:159], v[184:187], 0
	v_mfma_f32_16x16x32_bf16 v[32:35], v[164:167], v[184:187], 0
	v_mfma_f32_16x16x32_bf16 v[20:23], v[156:159], v[212:215], 0
	v_mfma_f32_16x16x32_bf16 v[16:19], v[164:167], v[212:215], 0
	v_mfma_f32_16x16x32_bf16 v[4:7], v[156:159], v[220:223], 0
	v_mfma_f32_16x16x32_bf16 v[0:3], v[164:167], v[220:223], 0
	v_mfma_f32_16x16x32_bf16 v[40:43], v[156:159], v[172:175], 0
	v_mfma_f32_16x16x32_bf16 v[44:47], v[164:167], v[172:175], 0
	v_mfma_f32_16x16x32_bf16 v[36:39], v[160:163], v[188:191], v[36:39]
	v_mfma_f32_16x16x32_bf16 v[32:35], v[168:171], v[188:191], v[32:35]
	v_mfma_f32_16x16x32_bf16 v[20:23], v[160:163], v[216:219], v[20:23]
	v_mfma_f32_16x16x32_bf16 v[16:19], v[168:171], v[216:219], v[16:19]
	v_mfma_f32_16x16x32_bf16 v[4:7], v[160:163], v[224:227], v[4:7]
	v_mfma_f32_16x16x32_bf16 v[0:3], v[168:171], v[224:227], v[0:3]
	v_mfma_f32_16x16x32_bf16 v[40:43], v[160:163], v[180:183], v[40:43]
	v_mfma_f32_16x16x32_bf16 v[44:47], v[168:171], v[180:183], v[44:47]
	s_setprio 0
	s_barrier
	s_add_i32 s66, 0, 0x18000
	s_add_i32 s67, 0, 0x1c000
	v_add_u32_e32 v68, s66, v178
	v_add_u32_e32 v168, s67, v178
	ds_read_b128 v[48:51], v68
	ds_read_b128 v[52:55], v68 offset:1024
	ds_read_b128 v[64:67], v68 offset:2048
	ds_read_b128 v[68:71], v68 offset:3072
	ds_read_b128 v[156:159], v168
	ds_read_b128 v[160:163], v168 offset:1024
	ds_read_b128 v[164:167], v168 offset:2048
	ds_read_b128 v[168:171], v168 offset:3072
	s_add_u32 s48, s48, 0x40000
	s_addc_u32 s49, s49, 0
	s_mov_b32 m0, s22
	v_lshl_add_u64 v[202:203], s[48:49], 0, v[150:151]
	ds_read_b128 v[172:175], v179 offset:32768
	ds_read_b128 v[180:183], v179 offset:33792
	ds_read_b128 v[184:187], v179 offset:34816
	ds_read_b128 v[188:191], v179 offset:35840
	ds_read_b128 v[212:215], v179 offset:36864
	ds_read_b128 v[216:219], v179 offset:37888
	ds_read_b128 v[220:223], v179 offset:38912
	ds_read_b128 v[224:227], v179 offset:39936
	global_load_lds_dwordx4 v[202:203], off
	v_lshl_add_u64 v[202:203], s[48:49], 0, v[146:147]
	s_mov_b32 m0, s23
	s_nop 0
	global_load_lds_dwordx4 v[202:203], off
	s_waitcnt vmcnt(8)
	s_waitcnt lgkmcnt(0)
	s_barrier
	s_setprio 1
	s_waitcnt lgkmcnt(0)
	v_mfma_f32_16x16x32_bf16 v[140:143], v[48:51], v[172:175], v[140:143]
	v_mfma_f32_16x16x32_bf16 v[136:139], v[64:67], v[172:175], v[136:139]
	v_mfma_f32_16x16x32_bf16 v[124:127], v[48:51], v[184:187], v[124:127]
	v_mfma_f32_16x16x32_bf16 v[120:123], v[64:67], v[184:187], v[120:123]
	v_mfma_f32_16x16x32_bf16 v[108:111], v[48:51], v[212:215], v[108:111]
	v_mfma_f32_16x16x32_bf16 v[104:107], v[64:67], v[212:215], v[104:107]
	v_mfma_f32_16x16x32_bf16 v[92:95], v[48:51], v[220:223], v[92:95]
	v_mfma_f32_16x16x32_bf16 v[88:91], v[64:67], v[220:223], v[88:91]
	v_mfma_f32_16x16x32_bf16 v[140:143], v[52:55], v[180:183], v[140:143]
	v_mfma_f32_16x16x32_bf16 v[136:139], v[68:71], v[180:183], v[136:139]
	v_mfma_f32_16x16x32_bf16 v[124:127], v[52:55], v[188:191], v[124:127]
	v_mfma_f32_16x16x32_bf16 v[120:123], v[68:71], v[188:191], v[120:123]
	v_mfma_f32_16x16x32_bf16 v[108:111], v[52:55], v[216:219], v[108:111]
	v_mfma_f32_16x16x32_bf16 v[104:107], v[68:71], v[216:219], v[104:107]
	v_mfma_f32_16x16x32_bf16 v[92:95], v[52:55], v[224:227], v[92:95]
	v_mfma_f32_16x16x32_bf16 v[88:91], v[68:71], v[224:227], v[88:91]
	s_setprio 0
	s_setprio 1
	v_mfma_f32_16x16x32_bf16 v[132:135], v[156:159], v[172:175], v[132:135]
	v_mfma_f32_16x16x32_bf16 v[128:131], v[164:167], v[172:175], v[128:131]
	v_mfma_f32_16x16x32_bf16 v[116:119], v[156:159], v[184:187], v[116:119]
	v_mfma_f32_16x16x32_bf16 v[112:115], v[164:167], v[184:187], v[112:115]
	v_mfma_f32_16x16x32_bf16 v[100:103], v[156:159], v[212:215], v[100:103]
	v_mfma_f32_16x16x32_bf16 v[96:99], v[164:167], v[212:215], v[96:99]
	v_mfma_f32_16x16x32_bf16 v[84:87], v[156:159], v[220:223], v[84:87]
	v_mfma_f32_16x16x32_bf16 v[80:83], v[164:167], v[220:223], v[80:83]
	v_mfma_f32_16x16x32_bf16 v[132:135], v[160:163], v[180:183], v[132:135]
	v_mfma_f32_16x16x32_bf16 v[128:131], v[168:171], v[180:183], v[128:131]
	v_mfma_f32_16x16x32_bf16 v[116:119], v[160:163], v[188:191], v[116:119]
	v_mfma_f32_16x16x32_bf16 v[112:115], v[168:171], v[188:191], v[112:115]
	v_mfma_f32_16x16x32_bf16 v[100:103], v[160:163], v[216:219], v[100:103]
	v_mfma_f32_16x16x32_bf16 v[96:99], v[168:171], v[216:219], v[96:99]
	v_mfma_f32_16x16x32_bf16 v[84:87], v[160:163], v[224:227], v[84:87]
	v_mfma_f32_16x16x32_bf16 v[80:83], v[168:171], v[224:227], v[80:83]
	s_setprio 0
	s_barrier
; #define PG8_STAGE(bufoff, gbase, voff) do { _Pragma("unroll") for (int _i = 0; _i < 2; ++_i) \
;         __builtin_amdgcn_global_load_lds((const unsigned*)((const char*)(gbase) + (voff)[_i]), (LAS unsigned*)(lds + (bufoff) + ldsw + _i * 8192), 16, 0, 0); } while (0)
; #define PG8_LDA(dst, b, h) do { _Pragma("unroll") for (int m = 0; m < 4; ++m) _Pragma("unroll") for (int k = 0; k < 2; ++k) dst[m][k] = *(const LAS bf16x8*)(lds + PG8_SA(b, h) + aoff + m * 2048 + k * 1024); } while (0)
; #define PG8_LDB(dst, b, h) do { _Pragma("unroll") for (int n = 0; n < 2; ++n) _Pragma("unroll") for (int k = 0; k < 2; ++k) dst[n][k] = *(const LAS bf16x8*)(lds + PG8_SB(b, h) + boff + n * 2048 + k * 1024); } while (0)
; #define PG8_MMA(ai, bj, At, Bt) do { __builtin_amdgcn_s_setprio(1); _Pragma("unroll") for (int m = 0; m < 4; ++m) _Pragma("unroll") for (int n = 0; n < 2; ++n) _Pragma("unroll") for (int k = 0; k < 2; ++k) \
;         acc[ai][bj][m][n] = __builtin_amdgcn_mfma_f32_16x16x32_bf16(Bt[n][k], At[m][k], acc[ai][bj][m][n], 0, 0, 0); __builtin_amdgcn_s_setprio(0); } while (0)
; #define PG8_WAIT_V(n) asm volatile("s_waitcnt vmcnt(" #n ")" ::: "memory")
; #define PG8_WAIT_L(n) asm volatile("s_waitcnt lgkmcnt(" #n ")" ::: "memory")
; #define PG8_BAR __builtin_amdgcn_s_barrier()
; #define PG8_SCHED __builtin_amdgcn_sched_barrier(0)
; template <class Epi, class Sched, bool ALIGN_EPI>
; __device__ __forceinline__ void gemm_phase(LAS unsigned char* lds, const Gemm g, const Sched& S, const Epi& E) {
;     ...
;             const bool last = (t == nt - 2);
;             const char* a1 = cA + (size_t)(t + 1) * kstep;
;             const char* a2 = last ? nA : cA + (size_t)(t + 2) * kstep; const char* b2 = last ? nB : cB + (size_t)(t + 2) * kstep;
;             const char* a3 = a2 + kstep; const char* b3 = b2 + kstep;
;             PG8_LDB(B0, 0, 0); PG8_LDB(B1, 0, 1); PG8_SCHED; PG8_LDA(At, 0, 0); PG8_STAGE(PG8_SA(1, 1), a1 + hstepA, voffA);
;     ...
;             PG8_LDA(At, 1, 1); PG8_STAGE(PG8_SB(1, 0), b3, voffB); PG8_STAGE(PG8_SB(1, 1), b3 + hstepB, voffB); PG8_STAGE(PG8_SA(1, 0), a3, voffA);
;             PG8_WAIT_V(8); PG8_WAIT_L(0); PG8_BAR; PG8_MMA(1, 0, At, B0); PG8_MMA(1, 1, At, B1); PG8_BAR; PG8_SCHED;
	s_add_i32 s48, s66, s53
	v_lshl_add_u64 v[194:195], v[194:195], 0, s[12:13]
	s_mov_b32 m0, s48
	ds_read_b128 v[172:175], v179 offset:49152
	ds_read_b128 v[180:183], v179 offset:50176
	ds_read_b128 v[184:187], v179 offset:51200
	ds_read_b128 v[188:191], v179 offset:52224
	ds_read_b128 v[212:215], v179 offset:53248
	ds_read_b128 v[216:219], v179 offset:54272
	ds_read_b128 v[220:223], v179 offset:55296
	ds_read_b128 v[224:227], v179 offset:56320
	global_load_lds_dwordx4 v[194:195], off
	s_add_i32 m0, s48, 0x2000
	s_add_u32 s8, s8, 0x40080
	v_lshl_add_u64 v[194:195], v[196:197], 0, s[12:13]
	s_addc_u32 s9, s9, 0
	s_add_i32 s48, s67, s53
	global_load_lds_dwordx4 v[194:195], off
	v_lshl_add_u64 v[194:195], s[8:9], 0, v[148:149]
	s_mov_b32 m0, s48
	s_nop 0
	global_load_lds_dwordx4 v[194:195], off
	v_lshl_add_u64 v[194:195], s[8:9], 0, v[144:145]
	s_add_i32 m0, s48, 0x2000
	s_nop 0
	global_load_lds_dwordx4 v[194:195], off
	v_lshl_add_u64 v[194:195], v[198:199], 0, s[12:13]
	s_mov_b32 m0, s20
	s_nop 0
	global_load_lds_dwordx4 v[194:195], off
	v_lshl_add_u64 v[194:195], v[200:201], 0, s[12:13]
	s_mov_b32 m0, s21
	s_nop 0
	global_load_lds_dwordx4 v[194:195], off
	s_waitcnt vmcnt(8)
	s_waitcnt lgkmcnt(0)
	s_barrier
	s_setprio 1
	s_waitcnt lgkmcnt(0)
	v_mfma_f32_16x16x32_bf16 v[76:79], v[48:51], v[172:175], v[76:79]
	v_mfma_f32_16x16x32_bf16 v[72:75], v[64:67], v[172:175], v[72:75]
	v_mfma_f32_16x16x32_bf16 v[60:63], v[48:51], v[184:187], v[60:63]
	v_mfma_f32_16x16x32_bf16 v[56:59], v[64:67], v[184:187], v[56:59]
	v_mfma_f32_16x16x32_bf16 v[28:31], v[48:51], v[212:215], v[28:31]
	v_mfma_f32_16x16x32_bf16 v[24:27], v[64:67], v[212:215], v[24:27]
	v_mfma_f32_16x16x32_bf16 v[12:15], v[48:51], v[220:223], v[12:15]
	v_mfma_f32_16x16x32_bf16 v[8:11], v[64:67], v[220:223], v[8:11]
	v_mfma_f32_16x16x32_bf16 v[76:79], v[52:55], v[180:183], v[76:79]
	v_mfma_f32_16x16x32_bf16 v[72:75], v[68:71], v[180:183], v[72:75]
	v_mfma_f32_16x16x32_bf16 v[60:63], v[52:55], v[188:191], v[60:63]
	v_mfma_f32_16x16x32_bf16 v[56:59], v[68:71], v[188:191], v[56:59]
	v_mfma_f32_16x16x32_bf16 v[28:31], v[52:55], v[216:219], v[28:31]
	v_mfma_f32_16x16x32_bf16 v[24:27], v[68:71], v[216:219], v[24:27]
	v_mfma_f32_16x16x32_bf16 v[12:15], v[52:55], v[224:227], v[12:15]
	v_mfma_f32_16x16x32_bf16 v[8:11], v[68:71], v[224:227], v[8:11]
	s_setprio 0
	s_setprio 1
	v_mfma_f32_16x16x32_bf16 v[40:43], v[156:159], v[172:175], v[40:43]
	s_add_i32 s65, s65, 2
	v_mfma_f32_16x16x32_bf16 v[68:71], v[160:163], v[180:183], v[40:43]
	s_add_u32 s46, s46, 0x100
	v_mfma_f32_16x16x32_bf16 v[40:43], v[164:167], v[172:175], v[44:47]
	s_addc_u32 s47, s47, 0
	v_mfma_f32_16x16x32_bf16 v[36:39], v[156:159], v[184:187], v[36:39]
	s_add_u32 s57, s57, 0x100
	v_mfma_f32_16x16x32_bf16 v[32:35], v[164:167], v[184:187], v[32:35]
	s_addc_u32 s64, s64, 0
	v_mfma_f32_16x16x32_bf16 v[20:23], v[156:159], v[212:215], v[20:23]
	s_add_u32 s8, s46, 0xfffc0080
	v_mfma_f32_16x16x32_bf16 v[16:19], v[164:167], v[212:215], v[16:19]
	s_addc_u32 s9, s47, -1
	v_mfma_f32_16x16x32_bf16 v[4:7], v[156:159], v[220:223], v[4:7]
	s_add_i32 s66, 0, 0x10000
	v_mfma_f32_16x16x32_bf16 v[0:3], v[164:167], v[220:223], v[0:3]
	s_cmp_eq_u32 s65, 12
	v_mfma_f32_16x16x32_bf16 v[64:67], v[168:171], v[180:183], v[40:43]
	s_cselect_b32 s49, s54, s9
	v_mfma_f32_16x16x32_bf16 v[36:39], v[160:163], v[188:191], v[36:39]
	s_cselect_b32 s48, s55, s8
	v_mfma_f32_16x16x32_bf16 v[32:35], v[168:171], v[188:191], v[32:35]
	s_cselect_b32 s9, s17, s64
	v_mfma_f32_16x16x32_bf16 v[20:23], v[160:163], v[216:219], v[20:23]
	s_cselect_b32 s8, s56, s57
	v_mfma_f32_16x16x32_bf16 v[16:19], v[168:171], v[216:219], v[16:19]
	s_add_i32 s76, 0, 0x14000
	v_mfma_f32_16x16x32_bf16 v[4:7], v[160:163], v[224:227], v[4:7]
	s_cmp_gt_u32 s65, 13
	v_mfma_f32_16x16x32_bf16 v[0:3], v[168:171], v[224:227], v[0:3]
	s_setprio 0
	s_barrier
.LBB0_453:
	v_add_u32_e32 v52, s66, v178
	v_add_u32_e32 v168, s76, v178
	ds_read_b128 v[40:43], v52
	ds_read_b128 v[44:47], v52 offset:1024
	ds_read_b128 v[48:51], v52 offset:2048
	ds_read_b128 v[52:55], v52 offset:3072
	ds_read_b128 v[156:159], v168
	ds_read_b128 v[160:163], v168 offset:1024
	ds_read_b128 v[164:167], v168 offset:2048
	ds_read_b128 v[168:171], v168 offset:3072
	v_lshl_add_u64 v[194:195], s[46:47], 0, v[152:153]
	s_add_i32 m0, s50, 0xc000
	ds_read_b128 v[172:175], v179
	ds_read_b128 v[180:183], v179 offset:1024
	ds_read_b128 v[184:187], v179 offset:2048
	ds_read_b128 v[188:191], v179 offset:3072
	ds_read_b128 v[212:215], v179 offset:4096
	ds_read_b128 v[216:219], v179 offset:5120
	ds_read_b128 v[220:223], v179 offset:6144
	ds_read_b128 v[224:227], v179 offset:7168
	global_load_lds_dwordx4 v[194:195], off
	v_lshl_add_u64 v[194:195], s[46:47], 0, v[154:155]
	s_add_i32 m0, s50, 0xe000
	s_nop 0
	global_load_lds_dwordx4 v[194:195], off
	s_waitcnt vmcnt(8)
	s_waitcnt lgkmcnt(0)
	s_barrier
; #define PG8_STAGE(bufoff, gbase, voff) do { _Pragma("unroll") for (int _i = 0; _i < 2; ++_i) \
;         __builtin_amdgcn_global_load_lds((const unsigned*)((const char*)(gbase) + (voff)[_i]), (LAS unsigned*)(lds + (bufoff) + ldsw + _i * 8192), 16, 0, 0); } while (0)
; #define PG8_LDA(dst, b, h) do { _Pragma("unroll") for (int m = 0; m < 4; ++m) _Pragma("unroll") for (int k = 0; k < 2; ++k) dst[m][k] = *(const LAS bf16x8*)(lds + PG8_SA(b, h) + aoff + m * 2048 + k * 1024); } while (0)
; #define PG8_MMA(ai, bj, At, Bt) do { __builtin_amdgcn_s_setprio(1); _Pragma("unroll") for (int m = 0; m < 4; ++m) _Pragma("unroll") for (int n = 0; n < 2; ++n) _Pragma("unroll") for (int k = 0; k < 2; ++k) \
;         acc[ai][bj][m][n] = __builtin_amdgcn_mfma_f32_16x16x32_bf16(Bt[n][k], At[m][k], acc[ai][bj][m][n], 0, 0, 0); __builtin_amdgcn_s_setprio(0); } while (0)
; #define PG8_WAIT_V(n) asm volatile("s_waitcnt vmcnt(" #n ")" ::: "memory")
; #define PG8_WAIT_L(n) asm volatile("s_waitcnt lgkmcnt(" #n ")" ::: "memory")
; #define PG8_BAR __builtin_amdgcn_s_barrier()
; #define PG8_SCHED __builtin_amdgcn_sched_barrier(0)
; template <class Epi, class Sched, bool ALIGN_EPI>
; __device__ __forceinline__ void gemm_phase(LAS unsigned char* lds, const Gemm g, const Sched& S, const Epi& E) {
;     ...
;             PG8_WAIT_V(8); PG8_WAIT_L(0); PG8_BAR; PG8_MMA(0, 0, At, B0); PG8_MMA(0, 1, At, B1); PG8_BAR; PG8_SCHED;
;             PG8_LDA(At, 0, 1); PG8_STAGE(PG8_SB(0, 0), b2, voffB); PG8_STAGE(PG8_SB(0, 1), b2 + hstepB, voffB); PG8_STAGE(PG8_SA(0, 0), a2, voffA);
;             PG8_WAIT_V(8); PG8_WAIT_L(0); PG8_BAR; PG8_MMA(1, 0, At, B0); PG8_MMA(1, 1, At, B1); PG8_BAR; PG8_SCHED;
	s_setprio 1
	s_waitcnt lgkmcnt(0)
	v_mfma_f32_16x16x32_bf16 v[140:143], v[40:43], v[172:175], v[140:143]
	v_mfma_f32_16x16x32_bf16 v[136:139], v[48:51], v[172:175], v[136:139]
	v_mfma_f32_16x16x32_bf16 v[124:127], v[40:43], v[184:187], v[124:127]
	v_mfma_f32_16x16x32_bf16 v[120:123], v[48:51], v[184:187], v[120:123]
	v_mfma_f32_16x16x32_bf16 v[108:111], v[40:43], v[212:215], v[108:111]
	v_mfma_f32_16x16x32_bf16 v[104:107], v[48:51], v[212:215], v[104:107]
	v_mfma_f32_16x16x32_bf16 v[92:95], v[40:43], v[220:223], v[92:95]
	v_mfma_f32_16x16x32_bf16 v[88:91], v[48:51], v[220:223], v[88:91]
	v_mfma_f32_16x16x32_bf16 v[140:143], v[44:47], v[180:183], v[140:143]
	v_mfma_f32_16x16x32_bf16 v[136:139], v[52:55], v[180:183], v[136:139]
	v_mfma_f32_16x16x32_bf16 v[124:127], v[44:47], v[188:191], v[124:127]
	v_mfma_f32_16x16x32_bf16 v[120:123], v[52:55], v[188:191], v[120:123]
	v_mfma_f32_16x16x32_bf16 v[108:111], v[44:47], v[216:219], v[108:111]
	v_mfma_f32_16x16x32_bf16 v[104:107], v[52:55], v[216:219], v[104:107]
	v_mfma_f32_16x16x32_bf16 v[92:95], v[44:47], v[224:227], v[92:95]
	v_mfma_f32_16x16x32_bf16 v[88:91], v[52:55], v[224:227], v[88:91]
	s_setprio 0
	s_setprio 1
	v_mfma_f32_16x16x32_bf16 v[132:135], v[156:159], v[172:175], v[132:135]
	v_mfma_f32_16x16x32_bf16 v[128:131], v[164:167], v[172:175], v[128:131]
	v_mfma_f32_16x16x32_bf16 v[116:119], v[156:159], v[184:187], v[116:119]
	v_mfma_f32_16x16x32_bf16 v[112:115], v[164:167], v[184:187], v[112:115]
	v_mfma_f32_16x16x32_bf16 v[100:103], v[156:159], v[212:215], v[100:103]
	v_mfma_f32_16x16x32_bf16 v[96:99], v[164:167], v[212:215], v[96:99]
	v_mfma_f32_16x16x32_bf16 v[84:87], v[156:159], v[220:223], v[84:87]
	v_mfma_f32_16x16x32_bf16 v[80:83], v[164:167], v[220:223], v[80:83]
	v_mfma_f32_16x16x32_bf16 v[132:135], v[160:163], v[180:183], v[132:135]
	v_mfma_f32_16x16x32_bf16 v[128:131], v[168:171], v[180:183], v[128:131]
	v_mfma_f32_16x16x32_bf16 v[116:119], v[160:163], v[188:191], v[116:119]
	v_mfma_f32_16x16x32_bf16 v[112:115], v[168:171], v[188:191], v[112:115]
	v_mfma_f32_16x16x32_bf16 v[100:103], v[160:163], v[216:219], v[100:103]
	v_mfma_f32_16x16x32_bf16 v[96:99], v[168:171], v[216:219], v[96:99]
	v_mfma_f32_16x16x32_bf16 v[84:87], v[160:163], v[224:227], v[84:87]
	v_mfma_f32_16x16x32_bf16 v[80:83], v[168:171], v[224:227], v[80:83]
	s_setprio 0
	s_barrier
	s_add_i32 s66, s66, s53
	v_lshl_add_u64 v[194:195], s[8:9], 0, v[148:149]
	s_mov_b32 m0, s66
	ds_read_b128 v[172:175], v179 offset:16384
	ds_read_b128 v[180:183], v179 offset:17408
	ds_read_b128 v[184:187], v179 offset:18432
	ds_read_b128 v[188:191], v179 offset:19456
	ds_read_b128 v[212:215], v179 offset:20480
	ds_read_b128 v[216:219], v179 offset:21504
	ds_read_b128 v[220:223], v179 offset:22528
	ds_read_b128 v[224:227], v179 offset:23552
	global_load_lds_dwordx4 v[194:195], off
	s_add_i32 m0, s66, 0x2000
	s_add_u32 s66, s8, 0x40000
	v_lshl_add_u64 v[196:197], s[8:9], 0, v[144:145]
	s_addc_u32 s67, s9, 0
	s_add_i32 s76, s76, s53
	global_load_lds_dwordx4 v[196:197], off
	v_lshl_add_u64 v[198:199], s[66:67], 0, v[148:149]
	s_mov_b32 m0, s76
	v_lshl_add_u64 v[200:201], s[48:49], 0, v[146:147]
	global_load_lds_dwordx4 v[198:199], off
	v_lshl_add_u64 v[198:199], s[66:67], 0, v[144:145]
	s_add_i32 m0, s76, 0x2000
	s_nop 0
	global_load_lds_dwordx4 v[198:199], off
	v_lshl_add_u64 v[198:199], s[48:49], 0, v[150:151]
	s_mov_b32 m0, s50
	s_nop 0
	global_load_lds_dwordx4 v[198:199], off
	s_mov_b32 m0, s51
	s_nop 0
	global_load_lds_dwordx4 v[200:201], off
	s_waitcnt vmcnt(8)
	s_waitcnt lgkmcnt(0)
	s_barrier
	s_setprio 1
	s_waitcnt lgkmcnt(0)
	v_mfma_f32_16x16x32_bf16 v[76:79], v[40:43], v[172:175], v[76:79]
	v_mfma_f32_16x16x32_bf16 v[72:75], v[48:51], v[172:175], v[72:75]
	v_mfma_f32_16x16x32_bf16 v[60:63], v[40:43], v[184:187], v[60:63]
	v_mfma_f32_16x16x32_bf16 v[56:59], v[48:51], v[184:187], v[56:59]
	v_mfma_f32_16x16x32_bf16 v[28:31], v[40:43], v[212:215], v[28:31]
	v_mfma_f32_16x16x32_bf16 v[24:27], v[48:51], v[212:215], v[24:27]
	v_mfma_f32_16x16x32_bf16 v[12:15], v[40:43], v[220:223], v[12:15]
	v_mfma_f32_16x16x32_bf16 v[8:11], v[48:51], v[220:223], v[8:11]
	v_mfma_f32_16x16x32_bf16 v[76:79], v[44:47], v[180:183], v[76:79]
	v_mfma_f32_16x16x32_bf16 v[72:75], v[52:55], v[180:183], v[72:75]
	v_mfma_f32_16x16x32_bf16 v[60:63], v[44:47], v[188:191], v[60:63]
	v_mfma_f32_16x16x32_bf16 v[56:59], v[52:55], v[188:191], v[56:59]
	v_mfma_f32_16x16x32_bf16 v[28:31], v[44:47], v[216:219], v[28:31]
	v_mfma_f32_16x16x32_bf16 v[24:27], v[52:55], v[216:219], v[24:27]
	v_mfma_f32_16x16x32_bf16 v[12:15], v[44:47], v[224:227], v[12:15]
	v_mfma_f32_16x16x32_bf16 v[8:11], v[52:55], v[224:227], v[8:11]
	s_setprio 0
	s_setprio 1
	v_mfma_f32_16x16x32_bf16 v[36:39], v[156:159], v[184:187], v[36:39]
	v_mfma_f32_16x16x32_bf16 v[32:35], v[164:167], v[184:187], v[32:35]
	v_mfma_f32_16x16x32_bf16 v[20:23], v[156:159], v[212:215], v[20:23]
	v_mfma_f32_16x16x32_bf16 v[16:19], v[164:167], v[212:215], v[16:19]
	v_mfma_f32_16x16x32_bf16 v[4:7], v[156:159], v[220:223], v[4:7]
	v_mfma_f32_16x16x32_bf16 v[0:3], v[164:167], v[220:223], v[0:3]
	v_mfma_f32_16x16x32_bf16 v[40:43], v[156:159], v[172:175], v[68:71]
	v_mfma_f32_16x16x32_bf16 v[44:47], v[164:167], v[172:175], v[64:67]
	v_mfma_f32_16x16x32_bf16 v[36:39], v[160:163], v[188:191], v[36:39]
	v_mfma_f32_16x16x32_bf16 v[32:35], v[168:171], v[188:191], v[32:35]
	v_mfma_f32_16x16x32_bf16 v[20:23], v[160:163], v[216:219], v[20:23]
	v_mfma_f32_16x16x32_bf16 v[16:19], v[168:171], v[216:219], v[16:19]
	v_mfma_f32_16x16x32_bf16 v[4:7], v[160:163], v[224:227], v[4:7]
	v_mfma_f32_16x16x32_bf16 v[0:3], v[168:171], v[224:227], v[0:3]
	v_mfma_f32_16x16x32_bf16 v[40:43], v[160:163], v[180:183], v[40:43]
	v_mfma_f32_16x16x32_bf16 v[44:47], v[168:171], v[180:183], v[44:47]
	s_setprio 0
	s_barrier
; #define PG8_STAGE(bufoff, gbase, voff) do { _Pragma("unroll") for (int _i = 0; _i < 2; ++_i) \
;         __builtin_amdgcn_global_load_lds((const unsigned*)((const char*)(gbase) + (voff)[_i]), (LAS unsigned*)(lds + (bufoff) + ldsw + _i * 8192), 16, 0, 0); } while (0)
; #define PG8_LDA(dst, b, h) do { _Pragma("unroll") for (int m = 0; m < 4; ++m) _Pragma("unroll") for (int k = 0; k < 2; ++k) dst[m][k] = *(const LAS bf16x8*)(lds + PG8_SA(b, h) + aoff + m * 2048 + k * 1024); } while (0)
; #define PG8_LDB(dst, b, h) do { _Pragma("unroll") for (int n = 0; n < 2; ++n) _Pragma("unroll") for (int k = 0; k < 2; ++k) dst[n][k] = *(const LAS bf16x8*)(lds + PG8_SB(b, h) + boff + n * 2048 + k * 1024); } while (0)
; #define PG8_MMA(ai, bj, At, Bt) do { __builtin_amdgcn_s_setprio(1); _Pragma("unroll") for (int m = 0; m < 4; ++m) _Pragma("unroll") for (int n = 0; n < 2; ++n) _Pragma("unroll") for (int k = 0; k < 2; ++k) \
;         acc[ai][bj][m][n] = __builtin_amdgcn_mfma_f32_16x16x32_bf16(Bt[n][k], At[m][k], acc[ai][bj][m][n], 0, 0, 0); __builtin_amdgcn_s_setprio(0); } while (0)
; #define PG8_WAIT_V(n) asm volatile("s_waitcnt vmcnt(" #n ")" ::: "memory")
; #define PG8_WAIT_L(n) asm volatile("s_waitcnt lgkmcnt(" #n ")" ::: "memory")
; #define PG8_BAR __builtin_amdgcn_s_barrier()
; #define PG8_SCHED __builtin_amdgcn_sched_barrier(0)
; template <class Epi, class Sched, bool ALIGN_EPI>
; __device__ __forceinline__ void gemm_phase(LAS unsigned char* lds, const Gemm g, const Sched& S, const Epi& E) {
;     ...
;             PG8_LDB(B0, 1, 0); PG8_LDB(B1, 1, 1); PG8_SCHED; PG8_LDA(At, 1, 0); PG8_STAGE(PG8_SA(0, 1), a2 + hstepA, voffA);
;             PG8_WAIT_V(8); PG8_WAIT_L(0); PG8_BAR; PG8_MMA(0, 0, At, B0); PG8_MMA(0, 1, At, B1); PG8_BAR; PG8_SCHED;
	s_add_i32 s66, 0, 0x18000
	s_add_i32 s67, 0, 0x1c000
	v_add_u32_e32 v68, s66, v178
	v_add_u32_e32 v168, s67, v178
	ds_read_b128 v[48:51], v68
	ds_read_b128 v[52:55], v68 offset:1024
	ds_read_b128 v[64:67], v68 offset:2048
	ds_read_b128 v[68:71], v68 offset:3072
	ds_read_b128 v[156:159], v168
	ds_read_b128 v[160:163], v168 offset:1024
	ds_read_b128 v[164:167], v168 offset:2048
	ds_read_b128 v[168:171], v168 offset:3072
	s_add_u32 s48, s48, 0x40000
	s_addc_u32 s49, s49, 0
	s_mov_b32 m0, s22
	v_lshl_add_u64 v[202:203], s[48:49], 0, v[150:151]
	ds_read_b128 v[172:175], v179 offset:32768
	ds_read_b128 v[180:183], v179 offset:33792
	ds_read_b128 v[184:187], v179 offset:34816
	ds_read_b128 v[188:191], v179 offset:35840
	ds_read_b128 v[212:215], v179 offset:36864
	ds_read_b128 v[216:219], v179 offset:37888
	ds_read_b128 v[220:223], v179 offset:38912
	ds_read_b128 v[224:227], v179 offset:39936
	global_load_lds_dwordx4 v[202:203], off
	v_lshl_add_u64 v[202:203], s[48:49], 0, v[146:147]
	s_mov_b32 m0, s23
	s_nop 0
	global_load_lds_dwordx4 v[202:203], off
	s_waitcnt vmcnt(8)
	s_waitcnt lgkmcnt(0)
	s_barrier
	s_setprio 1
	s_waitcnt lgkmcnt(0)
	v_mfma_f32_16x16x32_bf16 v[140:143], v[48:51], v[172:175], v[140:143]
	v_mfma_f32_16x16x32_bf16 v[136:139], v[64:67], v[172:175], v[136:139]
	v_mfma_f32_16x16x32_bf16 v[124:127], v[48:51], v[184:187], v[124:127]
	v_mfma_f32_16x16x32_bf16 v[120:123], v[64:67], v[184:187], v[120:123]
	v_mfma_f32_16x16x32_bf16 v[108:111], v[48:51], v[212:215], v[108:111]
	v_mfma_f32_16x16x32_bf16 v[104:107], v[64:67], v[212:215], v[104:107]
	v_mfma_f32_16x16x32_bf16 v[92:95], v[48:51], v[220:223], v[92:95]
	v_mfma_f32_16x16x32_bf16 v[88:91], v[64:67], v[220:223], v[88:91]
	v_mfma_f32_16x16x32_bf16 v[140:143], v[52:55], v[180:183], v[140:143]
	v_mfma_f32_16x16x32_bf16 v[136:139], v[68:71], v[180:183], v[136:139]
	v_mfma_f32_16x16x32_bf16 v[124:127], v[52:55], v[188:191], v[124:127]
	v_mfma_f32_16x16x32_bf16 v[120:123], v[68:71], v[188:191], v[120:123]
	v_mfma_f32_16x16x32_bf16 v[108:111], v[52:55], v[216:219], v[108:111]
	v_mfma_f32_16x16x32_bf16 v[104:107], v[68:71], v[216:219], v[104:107]
	v_mfma_f32_16x16x32_bf16 v[92:95], v[52:55], v[224:227], v[92:95]
	v_mfma_f32_16x16x32_bf16 v[88:91], v[68:71], v[224:227], v[88:91]
	s_setprio 0
	s_setprio 1
	v_mfma_f32_16x16x32_bf16 v[132:135], v[156:159], v[172:175], v[132:135]
	v_mfma_f32_16x16x32_bf16 v[128:131], v[164:167], v[172:175], v[128:131]
	v_mfma_f32_16x16x32_bf16 v[116:119], v[156:159], v[184:187], v[116:119]
	v_mfma_f32_16x16x32_bf16 v[112:115], v[164:167], v[184:187], v[112:115]
	v_mfma_f32_16x16x32_bf16 v[100:103], v[156:159], v[212:215], v[100:103]
	v_mfma_f32_16x16x32_bf16 v[96:99], v[164:167], v[212:215], v[96:99]
	v_mfma_f32_16x16x32_bf16 v[84:87], v[156:159], v[220:223], v[84:87]
	v_mfma_f32_16x16x32_bf16 v[80:83], v[164:167], v[220:223], v[80:83]
	v_mfma_f32_16x16x32_bf16 v[132:135], v[160:163], v[180:183], v[132:135]
	v_mfma_f32_16x16x32_bf16 v[128:131], v[168:171], v[180:183], v[128:131]
	v_mfma_f32_16x16x32_bf16 v[116:119], v[160:163], v[188:191], v[116:119]
	v_mfma_f32_16x16x32_bf16 v[112:115], v[168:171], v[188:191], v[112:115]
	v_mfma_f32_16x16x32_bf16 v[100:103], v[160:163], v[216:219], v[100:103]
	v_mfma_f32_16x16x32_bf16 v[96:99], v[168:171], v[216:219], v[96:99]
	v_mfma_f32_16x16x32_bf16 v[84:87], v[160:163], v[224:227], v[84:87]
	v_mfma_f32_16x16x32_bf16 v[80:83], v[168:171], v[224:227], v[80:83]
	s_setprio 0
	s_barrier
; #define PG8_STAGE(bufoff, gbase, voff) do { _Pragma("unroll") for (int _i = 0; _i < 2; ++_i) \
;         __builtin_amdgcn_global_load_lds((const unsigned*)((const char*)(gbase) + (voff)[_i]), (LAS unsigned*)(lds + (bufoff) + ldsw + _i * 8192), 16, 0, 0); } while (0)
; #define PG8_LDA(dst, b, h) do { _Pragma("unroll") for (int m = 0; m < 4; ++m) _Pragma("unroll") for (int k = 0; k < 2; ++k) dst[m][k] = *(const LAS bf16x8*)(lds + PG8_SA(b, h) + aoff + m * 2048 + k * 1024); } while (0)
; #define PG8_MMA(ai, bj, At, Bt) do { __builtin_amdgcn_s_setprio(1); _Pragma("unroll") for (int m = 0; m < 4; ++m) _Pragma("unroll") for (int n = 0; n < 2; ++n) _Pragma("unroll") for (int k = 0; k < 2; ++k) \
;         acc[ai][bj][m][n] = __builtin_amdgcn_mfma_f32_16x16x32_bf16(Bt[n][k], At[m][k], acc[ai][bj][m][n], 0, 0, 0); __builtin_amdgcn_s_setprio(0); } while (0)
; #define PG8_WAIT_V(n) asm volatile("s_waitcnt vmcnt(" #n ")" ::: "memory")
; #define PG8_WAIT_L(n) asm volatile("s_waitcnt lgkmcnt(" #n ")" ::: "memory")
; #define PG8_BAR __builtin_amdgcn_s_barrier()
; #define PG8_SCHED __builtin_amdgcn_sched_barrier(0)
; template <class Epi, class Sched, bool ALIGN_EPI>
; __device__ __forceinline__ void gemm_phase(LAS unsigned char* lds, const Gemm g, const Sched& S, const Epi& E) {
;     ...
;             PG8_LDA(At, 1, 1); PG8_STAGE(PG8_SB(1, 0), b3, voffB); PG8_STAGE(PG8_SB(1, 1), b3 + hstepB, voffB); PG8_STAGE(PG8_SA(1, 0), a3, voffA);
;             PG8_WAIT_V(8); PG8_WAIT_L(0); PG8_BAR; PG8_MMA(1, 0, At, B0); PG8_MMA(1, 1, At, B1); PG8_BAR; PG8_SCHED;
;         }
;         if constexpr (ALIGN_EPI) { if (wr == 0) PG8_BAR; }
	s_add_i32 s48, s66, s53
	v_lshl_add_u64 v[194:195], v[194:195], 0, s[12:13]
	s_mov_b32 m0, s48
	ds_read_b128 v[172:175], v179 offset:49152
	ds_read_b128 v[180:183], v179 offset:50176
	ds_read_b128 v[184:187], v179 offset:51200
	ds_read_b128 v[188:191], v179 offset:52224
	ds_read_b128 v[212:215], v179 offset:53248
	ds_read_b128 v[216:219], v179 offset:54272
	ds_read_b128 v[220:223], v179 offset:55296
	ds_read_b128 v[224:227], v179 offset:56320
	global_load_lds_dwordx4 v[194:195], off
	s_add_i32 m0, s48, 0x2000
	s_add_u32 s8, s8, 0x40080
	v_lshl_add_u64 v[194:195], v[196:197], 0, s[12:13]
	s_addc_u32 s9, s9, 0
	s_add_i32 s48, s67, s53
	global_load_lds_dwordx4 v[194:195], off
	v_lshl_add_u64 v[194:195], s[8:9], 0, v[148:149]
	s_mov_b32 m0, s48
	s_nop 0
	global_load_lds_dwordx4 v[194:195], off
	v_lshl_add_u64 v[194:195], s[8:9], 0, v[144:145]
	s_add_i32 m0, s48, 0x2000
	s_nop 0
	global_load_lds_dwordx4 v[194:195], off
	v_lshl_add_u64 v[194:195], v[198:199], 0, s[12:13]
	s_mov_b32 m0, s20
	s_nop 0
	global_load_lds_dwordx4 v[194:195], off
	v_lshl_add_u64 v[194:195], v[200:201], 0, s[12:13]
	s_mov_b32 m0, s21
	s_nop 0
	global_load_lds_dwordx4 v[194:195], off
	s_waitcnt vmcnt(8)
	s_waitcnt lgkmcnt(0)
	s_barrier
	s_setprio 1
	s_waitcnt lgkmcnt(0)
	v_mfma_f32_16x16x32_bf16 v[76:79], v[48:51], v[172:175], v[76:79]
	v_mfma_f32_16x16x32_bf16 v[72:75], v[64:67], v[172:175], v[72:75]
	v_mfma_f32_16x16x32_bf16 v[60:63], v[48:51], v[184:187], v[60:63]
	v_mfma_f32_16x16x32_bf16 v[56:59], v[64:67], v[184:187], v[56:59]
	v_mfma_f32_16x16x32_bf16 v[28:31], v[48:51], v[212:215], v[28:31]
	v_mfma_f32_16x16x32_bf16 v[24:27], v[64:67], v[212:215], v[24:27]
	v_mfma_f32_16x16x32_bf16 v[12:15], v[48:51], v[220:223], v[12:15]
	v_mfma_f32_16x16x32_bf16 v[8:11], v[64:67], v[220:223], v[8:11]
	v_mfma_f32_16x16x32_bf16 v[76:79], v[52:55], v[180:183], v[76:79]
	v_mfma_f32_16x16x32_bf16 v[72:75], v[68:71], v[180:183], v[72:75]
	v_mfma_f32_16x16x32_bf16 v[60:63], v[52:55], v[188:191], v[60:63]
	v_mfma_f32_16x16x32_bf16 v[56:59], v[68:71], v[188:191], v[56:59]
	v_mfma_f32_16x16x32_bf16 v[28:31], v[52:55], v[216:219], v[28:31]
	v_mfma_f32_16x16x32_bf16 v[24:27], v[68:71], v[216:219], v[24:27]
	v_mfma_f32_16x16x32_bf16 v[12:15], v[52:55], v[224:227], v[12:15]
	v_mfma_f32_16x16x32_bf16 v[8:11], v[68:71], v[224:227], v[8:11]
	s_setprio 0
	s_setprio 1
	v_mfma_f32_16x16x32_bf16 v[40:43], v[156:159], v[172:175], v[40:43]
	s_add_i32 s65, s65, 2
	v_mfma_f32_16x16x32_bf16 v[68:71], v[160:163], v[180:183], v[40:43]
	s_add_u32 s46, s46, 0x100
	v_mfma_f32_16x16x32_bf16 v[40:43], v[164:167], v[172:175], v[44:47]
	s_addc_u32 s47, s47, 0
	v_mfma_f32_16x16x32_bf16 v[36:39], v[156:159], v[184:187], v[36:39]
	s_add_u32 s57, s57, 0x100
	v_mfma_f32_16x16x32_bf16 v[32:35], v[164:167], v[184:187], v[32:35]
	s_addc_u32 s64, s64, 0
	v_mfma_f32_16x16x32_bf16 v[20:23], v[156:159], v[212:215], v[20:23]
	s_add_u32 s8, s46, 0xfffc0080
	v_mfma_f32_16x16x32_bf16 v[16:19], v[164:167], v[212:215], v[16:19]
	s_addc_u32 s9, s47, -1
	v_mfma_f32_16x16x32_bf16 v[4:7], v[156:159], v[220:223], v[4:7]
	s_add_i32 s66, 0, 0x10000
	v_mfma_f32_16x16x32_bf16 v[0:3], v[164:167], v[220:223], v[0:3]
	s_cmp_eq_u32 s65, 12
	v_mfma_f32_16x16x32_bf16 v[64:67], v[168:171], v[180:183], v[40:43]
	s_cselect_b32 s49, s54, s9
	v_mfma_f32_16x16x32_bf16 v[36:39], v[160:163], v[188:191], v[36:39]
	s_cselect_b32 s48, s55, s8
	v_mfma_f32_16x16x32_bf16 v[32:35], v[168:171], v[188:191], v[32:35]
	s_cselect_b32 s9, s17, s64
	v_mfma_f32_16x16x32_bf16 v[20:23], v[160:163], v[216:219], v[20:23]
	s_cselect_b32 s8, s56, s57
	v_mfma_f32_16x16x32_bf16 v[16:19], v[168:171], v[216:219], v[16:19]
	s_add_i32 s76, 0, 0x14000
	v_mfma_f32_16x16x32_bf16 v[4:7], v[160:163], v[224:227], v[4:7]
	s_cmp_gt_u32 s65, 13
	v_mfma_f32_16x16x32_bf16 v[0:3], v[168:171], v[224:227], v[0:3]
	s_setprio 0
	s_barrier
	s_cbranch_scc0 .LBB0_453
	v_readlane_b32 s8, v255, 58
	v_readlane_b32 s9, v255, 59
	s_and_b64 vcc, exec, s[8:9]
	s_cbranch_vccz .LBB0_456
	s_barrier

; #define PG8_STAGE(bufoff, gbase, voff) do { _Pragma("unroll") for (int _i = 0; _i < 2; ++_i) \
;         __builtin_amdgcn_global_load_lds((const unsigned*)((const char*)(gbase) + (voff)[_i]), (LAS unsigned*)(lds + (bufoff) + ldsw + _i * 8192), 16, 0, 0); } while (0)
; #define PG8_LDA(dst, b, h) do { _Pragma("unroll") for (int m = 0; m < 4; ++m) _Pragma("unroll") for (int k = 0; k < 2; ++k) dst[m][k] = *(const LAS bf16x8*)(lds + PG8_SA(b, h) + aoff + m * 2048 + k * 1024); } while (0)
; #define PG8_LDB(dst, b, h) do { _Pragma("unroll") for (int n = 0; n < 2; ++n) _Pragma("unroll") for (int k = 0; k < 2; ++k) dst[n][k] = *(const LAS bf16x8*)(lds + PG8_SB(b, h) + boff + n * 2048 + k * 1024); } while (0)
; #define PG8_MMA(ai, bj, At, Bt) do { __builtin_amdgcn_s_setprio(1); _Pragma("unroll") for (int m = 0; m < 4; ++m) _Pragma("unroll") for (int n = 0; n < 2; ++n) _Pragma("unroll") for (int k = 0; k < 2; ++k) \
;         acc[ai][bj][m][n] = __builtin_amdgcn_mfma_f32_16x16x32_bf16(Bt[n][k], At[m][k], acc[ai][bj][m][n], 0, 0, 0); __builtin_amdgcn_s_setprio(0); } while (0)
; #define PG8_WAIT_V(n) asm volatile("s_waitcnt vmcnt(" #n ")" ::: "memory")
; #define PG8_WAIT_L(n) asm volatile("s_waitcnt lgkmcnt(" #n ")" ::: "memory")
; #define PG8_BAR __builtin_amdgcn_s_barrier()
; template <class Epi, class Sched, bool ALIGN_EPI>
; __device__ __forceinline__ void gemm_phase(LAS unsigned char* lds, const Gemm g, const Sched& S, const Epi& E) {
;     ...
;         const char* nA = has_next ? (const char*)g.A + (size_t)nxt.pm * tstepA : cA; const char* nB = has_next ? (const char*)g.Bt + (size_t)nxt.pn * tstepB : cB;
;         for (int t = 0; t < nt; t += 2) {
;             const bool last = (t == nt - 2);
;             const char* a1 = cA + (size_t)(t + 1) * kstep;
;             const char* a2 = last ? nA : cA + (size_t)(t + 2) * kstep; const char* b2 = last ? nB : cB + (size_t)(t + 2) * kstep;
;             const char* a3 = a2 + kstep; const char* b3 = b2 + kstep;
;             PG8_LDB(B0, 0, 0); PG8_LDB(B1, 0, 1); PG8_SCHED; PG8_LDA(At, 0, 0); PG8_STAGE(PG8_SA(1, 1), a1 + hstepA, voffA);
;             PG8_WAIT_V(8); PG8_WAIT_L(0); PG8_BAR; PG8_MMA(0, 0, At, B0); PG8_MMA(0, 1, At, B1); PG8_BAR; PG8_SCHED;
;             PG8_LDA(At, 0, 1); PG8_STAGE(PG8_SB(0, 0), b2, voffB); PG8_STAGE(PG8_SB(0, 1), b2 + hstepB, voffB); PG8_STAGE(PG8_SA(0, 0), a2, voffA);
.LBB0_570:
	s_ashr_i32 s21, s20, 31
	s_lshl_b64 s[38:39], s[20:21], 19
	s_add_u32 s38, s22, s38
	s_addc_u32 s39, s23, s39
	s_and_b64 s[40:41], s[42:43], exec
	s_cselect_b32 s21, s39, s45
	s_cselect_b32 s86, s38, s44
	s_ashr_i32 s17, s16, 31
	s_lshl_b64 s[40:41], s[16:17], 19
	s_add_u32 s40, s50, s40
	s_addc_u32 s41, s51, s41
	s_and_b64 s[48:49], s[42:43], exec
	s_cselect_b32 s17, s41, s47
	s_cselect_b32 s87, s40, s46
	s_add_u32 s44, s44, 0x40080
	s_addc_u32 s45, s45, 0
	s_add_u32 s90, s46, 0x100
	s_addc_u32 s91, s47, 0
	s_mov_b32 s92, -2
	s_add_u32 s46, s44, 0xfffc0080
	s_addc_u32 s47, s45, -1
	s_add_i32 vcc_lo, 0, 0x10000
	s_cmp_eq_u32 s92, 12
	s_cselect_b32 s49, s21, s47
	s_cselect_b32 s48, s86, s46
	s_cselect_b32 s47, s17, s91
	s_cselect_b32 s46, s87, s90
	s_add_i32 s4, 0, 0x14000
	v_add_u32_e32 v76, vcc_lo, v162
	v_add_u32_e32 v158, s4, v162
	ds_read_b128 v[64:67], v76
	ds_read_b128 v[68:71], v76 offset:1024
	ds_read_b128 v[72:75], v76 offset:2048
	ds_read_b128 v[76:79], v76 offset:3072
	ds_read_b128 v[154:157], v158
	ds_read_b128 v[164:167], v158 offset:1024
	ds_read_b128 v[168:171], v158 offset:2048
	ds_read_b128 v[172:175], v158 offset:3072
	v_lshl_add_u64 v[158:159], s[44:45], 0, v[150:151]
	s_add_i32 m0, s54, 0xc000
	ds_read_b128 v[176:179], v163
	ds_read_b128 v[180:183], v163 offset:1024
	ds_read_b128 v[184:187], v163 offset:2048
	ds_read_b128 v[188:191], v163 offset:3072
	ds_read_b128 v[212:215], v163 offset:4096
	ds_read_b128 v[216:219], v163 offset:5120
	ds_read_b128 v[220:223], v163 offset:6144
	ds_read_b128 v[224:227], v163 offset:7168
	global_load_lds_dwordx4 v[158:159], off
	v_lshl_add_u64 v[158:159], s[44:45], 0, v[152:153]
	s_add_i32 m0, s54, 0xe000
	s_nop 0
	global_load_lds_dwordx4 v[158:159], off
	s_waitcnt vmcnt(8)
	s_waitcnt lgkmcnt(0)
	s_barrier
	s_setprio 1
	s_waitcnt lgkmcnt(0)
	v_mfma_f32_16x16x32_bf16 v[140:143], v[64:67], v[176:179], 0
	v_mfma_f32_16x16x32_bf16 v[136:139], v[72:75], v[176:179], 0
	v_mfma_f32_16x16x32_bf16 v[124:127], v[64:67], v[184:187], 0
	v_mfma_f32_16x16x32_bf16 v[120:123], v[72:75], v[184:187], 0
	v_mfma_f32_16x16x32_bf16 v[108:111], v[64:67], v[212:215], 0
	v_mfma_f32_16x16x32_bf16 v[104:107], v[72:75], v[212:215], 0
	v_mfma_f32_16x16x32_bf16 v[92:95], v[64:67], v[220:223], 0
	v_mfma_f32_16x16x32_bf16 v[88:91], v[72:75], v[220:223], 0
	v_mfma_f32_16x16x32_bf16 v[140:143], v[68:71], v[180:183], v[140:143]
	v_mfma_f32_16x16x32_bf16 v[136:139], v[76:79], v[180:183], v[136:139]
	v_mfma_f32_16x16x32_bf16 v[124:127], v[68:71], v[188:191], v[124:127]
	v_mfma_f32_16x16x32_bf16 v[120:123], v[76:79], v[188:191], v[120:123]
	v_mfma_f32_16x16x32_bf16 v[108:111], v[68:71], v[216:219], v[108:111]
	v_mfma_f32_16x16x32_bf16 v[104:107], v[76:79], v[216:219], v[104:107]
	v_mfma_f32_16x16x32_bf16 v[92:95], v[68:71], v[224:227], v[92:95]
	v_mfma_f32_16x16x32_bf16 v[88:91], v[76:79], v[224:227], v[88:91]
	s_setprio 0
	s_setprio 1
	v_mfma_f32_16x16x32_bf16 v[132:135], v[154:157], v[176:179], 0
	v_mfma_f32_16x16x32_bf16 v[128:131], v[168:171], v[176:179], 0
	v_mfma_f32_16x16x32_bf16 v[116:119], v[154:157], v[184:187], 0
	v_mfma_f32_16x16x32_bf16 v[112:115], v[168:171], v[184:187], 0
	v_mfma_f32_16x16x32_bf16 v[100:103], v[154:157], v[212:215], 0
	v_mfma_f32_16x16x32_bf16 v[96:99], v[168:171], v[212:215], 0
	v_mfma_f32_16x16x32_bf16 v[84:87], v[154:157], v[220:223], 0
	v_mfma_f32_16x16x32_bf16 v[80:83], v[168:171], v[220:223], 0
	v_mfma_f32_16x16x32_bf16 v[132:135], v[164:167], v[180:183], v[132:135]
	v_mfma_f32_16x16x32_bf16 v[128:131], v[172:175], v[180:183], v[128:131]
	v_mfma_f32_16x16x32_bf16 v[116:119], v[164:167], v[188:191], v[116:119]
	v_mfma_f32_16x16x32_bf16 v[112:115], v[172:175], v[188:191], v[112:115]
	v_mfma_f32_16x16x32_bf16 v[100:103], v[164:167], v[216:219], v[100:103]
	v_mfma_f32_16x16x32_bf16 v[96:99], v[172:175], v[216:219], v[96:99]
	v_mfma_f32_16x16x32_bf16 v[84:87], v[164:167], v[224:227], v[84:87]
	v_mfma_f32_16x16x32_bf16 v[80:83], v[172:175], v[224:227], v[80:83]
	s_setprio 0
	s_barrier
	s_add_i32 s5, vcc_lo, s53
	v_lshl_add_u64 v[158:159], s[46:47], 0, v[192:193]
	s_mov_b32 m0, s5
	ds_read_b128 v[176:179], v163 offset:16384
	ds_read_b128 v[180:183], v163 offset:17408
	ds_read_b128 v[184:187], v163 offset:18432
	ds_read_b128 v[188:191], v163 offset:19456
	ds_read_b128 v[212:215], v163 offset:20480
	ds_read_b128 v[216:219], v163 offset:21504
	ds_read_b128 v[220:223], v163 offset:22528
	ds_read_b128 v[224:227], v163 offset:23552
	global_load_lds_dwordx4 v[158:159], off
	s_add_i32 m0, s5, 0x2000
	s_add_u32 vcc_lo, s46, 0x40000
	v_lshl_add_u64 v[194:195], s[46:47], 0, v[144:145]
	s_addc_u32 vcc_hi, s47, 0
	s_add_i32 s4, s4, s53
	global_load_lds_dwordx4 v[194:195], off
	v_lshl_add_u64 v[196:197], vcc, 0, v[192:193]
	s_mov_b32 m0, s4
	v_lshl_add_u64 v[198:199], s[48:49], 0, v[146:147]
	global_load_lds_dwordx4 v[196:197], off
	v_lshl_add_u64 v[196:197], vcc, 0, v[144:145]
	s_add_i32 m0, s4, 0x2000
	s_nop 0
	global_load_lds_dwordx4 v[196:197], off
	v_lshl_add_u64 v[196:197], s[48:49], 0, v[148:149]
	s_mov_b32 m0, s54
	s_nop 0
	global_load_lds_dwordx4 v[196:197], off
	s_mov_b32 m0, s55
	s_nop 0
	global_load_lds_dwordx4 v[198:199], off
	s_waitcnt vmcnt(8)
	s_waitcnt lgkmcnt(0)
	s_barrier
; #define PG8_STAGE(bufoff, gbase, voff) do { _Pragma("unroll") for (int _i = 0; _i < 2; ++_i) \
;         __builtin_amdgcn_global_load_lds((const unsigned*)((const char*)(gbase) + (voff)[_i]), (LAS unsigned*)(lds + (bufoff) + ldsw + _i * 8192), 16, 0, 0); } while (0)
; #define PG8_LDA(dst, b, h) do { _Pragma("unroll") for (int m = 0; m < 4; ++m) _Pragma("unroll") for (int k = 0; k < 2; ++k) dst[m][k] = *(const LAS bf16x8*)(lds + PG8_SA(b, h) + aoff + m * 2048 + k * 1024); } while (0)
; #define PG8_LDB(dst, b, h) do { _Pragma("unroll") for (int n = 0; n < 2; ++n) _Pragma("unroll") for (int k = 0; k < 2; ++k) dst[n][k] = *(const LAS bf16x8*)(lds + PG8_SB(b, h) + boff + n * 2048 + k * 1024); } while (0)
; #define PG8_MMA(ai, bj, At, Bt) do { __builtin_amdgcn_s_setprio(1); _Pragma("unroll") for (int m = 0; m < 4; ++m) _Pragma("unroll") for (int n = 0; n < 2; ++n) _Pragma("unroll") for (int k = 0; k < 2; ++k) \
;         acc[ai][bj][m][n] = __builtin_amdgcn_mfma_f32_16x16x32_bf16(Bt[n][k], At[m][k], acc[ai][bj][m][n], 0, 0, 0); __builtin_amdgcn_s_setprio(0); } while (0)
; #define PG8_WAIT_V(n) asm volatile("s_waitcnt vmcnt(" #n ")" ::: "memory")
; #define PG8_WAIT_L(n) asm volatile("s_waitcnt lgkmcnt(" #n ")" ::: "memory")
; #define PG8_BAR __builtin_amdgcn_s_barrier()
; #define PG8_SCHED __builtin_amdgcn_sched_barrier(0)
; template <class Epi, class Sched, bool ALIGN_EPI>
; __device__ __forceinline__ void gemm_phase(LAS unsigned char* lds, const Gemm g, const Sched& S, const Epi& E) {
;     ...
;             PG8_WAIT_V(8); PG8_WAIT_L(0); PG8_BAR; PG8_MMA(1, 0, At, B0); PG8_MMA(1, 1, At, B1); PG8_BAR; PG8_SCHED;
;             PG8_LDB(B0, 1, 0); PG8_LDB(B1, 1, 1); PG8_SCHED; PG8_LDA(At, 1, 0); PG8_STAGE(PG8_SA(0, 1), a2 + hstepA, voffA);
;             PG8_WAIT_V(8); PG8_WAIT_L(0); PG8_BAR; PG8_MMA(0, 0, At, B0); PG8_MMA(0, 1, At, B1); PG8_BAR; PG8_SCHED;
	s_setprio 1
	s_waitcnt lgkmcnt(0)
	v_mfma_f32_16x16x32_bf16 v[60:63], v[64:67], v[176:179], 0
	v_mfma_f32_16x16x32_bf16 v[56:59], v[72:75], v[176:179], 0
	v_mfma_f32_16x16x32_bf16 v[44:47], v[64:67], v[184:187], 0
	v_mfma_f32_16x16x32_bf16 v[40:43], v[72:75], v[184:187], 0
	v_mfma_f32_16x16x32_bf16 v[28:31], v[64:67], v[212:215], 0
	v_mfma_f32_16x16x32_bf16 v[24:27], v[72:75], v[212:215], 0
	v_mfma_f32_16x16x32_bf16 v[12:15], v[64:67], v[220:223], 0
	v_mfma_f32_16x16x32_bf16 v[8:11], v[72:75], v[220:223], 0
	v_mfma_f32_16x16x32_bf16 v[60:63], v[68:71], v[180:183], v[60:63]
	v_mfma_f32_16x16x32_bf16 v[56:59], v[76:79], v[180:183], v[56:59]
	v_mfma_f32_16x16x32_bf16 v[44:47], v[68:71], v[188:191], v[44:47]
	v_mfma_f32_16x16x32_bf16 v[40:43], v[76:79], v[188:191], v[40:43]
	v_mfma_f32_16x16x32_bf16 v[28:31], v[68:71], v[216:219], v[28:31]
	v_mfma_f32_16x16x32_bf16 v[24:27], v[76:79], v[216:219], v[24:27]
	v_mfma_f32_16x16x32_bf16 v[12:15], v[68:71], v[224:227], v[12:15]
	v_mfma_f32_16x16x32_bf16 v[8:11], v[76:79], v[224:227], v[8:11]
	s_setprio 0
	s_setprio 1
	v_mfma_f32_16x16x32_bf16 v[52:55], v[154:157], v[176:179], 0
	v_mfma_f32_16x16x32_bf16 v[48:51], v[168:171], v[176:179], 0
	v_mfma_f32_16x16x32_bf16 v[36:39], v[154:157], v[184:187], 0
	v_mfma_f32_16x16x32_bf16 v[32:35], v[168:171], v[184:187], 0
	v_mfma_f32_16x16x32_bf16 v[20:23], v[154:157], v[212:215], 0
	v_mfma_f32_16x16x32_bf16 v[16:19], v[168:171], v[212:215], 0
	v_mfma_f32_16x16x32_bf16 v[4:7], v[154:157], v[220:223], 0
	v_mfma_f32_16x16x32_bf16 v[0:3], v[168:171], v[220:223], 0
	v_mfma_f32_16x16x32_bf16 v[52:55], v[164:167], v[180:183], v[52:55]
	v_mfma_f32_16x16x32_bf16 v[48:51], v[172:175], v[180:183], v[48:51]
	v_mfma_f32_16x16x32_bf16 v[36:39], v[164:167], v[188:191], v[36:39]
	v_mfma_f32_16x16x32_bf16 v[32:35], v[172:175], v[188:191], v[32:35]
	v_mfma_f32_16x16x32_bf16 v[20:23], v[164:167], v[216:219], v[20:23]
	v_mfma_f32_16x16x32_bf16 v[16:19], v[172:175], v[216:219], v[16:19]
	v_mfma_f32_16x16x32_bf16 v[4:7], v[164:167], v[224:227], v[4:7]
	v_mfma_f32_16x16x32_bf16 v[0:3], v[172:175], v[224:227], v[0:3]
	s_setprio 0
	s_barrier
	s_add_i32 s4, 0, 0x18000
	s_add_i32 s5, 0, 0x1c000
	v_add_u32_e32 v76, s4, v162
	v_add_u32_e32 v172, s5, v162
	ds_read_b128 v[64:67], v76
	ds_read_b128 v[68:71], v76 offset:1024
	ds_read_b128 v[72:75], v76 offset:2048
	ds_read_b128 v[76:79], v76 offset:3072
	ds_read_b128 v[154:157], v172
	ds_read_b128 v[164:167], v172 offset:1024
	ds_read_b128 v[168:171], v172 offset:2048
	ds_read_b128 v[172:175], v172 offset:3072
	s_add_u32 s48, s48, 0x40000
	s_addc_u32 s49, s49, 0
	s_mov_b32 m0, s56
	v_lshl_add_u64 v[200:201], s[48:49], 0, v[148:149]
	ds_read_b128 v[176:179], v163 offset:32768
	ds_read_b128 v[180:183], v163 offset:33792
	ds_read_b128 v[184:187], v163 offset:34816
	ds_read_b128 v[188:191], v163 offset:35840
	ds_read_b128 v[212:215], v163 offset:36864
	ds_read_b128 v[216:219], v163 offset:37888
	ds_read_b128 v[220:223], v163 offset:38912
	ds_read_b128 v[224:227], v163 offset:39936
	global_load_lds_dwordx4 v[200:201], off
	v_lshl_add_u64 v[200:201], s[48:49], 0, v[146:147]
	s_mov_b32 m0, s57
	s_nop 0
	global_load_lds_dwordx4 v[200:201], off
	s_waitcnt vmcnt(8)
	s_waitcnt lgkmcnt(0)
	s_barrier
	s_setprio 1
	s_waitcnt lgkmcnt(0)
	v_mfma_f32_16x16x32_bf16 v[140:143], v[64:67], v[176:179], v[140:143]
	v_mfma_f32_16x16x32_bf16 v[136:139], v[72:75], v[176:179], v[136:139]
	v_mfma_f32_16x16x32_bf16 v[124:127], v[64:67], v[184:187], v[124:127]
	v_mfma_f32_16x16x32_bf16 v[120:123], v[72:75], v[184:187], v[120:123]
	v_mfma_f32_16x16x32_bf16 v[108:111], v[64:67], v[212:215], v[108:111]
	v_mfma_f32_16x16x32_bf16 v[104:107], v[72:75], v[212:215], v[104:107]
	v_mfma_f32_16x16x32_bf16 v[92:95], v[64:67], v[220:223], v[92:95]
	v_mfma_f32_16x16x32_bf16 v[88:91], v[72:75], v[220:223], v[88:91]
	v_mfma_f32_16x16x32_bf16 v[140:143], v[68:71], v[180:183], v[140:143]
	v_mfma_f32_16x16x32_bf16 v[136:139], v[76:79], v[180:183], v[136:139]
	v_mfma_f32_16x16x32_bf16 v[124:127], v[68:71], v[188:191], v[124:127]
	v_mfma_f32_16x16x32_bf16 v[120:123], v[76:79], v[188:191], v[120:123]
	v_mfma_f32_16x16x32_bf16 v[108:111], v[68:71], v[216:219], v[108:111]
	v_mfma_f32_16x16x32_bf16 v[104:107], v[76:79], v[216:219], v[104:107]
	v_mfma_f32_16x16x32_bf16 v[92:95], v[68:71], v[224:227], v[92:95]
	v_mfma_f32_16x16x32_bf16 v[88:91], v[76:79], v[224:227], v[88:91]
	s_setprio 0
	s_setprio 1
	v_mfma_f32_16x16x32_bf16 v[132:135], v[154:157], v[176:179], v[132:135]
	v_mfma_f32_16x16x32_bf16 v[128:131], v[168:171], v[176:179], v[128:131]
	v_mfma_f32_16x16x32_bf16 v[116:119], v[154:157], v[184:187], v[116:119]
	v_mfma_f32_16x16x32_bf16 v[112:115], v[168:171], v[184:187], v[112:115]
	v_mfma_f32_16x16x32_bf16 v[100:103], v[154:157], v[212:215], v[100:103]
	v_mfma_f32_16x16x32_bf16 v[96:99], v[168:171], v[212:215], v[96:99]
	v_mfma_f32_16x16x32_bf16 v[84:87], v[154:157], v[220:223], v[84:87]
	v_mfma_f32_16x16x32_bf16 v[80:83], v[168:171], v[220:223], v[80:83]
	v_mfma_f32_16x16x32_bf16 v[132:135], v[164:167], v[180:183], v[132:135]
	v_mfma_f32_16x16x32_bf16 v[128:131], v[172:175], v[180:183], v[128:131]
	v_mfma_f32_16x16x32_bf16 v[116:119], v[164:167], v[188:191], v[116:119]
	v_mfma_f32_16x16x32_bf16 v[112:115], v[172:175], v[188:191], v[112:115]
	v_mfma_f32_16x16x32_bf16 v[100:103], v[164:167], v[216:219], v[100:103]
	v_mfma_f32_16x16x32_bf16 v[96:99], v[172:175], v[216:219], v[96:99]
	v_mfma_f32_16x16x32_bf16 v[84:87], v[164:167], v[224:227], v[84:87]
	v_mfma_f32_16x16x32_bf16 v[80:83], v[172:175], v[224:227], v[80:83]
	s_setprio 0
	s_barrier
; #define PG8_STAGE(bufoff, gbase, voff) do { _Pragma("unroll") for (int _i = 0; _i < 2; ++_i) \
;         __builtin_amdgcn_global_load_lds((const unsigned*)((const char*)(gbase) + (voff)[_i]), (LAS unsigned*)(lds + (bufoff) + ldsw + _i * 8192), 16, 0, 0); } while (0)
; #define PG8_LDA(dst, b, h) do { _Pragma("unroll") for (int m = 0; m < 4; ++m) _Pragma("unroll") for (int k = 0; k < 2; ++k) dst[m][k] = *(const LAS bf16x8*)(lds + PG8_SA(b, h) + aoff + m * 2048 + k * 1024); } while (0)
; #define PG8_LDB(dst, b, h) do { _Pragma("unroll") for (int n = 0; n < 2; ++n) _Pragma("unroll") for (int k = 0; k < 2; ++k) dst[n][k] = *(const LAS bf16x8*)(lds + PG8_SB(b, h) + boff + n * 2048 + k * 1024); } while (0)
; #define PG8_MMA(ai, bj, At, Bt) do { __builtin_amdgcn_s_setprio(1); _Pragma("unroll") for (int m = 0; m < 4; ++m) _Pragma("unroll") for (int n = 0; n < 2; ++n) _Pragma("unroll") for (int k = 0; k < 2; ++k) \
;         acc[ai][bj][m][n] = __builtin_amdgcn_mfma_f32_16x16x32_bf16(Bt[n][k], At[m][k], acc[ai][bj][m][n], 0, 0, 0); __builtin_amdgcn_s_setprio(0); } while (0)
; #define PG8_WAIT_V(n) asm volatile("s_waitcnt vmcnt(" #n ")" ::: "memory")
; #define PG8_WAIT_L(n) asm volatile("s_waitcnt lgkmcnt(" #n ")" ::: "memory")
; #define PG8_BAR __builtin_amdgcn_s_barrier()
; #define PG8_SCHED __builtin_amdgcn_sched_barrier(0)
; template <class Epi, class Sched, bool ALIGN_EPI>
; __device__ __forceinline__ void gemm_phase(LAS unsigned char* lds, const Gemm g, const Sched& S, const Epi& E) {
;     ...
;             const bool last = (t == nt - 2);
;             const char* a1 = cA + (size_t)(t + 1) * kstep;
;             const char* a2 = last ? nA : cA + (size_t)(t + 2) * kstep; const char* b2 = last ? nB : cB + (size_t)(t + 2) * kstep;
;             const char* a3 = a2 + kstep; const char* b3 = b2 + kstep;
;             PG8_LDB(B0, 0, 0); PG8_LDB(B1, 0, 1); PG8_SCHED; PG8_LDA(At, 0, 0); PG8_STAGE(PG8_SA(1, 1), a1 + hstepA, voffA);
;     ...
;             PG8_LDA(At, 1, 1); PG8_STAGE(PG8_SB(1, 0), b3, voffB); PG8_STAGE(PG8_SB(1, 1), b3 + hstepB, voffB); PG8_STAGE(PG8_SA(1, 0), a3, voffA);
;             PG8_WAIT_V(8); PG8_WAIT_L(0); PG8_BAR; PG8_MMA(1, 0, At, B0); PG8_MMA(1, 1, At, B1); PG8_BAR; PG8_SCHED;
	s_add_i32 s4, s4, s53
	v_lshl_add_u64 v[158:159], v[158:159], 0, s[12:13]
	s_mov_b32 m0, s4
	ds_read_b128 v[176:179], v163 offset:49152
	ds_read_b128 v[180:183], v163 offset:50176
	ds_read_b128 v[184:187], v163 offset:51200
	ds_read_b128 v[188:191], v163 offset:52224
	ds_read_b128 v[212:215], v163 offset:53248
	ds_read_b128 v[216:219], v163 offset:54272
	ds_read_b128 v[220:223], v163 offset:55296
	ds_read_b128 v[224:227], v163 offset:56320
	global_load_lds_dwordx4 v[158:159], off
	s_add_i32 m0, s4, 0x2000
	s_add_u32 s46, s46, 0x40080
	v_lshl_add_u64 v[158:159], v[194:195], 0, s[12:13]
	s_addc_u32 s47, s47, 0
	s_add_i32 s4, s5, s53
	global_load_lds_dwordx4 v[158:159], off
	v_lshl_add_u64 v[158:159], s[46:47], 0, v[192:193]
	s_mov_b32 m0, s4
	s_nop 0
	global_load_lds_dwordx4 v[158:159], off
	v_lshl_add_u64 v[158:159], s[46:47], 0, v[144:145]
	s_add_i32 m0, s4, 0x2000
	s_nop 0
	global_load_lds_dwordx4 v[158:159], off
	v_lshl_add_u64 v[158:159], v[196:197], 0, s[12:13]
	s_mov_b32 m0, s65
	s_nop 0
	global_load_lds_dwordx4 v[158:159], off
	v_lshl_add_u64 v[158:159], v[198:199], 0, s[12:13]
	s_mov_b32 m0, s66
	s_nop 0
	global_load_lds_dwordx4 v[158:159], off
	s_waitcnt vmcnt(8)
	s_waitcnt lgkmcnt(0)
	s_barrier
	s_setprio 1
	s_waitcnt lgkmcnt(0)
	v_mfma_f32_16x16x32_bf16 v[60:63], v[64:67], v[176:179], v[60:63]
	v_mfma_f32_16x16x32_bf16 v[56:59], v[72:75], v[176:179], v[56:59]
	v_mfma_f32_16x16x32_bf16 v[44:47], v[64:67], v[184:187], v[44:47]
	v_mfma_f32_16x16x32_bf16 v[40:43], v[72:75], v[184:187], v[40:43]
	v_mfma_f32_16x16x32_bf16 v[28:31], v[64:67], v[212:215], v[28:31]
	v_mfma_f32_16x16x32_bf16 v[24:27], v[72:75], v[212:215], v[24:27]
	v_mfma_f32_16x16x32_bf16 v[12:15], v[64:67], v[220:223], v[12:15]
	v_mfma_f32_16x16x32_bf16 v[8:11], v[72:75], v[220:223], v[8:11]
	v_mfma_f32_16x16x32_bf16 v[60:63], v[68:71], v[180:183], v[60:63]
	v_mfma_f32_16x16x32_bf16 v[56:59], v[76:79], v[180:183], v[56:59]
	v_mfma_f32_16x16x32_bf16 v[44:47], v[68:71], v[188:191], v[44:47]
	v_mfma_f32_16x16x32_bf16 v[40:43], v[76:79], v[188:191], v[40:43]
	v_mfma_f32_16x16x32_bf16 v[28:31], v[68:71], v[216:219], v[28:31]
	v_mfma_f32_16x16x32_bf16 v[24:27], v[76:79], v[216:219], v[24:27]
	v_mfma_f32_16x16x32_bf16 v[12:15], v[68:71], v[224:227], v[12:15]
	v_mfma_f32_16x16x32_bf16 v[8:11], v[76:79], v[224:227], v[8:11]
	s_setprio 0
	s_setprio 1
	v_mfma_f32_16x16x32_bf16 v[52:55], v[154:157], v[176:179], v[52:55]
	s_add_i32 s92, s92, 2
	v_mfma_f32_16x16x32_bf16 v[48:51], v[168:171], v[176:179], v[48:51]
	s_add_u32 s44, s44, 0x100
	v_mfma_f32_16x16x32_bf16 v[36:39], v[154:157], v[184:187], v[36:39]
	s_addc_u32 s45, s45, 0
	v_mfma_f32_16x16x32_bf16 v[32:35], v[168:171], v[184:187], v[32:35]
	s_add_u32 s90, s90, 0x100
	v_mfma_f32_16x16x32_bf16 v[20:23], v[154:157], v[212:215], v[20:23]
	s_addc_u32 s91, s91, 0
	v_mfma_f32_16x16x32_bf16 v[16:19], v[168:171], v[212:215], v[16:19]
	s_add_u32 s46, s44, 0xfffc0080
	v_mfma_f32_16x16x32_bf16 v[4:7], v[154:157], v[220:223], v[4:7]
	s_addc_u32 s47, s45, -1
	v_mfma_f32_16x16x32_bf16 v[0:3], v[168:171], v[220:223], v[0:3]
	s_add_i32 vcc_lo, 0, 0x10000
	v_mfma_f32_16x16x32_bf16 v[52:55], v[164:167], v[180:183], v[52:55]
	s_cmp_eq_u32 s92, 12
	v_mfma_f32_16x16x32_bf16 v[48:51], v[172:175], v[180:183], v[48:51]
	s_cselect_b32 s49, s21, s47
	v_mfma_f32_16x16x32_bf16 v[36:39], v[164:167], v[188:191], v[36:39]
	s_cselect_b32 s48, s86, s46
	v_mfma_f32_16x16x32_bf16 v[32:35], v[172:175], v[188:191], v[32:35]
	s_cselect_b32 s47, s17, s91
	v_mfma_f32_16x16x32_bf16 v[20:23], v[164:167], v[216:219], v[20:23]
	s_cselect_b32 s46, s87, s90
	v_mfma_f32_16x16x32_bf16 v[16:19], v[172:175], v[216:219], v[16:19]
	s_add_i32 s4, 0, 0x14000
	v_mfma_f32_16x16x32_bf16 v[4:7], v[164:167], v[224:227], v[4:7]
	s_cmp_gt_u32 s92, 13
	v_mfma_f32_16x16x32_bf16 v[0:3], v[172:175], v[224:227], v[0:3]
	s_setprio 0
	s_barrier
.LBB0_571:
	v_add_u32_e32 v76, vcc_lo, v162
	v_add_u32_e32 v158, s4, v162
	ds_read_b128 v[64:67], v76
	ds_read_b128 v[68:71], v76 offset:1024
	ds_read_b128 v[72:75], v76 offset:2048
	ds_read_b128 v[76:79], v76 offset:3072
	ds_read_b128 v[154:157], v158
	ds_read_b128 v[164:167], v158 offset:1024
	ds_read_b128 v[168:171], v158 offset:2048
	ds_read_b128 v[172:175], v158 offset:3072
	v_lshl_add_u64 v[158:159], s[44:45], 0, v[150:151]
	s_add_i32 m0, s54, 0xc000
	ds_read_b128 v[176:179], v163
	ds_read_b128 v[180:183], v163 offset:1024
	ds_read_b128 v[184:187], v163 offset:2048
	ds_read_b128 v[188:191], v163 offset:3072
	ds_read_b128 v[212:215], v163 offset:4096
	ds_read_b128 v[216:219], v163 offset:5120
	ds_read_b128 v[220:223], v163 offset:6144
	ds_read_b128 v[224:227], v163 offset:7168
	global_load_lds_dwordx4 v[158:159], off
	v_lshl_add_u64 v[158:159], s[44:45], 0, v[152:153]
	s_add_i32 m0, s54, 0xe000
	s_nop 0
	global_load_lds_dwordx4 v[158:159], off
	s_waitcnt vmcnt(8)
	s_waitcnt lgkmcnt(0)
	s_barrier
; #define PG8_STAGE(bufoff, gbase, voff) do { _Pragma("unroll") for (int _i = 0; _i < 2; ++_i) \
;         __builtin_amdgcn_global_load_lds((const unsigned*)((const char*)(gbase) + (voff)[_i]), (LAS unsigned*)(lds + (bufoff) + ldsw + _i * 8192), 16, 0, 0); } while (0)
; #define PG8_LDA(dst, b, h) do { _Pragma("unroll") for (int m = 0; m < 4; ++m) _Pragma("unroll") for (int k = 0; k < 2; ++k) dst[m][k] = *(const LAS bf16x8*)(lds + PG8_SA(b, h) + aoff + m * 2048 + k * 1024); } while (0)
; #define PG8_MMA(ai, bj, At, Bt) do { __builtin_amdgcn_s_setprio(1); _Pragma("unroll") for (int m = 0; m < 4; ++m) _Pragma("unroll") for (int n = 0; n < 2; ++n) _Pragma("unroll") for (int k = 0; k < 2; ++k) \
;         acc[ai][bj][m][n] = __builtin_amdgcn_mfma_f32_16x16x32_bf16(Bt[n][k], At[m][k], acc[ai][bj][m][n], 0, 0, 0); __builtin_amdgcn_s_setprio(0); } while (0)
; #define PG8_WAIT_V(n) asm volatile("s_waitcnt vmcnt(" #n ")" ::: "memory")
; #define PG8_WAIT_L(n) asm volatile("s_waitcnt lgkmcnt(" #n ")" ::: "memory")
; #define PG8_BAR __builtin_amdgcn_s_barrier()
; #define PG8_SCHED __builtin_amdgcn_sched_barrier(0)
; template <class Epi, class Sched, bool ALIGN_EPI>
; __device__ __forceinline__ void gemm_phase(LAS unsigned char* lds, const Gemm g, const Sched& S, const Epi& E) {
;     ...
;             PG8_WAIT_V(8); PG8_WAIT_L(0); PG8_BAR; PG8_MMA(0, 0, At, B0); PG8_MMA(0, 1, At, B1); PG8_BAR; PG8_SCHED;
;             PG8_LDA(At, 0, 1); PG8_STAGE(PG8_SB(0, 0), b2, voffB); PG8_STAGE(PG8_SB(0, 1), b2 + hstepB, voffB); PG8_STAGE(PG8_SA(0, 0), a2, voffA);
;             PG8_WAIT_V(8); PG8_WAIT_L(0); PG8_BAR; PG8_MMA(1, 0, At, B0); PG8_MMA(1, 1, At, B1); PG8_BAR; PG8_SCHED;
	s_setprio 1
	s_waitcnt lgkmcnt(0)
	v_mfma_f32_16x16x32_bf16 v[140:143], v[64:67], v[176:179], v[140:143]
	v_mfma_f32_16x16x32_bf16 v[136:139], v[72:75], v[176:179], v[136:139]
	v_mfma_f32_16x16x32_bf16 v[124:127], v[64:67], v[184:187], v[124:127]
	v_mfma_f32_16x16x32_bf16 v[120:123], v[72:75], v[184:187], v[120:123]
	v_mfma_f32_16x16x32_bf16 v[108:111], v[64:67], v[212:215], v[108:111]
	v_mfma_f32_16x16x32_bf16 v[104:107], v[72:75], v[212:215], v[104:107]
	v_mfma_f32_16x16x32_bf16 v[92:95], v[64:67], v[220:223], v[92:95]
	v_mfma_f32_16x16x32_bf16 v[88:91], v[72:75], v[220:223], v[88:91]
	v_mfma_f32_16x16x32_bf16 v[140:143], v[68:71], v[180:183], v[140:143]
	v_mfma_f32_16x16x32_bf16 v[136:139], v[76:79], v[180:183], v[136:139]
	v_mfma_f32_16x16x32_bf16 v[124:127], v[68:71], v[188:191], v[124:127]
	v_mfma_f32_16x16x32_bf16 v[120:123], v[76:79], v[188:191], v[120:123]
	v_mfma_f32_16x16x32_bf16 v[108:111], v[68:71], v[216:219], v[108:111]
	v_mfma_f32_16x16x32_bf16 v[104:107], v[76:79], v[216:219], v[104:107]
	v_mfma_f32_16x16x32_bf16 v[92:95], v[68:71], v[224:227], v[92:95]
	v_mfma_f32_16x16x32_bf16 v[88:91], v[76:79], v[224:227], v[88:91]
	s_setprio 0
	s_setprio 1
	v_mfma_f32_16x16x32_bf16 v[132:135], v[154:157], v[176:179], v[132:135]
	v_mfma_f32_16x16x32_bf16 v[128:131], v[168:171], v[176:179], v[128:131]
	v_mfma_f32_16x16x32_bf16 v[116:119], v[154:157], v[184:187], v[116:119]
	v_mfma_f32_16x16x32_bf16 v[112:115], v[168:171], v[184:187], v[112:115]
	v_mfma_f32_16x16x32_bf16 v[100:103], v[154:157], v[212:215], v[100:103]
	v_mfma_f32_16x16x32_bf16 v[96:99], v[168:171], v[212:215], v[96:99]
	v_mfma_f32_16x16x32_bf16 v[84:87], v[154:157], v[220:223], v[84:87]
	v_mfma_f32_16x16x32_bf16 v[80:83], v[168:171], v[220:223], v[80:83]
	v_mfma_f32_16x16x32_bf16 v[132:135], v[164:167], v[180:183], v[132:135]
	v_mfma_f32_16x16x32_bf16 v[128:131], v[172:175], v[180:183], v[128:131]
	v_mfma_f32_16x16x32_bf16 v[116:119], v[164:167], v[188:191], v[116:119]
	v_mfma_f32_16x16x32_bf16 v[112:115], v[172:175], v[188:191], v[112:115]
	v_mfma_f32_16x16x32_bf16 v[100:103], v[164:167], v[216:219], v[100:103]
	v_mfma_f32_16x16x32_bf16 v[96:99], v[172:175], v[216:219], v[96:99]
	v_mfma_f32_16x16x32_bf16 v[84:87], v[164:167], v[224:227], v[84:87]
	v_mfma_f32_16x16x32_bf16 v[80:83], v[172:175], v[224:227], v[80:83]
	s_setprio 0
	s_barrier
	s_add_i32 s5, vcc_lo, s53
	v_lshl_add_u64 v[158:159], s[46:47], 0, v[192:193]
	s_mov_b32 m0, s5
	ds_read_b128 v[176:179], v163 offset:16384
	ds_read_b128 v[180:183], v163 offset:17408
	ds_read_b128 v[184:187], v163 offset:18432
	ds_read_b128 v[188:191], v163 offset:19456
	ds_read_b128 v[212:215], v163 offset:20480
	ds_read_b128 v[216:219], v163 offset:21504
	ds_read_b128 v[220:223], v163 offset:22528
	ds_read_b128 v[224:227], v163 offset:23552
	global_load_lds_dwordx4 v[158:159], off
	s_add_i32 m0, s5, 0x2000
	s_add_u32 vcc_lo, s46, 0x40000
	v_lshl_add_u64 v[194:195], s[46:47], 0, v[144:145]
	s_addc_u32 vcc_hi, s47, 0
	s_add_i32 s4, s4, s53
	global_load_lds_dwordx4 v[194:195], off
	v_lshl_add_u64 v[196:197], vcc, 0, v[192:193]
	s_mov_b32 m0, s4
	v_lshl_add_u64 v[198:199], s[48:49], 0, v[146:147]
	global_load_lds_dwordx4 v[196:197], off
	v_lshl_add_u64 v[196:197], vcc, 0, v[144:145]
	s_add_i32 m0, s4, 0x2000
	s_nop 0
	global_load_lds_dwordx4 v[196:197], off
	v_lshl_add_u64 v[196:197], s[48:49], 0, v[148:149]
	s_mov_b32 m0, s54
	s_nop 0
	global_load_lds_dwordx4 v[196:197], off
	s_mov_b32 m0, s55
	s_nop 0
	global_load_lds_dwordx4 v[198:199], off
	s_waitcnt vmcnt(8)
	s_waitcnt lgkmcnt(0)
	s_barrier
	s_setprio 1
	s_waitcnt lgkmcnt(0)
	v_mfma_f32_16x16x32_bf16 v[60:63], v[64:67], v[176:179], v[60:63]
	v_mfma_f32_16x16x32_bf16 v[56:59], v[72:75], v[176:179], v[56:59]
	v_mfma_f32_16x16x32_bf16 v[44:47], v[64:67], v[184:187], v[44:47]
	v_mfma_f32_16x16x32_bf16 v[40:43], v[72:75], v[184:187], v[40:43]
	v_mfma_f32_16x16x32_bf16 v[28:31], v[64:67], v[212:215], v[28:31]
	v_mfma_f32_16x16x32_bf16 v[24:27], v[72:75], v[212:215], v[24:27]
	v_mfma_f32_16x16x32_bf16 v[12:15], v[64:67], v[220:223], v[12:15]
	v_mfma_f32_16x16x32_bf16 v[8:11], v[72:75], v[220:223], v[8:11]
	v_mfma_f32_16x16x32_bf16 v[60:63], v[68:71], v[180:183], v[60:63]
	v_mfma_f32_16x16x32_bf16 v[56:59], v[76:79], v[180:183], v[56:59]
	v_mfma_f32_16x16x32_bf16 v[44:47], v[68:71], v[188:191], v[44:47]
	v_mfma_f32_16x16x32_bf16 v[40:43], v[76:79], v[188:191], v[40:43]
	v_mfma_f32_16x16x32_bf16 v[28:31], v[68:71], v[216:219], v[28:31]
	v_mfma_f32_16x16x32_bf16 v[24:27], v[76:79], v[216:219], v[24:27]
	v_mfma_f32_16x16x32_bf16 v[12:15], v[68:71], v[224:227], v[12:15]
	v_mfma_f32_16x16x32_bf16 v[8:11], v[76:79], v[224:227], v[8:11]
	s_setprio 0
	s_setprio 1
	v_mfma_f32_16x16x32_bf16 v[52:55], v[154:157], v[176:179], v[52:55]
	v_mfma_f32_16x16x32_bf16 v[48:51], v[168:171], v[176:179], v[48:51]
	v_mfma_f32_16x16x32_bf16 v[36:39], v[154:157], v[184:187], v[36:39]
	v_mfma_f32_16x16x32_bf16 v[32:35], v[168:171], v[184:187], v[32:35]
	v_mfma_f32_16x16x32_bf16 v[20:23], v[154:157], v[212:215], v[20:23]
	v_mfma_f32_16x16x32_bf16 v[16:19], v[168:171], v[212:215], v[16:19]
	v_mfma_f32_16x16x32_bf16 v[4:7], v[154:157], v[220:223], v[4:7]
	v_mfma_f32_16x16x32_bf16 v[0:3], v[168:171], v[220:223], v[0:3]
	v_mfma_f32_16x16x32_bf16 v[52:55], v[164:167], v[180:183], v[52:55]
	v_mfma_f32_16x16x32_bf16 v[48:51], v[172:175], v[180:183], v[48:51]
	v_mfma_f32_16x16x32_bf16 v[36:39], v[164:167], v[188:191], v[36:39]
	v_mfma_f32_16x16x32_bf16 v[32:35], v[172:175], v[188:191], v[32:35]
	v_mfma_f32_16x16x32_bf16 v[20:23], v[164:167], v[216:219], v[20:23]
	v_mfma_f32_16x16x32_bf16 v[16:19], v[172:175], v[216:219], v[16:19]
	v_mfma_f32_16x16x32_bf16 v[4:7], v[164:167], v[224:227], v[4:7]
	v_mfma_f32_16x16x32_bf16 v[0:3], v[172:175], v[224:227], v[0:3]
	s_setprio 0
	s_barrier
; #define PG8_STAGE(bufoff, gbase, voff) do { _Pragma("unroll") for (int _i = 0; _i < 2; ++_i) \
;         __builtin_amdgcn_global_load_lds((const unsigned*)((const char*)(gbase) + (voff)[_i]), (LAS unsigned*)(lds + (bufoff) + ldsw + _i * 8192), 16, 0, 0); } while (0)
; #define PG8_LDA(dst, b, h) do { _Pragma("unroll") for (int m = 0; m < 4; ++m) _Pragma("unroll") for (int k = 0; k < 2; ++k) dst[m][k] = *(const LAS bf16x8*)(lds + PG8_SA(b, h) + aoff + m * 2048 + k * 1024); } while (0)
; #define PG8_LDB(dst, b, h) do { _Pragma("unroll") for (int n = 0; n < 2; ++n) _Pragma("unroll") for (int k = 0; k < 2; ++k) dst[n][k] = *(const LAS bf16x8*)(lds + PG8_SB(b, h) + boff + n * 2048 + k * 1024); } while (0)
; #define PG8_MMA(ai, bj, At, Bt) do { __builtin_amdgcn_s_setprio(1); _Pragma("unroll") for (int m = 0; m < 4; ++m) _Pragma("unroll") for (int n = 0; n < 2; ++n) _Pragma("unroll") for (int k = 0; k < 2; ++k) \
;         acc[ai][bj][m][n] = __builtin_amdgcn_mfma_f32_16x16x32_bf16(Bt[n][k], At[m][k], acc[ai][bj][m][n], 0, 0, 0); __builtin_amdgcn_s_setprio(0); } while (0)
; #define PG8_WAIT_V(n) asm volatile("s_waitcnt vmcnt(" #n ")" ::: "memory")
; #define PG8_WAIT_L(n) asm volatile("s_waitcnt lgkmcnt(" #n ")" ::: "memory")
; #define PG8_BAR __builtin_amdgcn_s_barrier()
; #define PG8_SCHED __builtin_amdgcn_sched_barrier(0)
; template <class Epi, class Sched, bool ALIGN_EPI>
; __device__ __forceinline__ void gemm_phase(LAS unsigned char* lds, const Gemm g, const Sched& S, const Epi& E) {
;     ...
;             PG8_LDB(B0, 1, 0); PG8_LDB(B1, 1, 1); PG8_SCHED; PG8_LDA(At, 1, 0); PG8_STAGE(PG8_SA(0, 1), a2 + hstepA, voffA);
;             PG8_WAIT_V(8); PG8_WAIT_L(0); PG8_BAR; PG8_MMA(0, 0, At, B0); PG8_MMA(0, 1, At, B1); PG8_BAR; PG8_SCHED;
	s_add_i32 s4, 0, 0x18000
	s_add_i32 s5, 0, 0x1c000
	v_add_u32_e32 v76, s4, v162
	v_add_u32_e32 v172, s5, v162
	ds_read_b128 v[64:67], v76
	ds_read_b128 v[68:71], v76 offset:1024
	ds_read_b128 v[72:75], v76 offset:2048
	ds_read_b128 v[76:79], v76 offset:3072
	ds_read_b128 v[154:157], v172
	ds_read_b128 v[164:167], v172 offset:1024
	ds_read_b128 v[168:171], v172 offset:2048
	ds_read_b128 v[172:175], v172 offset:3072
	s_add_u32 s48, s48, 0x40000
	s_addc_u32 s49, s49, 0
	s_mov_b32 m0, s56
	v_lshl_add_u64 v[200:201], s[48:49], 0, v[148:149]
	ds_read_b128 v[176:179], v163 offset:32768
	ds_read_b128 v[180:183], v163 offset:33792
	ds_read_b128 v[184:187], v163 offset:34816
	ds_read_b128 v[188:191], v163 offset:35840
	ds_read_b128 v[212:215], v163 offset:36864
	ds_read_b128 v[216:219], v163 offset:37888
	ds_read_b128 v[220:223], v163 offset:38912
	ds_read_b128 v[224:227], v163 offset:39936
	global_load_lds_dwordx4 v[200:201], off
	v_lshl_add_u64 v[200:201], s[48:49], 0, v[146:147]
	s_mov_b32 m0, s57
	s_nop 0
	global_load_lds_dwordx4 v[200:201], off
	s_waitcnt vmcnt(8)
	s_waitcnt lgkmcnt(0)
	s_barrier
	s_setprio 1
	s_waitcnt lgkmcnt(0)
	v_mfma_f32_16x16x32_bf16 v[140:143], v[64:67], v[176:179], v[140:143]
	v_mfma_f32_16x16x32_bf16 v[136:139], v[72:75], v[176:179], v[136:139]
	v_mfma_f32_16x16x32_bf16 v[124:127], v[64:67], v[184:187], v[124:127]
	v_mfma_f32_16x16x32_bf16 v[120:123], v[72:75], v[184:187], v[120:123]
	v_mfma_f32_16x16x32_bf16 v[108:111], v[64:67], v[212:215], v[108:111]
	v_mfma_f32_16x16x32_bf16 v[104:107], v[72:75], v[212:215], v[104:107]
	v_mfma_f32_16x16x32_bf16 v[92:95], v[64:67], v[220:223], v[92:95]
	v_mfma_f32_16x16x32_bf16 v[88:91], v[72:75], v[220:223], v[88:91]
	v_mfma_f32_16x16x32_bf16 v[140:143], v[68:71], v[180:183], v[140:143]
	v_mfma_f32_16x16x32_bf16 v[136:139], v[76:79], v[180:183], v[136:139]
	v_mfma_f32_16x16x32_bf16 v[124:127], v[68:71], v[188:191], v[124:127]
	v_mfma_f32_16x16x32_bf16 v[120:123], v[76:79], v[188:191], v[120:123]
	v_mfma_f32_16x16x32_bf16 v[108:111], v[68:71], v[216:219], v[108:111]
	v_mfma_f32_16x16x32_bf16 v[104:107], v[76:79], v[216:219], v[104:107]
	v_mfma_f32_16x16x32_bf16 v[92:95], v[68:71], v[224:227], v[92:95]
	v_mfma_f32_16x16x32_bf16 v[88:91], v[76:79], v[224:227], v[88:91]
	s_setprio 0
	s_setprio 1
	v_mfma_f32_16x16x32_bf16 v[132:135], v[154:157], v[176:179], v[132:135]
	v_mfma_f32_16x16x32_bf16 v[128:131], v[168:171], v[176:179], v[128:131]
	v_mfma_f32_16x16x32_bf16 v[116:119], v[154:157], v[184:187], v[116:119]
	v_mfma_f32_16x16x32_bf16 v[112:115], v[168:171], v[184:187], v[112:115]
	v_mfma_f32_16x16x32_bf16 v[100:103], v[154:157], v[212:215], v[100:103]
	v_mfma_f32_16x16x32_bf16 v[96:99], v[168:171], v[212:215], v[96:99]
	v_mfma_f32_16x16x32_bf16 v[84:87], v[154:157], v[220:223], v[84:87]
	v_mfma_f32_16x16x32_bf16 v[80:83], v[168:171], v[220:223], v[80:83]
	v_mfma_f32_16x16x32_bf16 v[132:135], v[164:167], v[180:183], v[132:135]
	v_mfma_f32_16x16x32_bf16 v[128:131], v[172:175], v[180:183], v[128:131]
	v_mfma_f32_16x16x32_bf16 v[116:119], v[164:167], v[188:191], v[116:119]
	v_mfma_f32_16x16x32_bf16 v[112:115], v[172:175], v[188:191], v[112:115]
	v_mfma_f32_16x16x32_bf16 v[100:103], v[164:167], v[216:219], v[100:103]
	v_mfma_f32_16x16x32_bf16 v[96:99], v[172:175], v[216:219], v[96:99]
	v_mfma_f32_16x16x32_bf16 v[84:87], v[164:167], v[224:227], v[84:87]
	v_mfma_f32_16x16x32_bf16 v[80:83], v[172:175], v[224:227], v[80:83]
	s_setprio 0
	s_barrier
; #define PG8_STAGE(bufoff, gbase, voff) do { _Pragma("unroll") for (int _i = 0; _i < 2; ++_i) \
;         __builtin_amdgcn_global_load_lds((const unsigned*)((const char*)(gbase) + (voff)[_i]), (LAS unsigned*)(lds + (bufoff) + ldsw + _i * 8192), 16, 0, 0); } while (0)
; #define PG8_LDA(dst, b, h) do { _Pragma("unroll") for (int m = 0; m < 4; ++m) _Pragma("unroll") for (int k = 0; k < 2; ++k) dst[m][k] = *(const LAS bf16x8*)(lds + PG8_SA(b, h) + aoff + m * 2048 + k * 1024); } while (0)
; #define PG8_MMA(ai, bj, At, Bt) do { __builtin_amdgcn_s_setprio(1); _Pragma("unroll") for (int m = 0; m < 4; ++m) _Pragma("unroll") for (int n = 0; n < 2; ++n) _Pragma("unroll") for (int k = 0; k < 2; ++k) \
;         acc[ai][bj][m][n] = __builtin_amdgcn_mfma_f32_16x16x32_bf16(Bt[n][k], At[m][k], acc[ai][bj][m][n], 0, 0, 0); __builtin_amdgcn_s_setprio(0); } while (0)
; #define PG8_WAIT_V(n) asm volatile("s_waitcnt vmcnt(" #n ")" ::: "memory")
; #define PG8_WAIT_L(n) asm volatile("s_waitcnt lgkmcnt(" #n ")" ::: "memory")
; #define PG8_BAR __builtin_amdgcn_s_barrier()
; #define PG8_SCHED __builtin_amdgcn_sched_barrier(0)
; template <class Epi, class Sched, bool ALIGN_EPI>
; __device__ __forceinline__ void gemm_phase(LAS unsigned char* lds, const Gemm g, const Sched& S, const Epi& E) {
;     ...
;             PG8_LDA(At, 1, 1); PG8_STAGE(PG8_SB(1, 0), b3, voffB); PG8_STAGE(PG8_SB(1, 1), b3 + hstepB, voffB); PG8_STAGE(PG8_SA(1, 0), a3, voffA);
;             PG8_WAIT_V(8); PG8_WAIT_L(0); PG8_BAR; PG8_MMA(1, 0, At, B0); PG8_MMA(1, 1, At, B1); PG8_BAR; PG8_SCHED;
;         }
;         if constexpr (ALIGN_EPI) { if (wr == 0) PG8_BAR; }
	s_add_i32 s4, s4, s53
	v_lshl_add_u64 v[158:159], v[158:159], 0, s[12:13]
	s_mov_b32 m0, s4
	ds_read_b128 v[176:179], v163 offset:49152
	ds_read_b128 v[180:183], v163 offset:50176
	ds_read_b128 v[184:187], v163 offset:51200
	ds_read_b128 v[188:191], v163 offset:52224
	ds_read_b128 v[212:215], v163 offset:53248
	ds_read_b128 v[216:219], v163 offset:54272
	ds_read_b128 v[220:223], v163 offset:55296
	ds_read_b128 v[224:227], v163 offset:56320
	global_load_lds_dwordx4 v[158:159], off
	s_add_i32 m0, s4, 0x2000
	s_add_u32 s46, s46, 0x40080
	v_lshl_add_u64 v[158:159], v[194:195], 0, s[12:13]
	s_addc_u32 s47, s47, 0
	s_add_i32 s4, s5, s53
	global_load_lds_dwordx4 v[158:159], off
	v_lshl_add_u64 v[158:159], s[46:47], 0, v[192:193]
	s_mov_b32 m0, s4
	s_nop 0
	global_load_lds_dwordx4 v[158:159], off
	v_lshl_add_u64 v[158:159], s[46:47], 0, v[144:145]
	s_add_i32 m0, s4, 0x2000
	s_nop 0
	global_load_lds_dwordx4 v[158:159], off
	v_lshl_add_u64 v[158:159], v[196:197], 0, s[12:13]
	s_mov_b32 m0, s65
	s_nop 0
	global_load_lds_dwordx4 v[158:159], off
	v_lshl_add_u64 v[158:159], v[198:199], 0, s[12:13]
	s_mov_b32 m0, s66
	s_nop 0
	global_load_lds_dwordx4 v[158:159], off
	s_waitcnt vmcnt(8)
	s_waitcnt lgkmcnt(0)
	s_barrier
	s_setprio 1
	s_waitcnt lgkmcnt(0)
	v_mfma_f32_16x16x32_bf16 v[60:63], v[64:67], v[176:179], v[60:63]
	v_mfma_f32_16x16x32_bf16 v[56:59], v[72:75], v[176:179], v[56:59]
	v_mfma_f32_16x16x32_bf16 v[44:47], v[64:67], v[184:187], v[44:47]
	v_mfma_f32_16x16x32_bf16 v[40:43], v[72:75], v[184:187], v[40:43]
	v_mfma_f32_16x16x32_bf16 v[28:31], v[64:67], v[212:215], v[28:31]
	v_mfma_f32_16x16x32_bf16 v[24:27], v[72:75], v[212:215], v[24:27]
	v_mfma_f32_16x16x32_bf16 v[12:15], v[64:67], v[220:223], v[12:15]
	v_mfma_f32_16x16x32_bf16 v[8:11], v[72:75], v[220:223], v[8:11]
	v_mfma_f32_16x16x32_bf16 v[60:63], v[68:71], v[180:183], v[60:63]
	v_mfma_f32_16x16x32_bf16 v[56:59], v[76:79], v[180:183], v[56:59]
	v_mfma_f32_16x16x32_bf16 v[44:47], v[68:71], v[188:191], v[44:47]
	v_mfma_f32_16x16x32_bf16 v[40:43], v[76:79], v[188:191], v[40:43]
	v_mfma_f32_16x16x32_bf16 v[28:31], v[68:71], v[216:219], v[28:31]
	v_mfma_f32_16x16x32_bf16 v[24:27], v[76:79], v[216:219], v[24:27]
	v_mfma_f32_16x16x32_bf16 v[12:15], v[68:71], v[224:227], v[12:15]
	v_mfma_f32_16x16x32_bf16 v[8:11], v[76:79], v[224:227], v[8:11]
	s_setprio 0
	s_setprio 1
	v_mfma_f32_16x16x32_bf16 v[52:55], v[154:157], v[176:179], v[52:55]
	s_add_i32 s92, s92, 2
	v_mfma_f32_16x16x32_bf16 v[48:51], v[168:171], v[176:179], v[48:51]
	s_add_u32 s44, s44, 0x100
	v_mfma_f32_16x16x32_bf16 v[36:39], v[154:157], v[184:187], v[36:39]
	s_addc_u32 s45, s45, 0
	v_mfma_f32_16x16x32_bf16 v[32:35], v[168:171], v[184:187], v[32:35]
	s_add_u32 s90, s90, 0x100
	v_mfma_f32_16x16x32_bf16 v[20:23], v[154:157], v[212:215], v[20:23]
	s_addc_u32 s91, s91, 0
	v_mfma_f32_16x16x32_bf16 v[16:19], v[168:171], v[212:215], v[16:19]
	s_add_u32 s46, s44, 0xfffc0080
	v_mfma_f32_16x16x32_bf16 v[4:7], v[154:157], v[220:223], v[4:7]
	s_addc_u32 s47, s45, -1
	v_mfma_f32_16x16x32_bf16 v[0:3], v[168:171], v[220:223], v[0:3]
	s_add_i32 vcc_lo, 0, 0x10000
	v_mfma_f32_16x16x32_bf16 v[52:55], v[164:167], v[180:183], v[52:55]
	s_cmp_eq_u32 s92, 12
	v_mfma_f32_16x16x32_bf16 v[48:51], v[172:175], v[180:183], v[48:51]
	s_cselect_b32 s49, s21, s47
	v_mfma_f32_16x16x32_bf16 v[36:39], v[164:167], v[188:191], v[36:39]
	s_cselect_b32 s48, s86, s46
	v_mfma_f32_16x16x32_bf16 v[32:35], v[172:175], v[188:191], v[32:35]
	s_cselect_b32 s47, s17, s91
	v_mfma_f32_16x16x32_bf16 v[20:23], v[164:167], v[216:219], v[20:23]
	s_cselect_b32 s46, s87, s90
	v_mfma_f32_16x16x32_bf16 v[16:19], v[172:175], v[216:219], v[16:19]
	s_add_i32 s4, 0, 0x14000
	v_mfma_f32_16x16x32_bf16 v[4:7], v[164:167], v[224:227], v[4:7]
	s_cmp_gt_u32 s92, 13
	v_mfma_f32_16x16x32_bf16 v[0:3], v[172:175], v[224:227], v[0:3]
	s_setprio 0
	s_barrier
	s_cbranch_scc0 .LBB0_571
	s_and_b64 vcc, exec, s[8:9]
	s_cbranch_vccz .LBB0_574
	s_barrier
